# snake_pairs_peel
# speedup vs baseline: 1.0060x; 1.0042x over previous
.LBB0_224:
	s_add_u32 s33, s16, 0x100
	s_addc_u32 s42, s17, 0
	s_mov_b32 s18, -2
	s_mov_b64 s[4:5], 0
	s_add_i32 s43, s18, 2
	s_lshr_b32 s44, s43, 2
	s_add_i32 s16, s18, 4
	s_lshl_b64 s[60:61], s[44:45], 9
	s_lshr_b32 s44, s16, 2
	s_and_b32 s47, s4, 0x100
	s_lshl_b64 s[16:17], s[44:45], 9
	s_add_u32 s19, s14, s16
	s_addc_u32 s44, s15, s17
	s_add_u32 s16, s4, 0x100
	s_addc_u32 s17, s5, 0
	s_and_b32 s49, s16, 0x100
	s_add_u32 s49, s19, s49
	s_addc_u32 s19, s44, 0
	s_add_u32 s4, s33, s4
	s_addc_u32 s5, s42, s5
	s_add_i32 s44, 0, 0x10000
	s_add_u32 s59, s14, s60
	s_addc_u32 s60, s15, s61
	s_cmp_eq_u32 s18, 28
	s_cselect_b32 s19, s11, s19
	s_cselect_b32 s18, s10, s49
	s_cselect_b32 s5, s13, s5
	s_cselect_b32 s4, s12, s4
	s_add_i32 s49, 0, 0x14000
	v_add_u32_e32 v154, s44, v152
	v_add_u32_e32 v170, s49, v152
	ds_read_b128 v[140:143], v154
	ds_read_b128 v[144:147], v154 offset:1024
	ds_read_b128 v[148:151], v154 offset:2048
	ds_read_b128 v[154:157], v154 offset:3072
	ds_read_b128 v[158:161], v170
	ds_read_b128 v[162:165], v170 offset:1024
	ds_read_b128 v[166:169], v170 offset:2048
	ds_read_b128 v[170:173], v170 offset:3072
	s_add_u32 s47, s59, s47
	s_addc_u32 s59, s60, 0
	s_add_u32 s60, s47, 0x80080
	s_addc_u32 s61, s59, 0
	v_lshl_add_u64 v[194:195], s[60:61], 0, v[130:131]
	s_add_i32 m0, s27, 0xc000
	ds_read_b128 v[174:177], v153
	ds_read_b128 v[178:181], v153 offset:1024
	ds_read_b128 v[182:185], v153 offset:2048
	ds_read_b128 v[186:189], v153 offset:3072
	ds_read_b128 v[190:193], v153 offset:4096
	ds_read_b128 v[198:201], v153 offset:5120
	ds_read_b128 v[202:205], v153 offset:6144
	ds_read_b128 v[206:209], v153 offset:7168
	global_load_lds_dwordx4 v[194:195], off
	v_lshl_add_u64 v[194:195], s[60:61], 0, v[134:135]
	s_add_i32 m0, s27, 0xe000
	s_nop 0
	global_load_lds_dwordx4 v[194:195], off
	s_waitcnt vmcnt(8)
	s_waitcnt lgkmcnt(0)
	s_barrier
	s_setprio 1
	s_waitcnt lgkmcnt(0)
	v_mfma_f32_16x16x32_bf16 v[126:129], v[140:143], v[174:177], 0
	v_mfma_f32_16x16x32_bf16 v[126:129], v[144:147], v[178:181], v[126:129]
	v_mfma_f32_16x16x32_bf16 v[122:125], v[154:157], v[178:181], 0
	v_mfma_f32_16x16x32_bf16 v[122:125], v[148:151], v[174:177], v[122:125]
	v_mfma_f32_16x16x32_bf16 v[106:109], v[148:151], v[182:185], 0
	v_mfma_f32_16x16x32_bf16 v[106:109], v[154:157], v[186:189], v[106:109]
	v_mfma_f32_16x16x32_bf16 v[110:113], v[144:147], v[186:189], 0
	v_mfma_f32_16x16x32_bf16 v[110:113], v[140:143], v[182:185], v[110:113]
	v_mfma_f32_16x16x32_bf16 v[94:97], v[140:143], v[190:193], 0
	v_mfma_f32_16x16x32_bf16 v[94:97], v[144:147], v[198:201], v[94:97]
	v_mfma_f32_16x16x32_bf16 v[90:93], v[154:157], v[198:201], 0
	v_mfma_f32_16x16x32_bf16 v[90:93], v[148:151], v[190:193], v[90:93]
	v_mfma_f32_16x16x32_bf16 v[74:77], v[148:151], v[202:205], 0
	v_mfma_f32_16x16x32_bf16 v[74:77], v[154:157], v[206:209], v[74:77]
	v_mfma_f32_16x16x32_bf16 v[78:81], v[144:147], v[206:209], 0
	v_mfma_f32_16x16x32_bf16 v[78:81], v[140:143], v[202:205], v[78:81]
	s_setprio 0
	s_setprio 1
	v_mfma_f32_16x16x32_bf16 v[118:121], v[158:161], v[174:177], 0
	v_mfma_f32_16x16x32_bf16 v[118:121], v[162:165], v[178:181], v[118:121]
	v_mfma_f32_16x16x32_bf16 v[114:117], v[170:173], v[178:181], 0
	v_mfma_f32_16x16x32_bf16 v[114:117], v[166:169], v[174:177], v[114:117]
	v_mfma_f32_16x16x32_bf16 v[98:101], v[166:169], v[182:185], 0
	v_mfma_f32_16x16x32_bf16 v[98:101], v[170:173], v[186:189], v[98:101]
	v_mfma_f32_16x16x32_bf16 v[102:105], v[162:165], v[186:189], 0
	v_mfma_f32_16x16x32_bf16 v[102:105], v[158:161], v[182:185], v[102:105]
	v_mfma_f32_16x16x32_bf16 v[86:89], v[158:161], v[190:193], 0
	v_mfma_f32_16x16x32_bf16 v[86:89], v[162:165], v[198:201], v[86:89]
	v_mfma_f32_16x16x32_bf16 v[82:85], v[170:173], v[198:201], 0
	v_mfma_f32_16x16x32_bf16 v[82:85], v[166:169], v[190:193], v[82:85]
	v_mfma_f32_16x16x32_bf16 v[66:69], v[166:169], v[202:205], 0
	v_mfma_f32_16x16x32_bf16 v[66:69], v[170:173], v[206:209], v[66:69]
	v_mfma_f32_16x16x32_bf16 v[70:73], v[162:165], v[206:209], 0
	v_mfma_f32_16x16x32_bf16 v[70:73], v[158:161], v[202:205], v[70:73]
	s_setprio 0
	s_barrier
	s_add_i32 s44, s44, s9
	v_lshl_add_u64 v[194:195], s[4:5], 0, v[132:133]
	s_mov_b32 m0, s44
	ds_read_b128 v[174:177], v153 offset:16384
	ds_read_b128 v[178:181], v153 offset:17408
	ds_read_b128 v[182:185], v153 offset:18432
	ds_read_b128 v[186:189], v153 offset:19456
	ds_read_b128 v[190:193], v153 offset:20480
	ds_read_b128 v[198:201], v153 offset:21504
	ds_read_b128 v[202:205], v153 offset:22528
	ds_read_b128 v[206:209], v153 offset:23552
	global_load_lds_dwordx4 v[194:195], off
	s_add_i32 m0, s44, 0x2000
	s_add_u32 s60, s4, 0x80000
	v_lshl_add_u64 v[210:211], s[4:5], 0, v[136:137]
	s_addc_u32 s61, s5, 0
	s_add_i32 s44, s49, s9
	global_load_lds_dwordx4 v[210:211], off
	v_lshl_add_u64 v[212:213], s[60:61], 0, v[132:133]
	s_mov_b32 m0, s44
	v_lshl_add_u64 v[214:215], s[18:19], 0, v[134:135]
	global_load_lds_dwordx4 v[212:213], off
	v_lshl_add_u64 v[212:213], s[60:61], 0, v[136:137]
	s_add_i32 m0, s44, 0x2000
	s_nop 0
	global_load_lds_dwordx4 v[212:213], off
	v_lshl_add_u64 v[212:213], s[18:19], 0, v[130:131]
	s_mov_b32 m0, s27
	s_nop 0
	global_load_lds_dwordx4 v[212:213], off
	s_mov_b32 m0, s28
	s_nop 0
	global_load_lds_dwordx4 v[214:215], off
	s_waitcnt vmcnt(8)
	s_waitcnt lgkmcnt(0)
	s_barrier
	s_setprio 1
	s_waitcnt lgkmcnt(0)
	v_mfma_f32_16x16x32_bf16 v[62:65], v[140:143], v[174:177], 0
	v_mfma_f32_16x16x32_bf16 v[62:65], v[144:147], v[178:181], v[62:65]
	v_mfma_f32_16x16x32_bf16 v[58:61], v[154:157], v[178:181], 0
	v_mfma_f32_16x16x32_bf16 v[58:61], v[148:151], v[174:177], v[58:61]
	v_mfma_f32_16x16x32_bf16 v[42:45], v[148:151], v[182:185], 0
	v_mfma_f32_16x16x32_bf16 v[42:45], v[154:157], v[186:189], v[42:45]
	v_mfma_f32_16x16x32_bf16 v[46:49], v[144:147], v[186:189], 0
	v_mfma_f32_16x16x32_bf16 v[46:49], v[140:143], v[182:185], v[46:49]
	v_mfma_f32_16x16x32_bf16 v[30:33], v[140:143], v[190:193], 0
	v_mfma_f32_16x16x32_bf16 v[30:33], v[144:147], v[198:201], v[30:33]
	v_mfma_f32_16x16x32_bf16 v[26:29], v[154:157], v[198:201], 0
	v_mfma_f32_16x16x32_bf16 v[26:29], v[148:151], v[190:193], v[26:29]
	v_mfma_f32_16x16x32_bf16 v[10:13], v[148:151], v[202:205], 0
	v_mfma_f32_16x16x32_bf16 v[10:13], v[154:157], v[206:209], v[10:13]
	v_mfma_f32_16x16x32_bf16 v[14:17], v[144:147], v[206:209], 0
	v_mfma_f32_16x16x32_bf16 v[14:17], v[140:143], v[202:205], v[14:17]
	s_setprio 0
	s_setprio 1
	v_mfma_f32_16x16x32_bf16 v[54:57], v[158:161], v[174:177], 0
	v_mfma_f32_16x16x32_bf16 v[54:57], v[162:165], v[178:181], v[54:57]
	v_mfma_f32_16x16x32_bf16 v[50:53], v[170:173], v[178:181], 0
	v_mfma_f32_16x16x32_bf16 v[50:53], v[166:169], v[174:177], v[50:53]
	v_mfma_f32_16x16x32_bf16 v[34:37], v[166:169], v[182:185], 0
	v_mfma_f32_16x16x32_bf16 v[34:37], v[170:173], v[186:189], v[34:37]
	v_mfma_f32_16x16x32_bf16 v[38:41], v[162:165], v[186:189], 0
	v_mfma_f32_16x16x32_bf16 v[38:41], v[158:161], v[182:185], v[38:41]
	v_mfma_f32_16x16x32_bf16 v[22:25], v[158:161], v[190:193], 0
	v_mfma_f32_16x16x32_bf16 v[22:25], v[162:165], v[198:201], v[22:25]
	v_mfma_f32_16x16x32_bf16 v[18:21], v[170:173], v[198:201], 0
	v_mfma_f32_16x16x32_bf16 v[18:21], v[166:169], v[190:193], v[18:21]
	v_mfma_f32_16x16x32_bf16 v[2:5], v[166:169], v[202:205], 0
	v_mfma_f32_16x16x32_bf16 v[2:5], v[170:173], v[206:209], v[2:5]
	v_mfma_f32_16x16x32_bf16 v[6:9], v[162:165], v[206:209], 0
	v_mfma_f32_16x16x32_bf16 v[6:9], v[158:161], v[202:205], v[6:9]
	s_setprio 0
	s_barrier
	s_add_i32 s44, 0, 0x18000
	s_add_i32 s47, 0, 0x1c000
	v_add_u32_e32 v154, s44, v152
	v_add_u32_e32 v170, s47, v152
	ds_read_b128 v[140:143], v154
	ds_read_b128 v[144:147], v154 offset:1024
	ds_read_b128 v[148:151], v154 offset:2048
	ds_read_b128 v[154:157], v154 offset:3072
	ds_read_b128 v[158:161], v170
	ds_read_b128 v[162:165], v170 offset:1024
	ds_read_b128 v[166:169], v170 offset:2048
	ds_read_b128 v[170:173], v170 offset:3072
	s_add_u32 s18, s18, 0x80000
	s_addc_u32 s19, s19, 0
	s_mov_b32 m0, s29
	v_lshl_add_u64 v[216:217], s[18:19], 0, v[130:131]
	ds_read_b128 v[174:177], v153 offset:32768
	ds_read_b128 v[178:181], v153 offset:33792
	ds_read_b128 v[182:185], v153 offset:34816
	ds_read_b128 v[186:189], v153 offset:35840
	ds_read_b128 v[190:193], v153 offset:36864
	ds_read_b128 v[198:201], v153 offset:37888
	ds_read_b128 v[202:205], v153 offset:38912
	ds_read_b128 v[206:209], v153 offset:39936
	global_load_lds_dwordx4 v[216:217], off
	v_lshl_add_u64 v[216:217], s[18:19], 0, v[134:135]
	s_mov_b32 m0, s30
	s_nop 0
	global_load_lds_dwordx4 v[216:217], off
	s_waitcnt vmcnt(8)
	s_waitcnt lgkmcnt(0)
	s_barrier
	s_setprio 1
	s_waitcnt lgkmcnt(0)
	v_mfma_f32_16x16x32_bf16 v[126:129], v[140:143], v[174:177], v[126:129]
	v_mfma_f32_16x16x32_bf16 v[126:129], v[144:147], v[178:181], v[126:129]
	v_mfma_f32_16x16x32_bf16 v[122:125], v[154:157], v[178:181], v[122:125]
	v_mfma_f32_16x16x32_bf16 v[122:125], v[148:151], v[174:177], v[122:125]
	v_mfma_f32_16x16x32_bf16 v[106:109], v[148:151], v[182:185], v[106:109]
	v_mfma_f32_16x16x32_bf16 v[106:109], v[154:157], v[186:189], v[106:109]
	v_mfma_f32_16x16x32_bf16 v[110:113], v[144:147], v[186:189], v[110:113]
	v_mfma_f32_16x16x32_bf16 v[110:113], v[140:143], v[182:185], v[110:113]
	v_mfma_f32_16x16x32_bf16 v[94:97], v[140:143], v[190:193], v[94:97]
	v_mfma_f32_16x16x32_bf16 v[94:97], v[144:147], v[198:201], v[94:97]
	v_mfma_f32_16x16x32_bf16 v[90:93], v[154:157], v[198:201], v[90:93]
	v_mfma_f32_16x16x32_bf16 v[90:93], v[148:151], v[190:193], v[90:93]
	v_mfma_f32_16x16x32_bf16 v[74:77], v[148:151], v[202:205], v[74:77]
	v_mfma_f32_16x16x32_bf16 v[74:77], v[154:157], v[206:209], v[74:77]
	v_mfma_f32_16x16x32_bf16 v[78:81], v[144:147], v[206:209], v[78:81]
	v_mfma_f32_16x16x32_bf16 v[78:81], v[140:143], v[202:205], v[78:81]
	s_setprio 0
	s_setprio 1
	v_mfma_f32_16x16x32_bf16 v[118:121], v[158:161], v[174:177], v[118:121]
	v_mfma_f32_16x16x32_bf16 v[118:121], v[162:165], v[178:181], v[118:121]
	v_mfma_f32_16x16x32_bf16 v[114:117], v[170:173], v[178:181], v[114:117]
	v_mfma_f32_16x16x32_bf16 v[114:117], v[166:169], v[174:177], v[114:117]
	v_mfma_f32_16x16x32_bf16 v[98:101], v[166:169], v[182:185], v[98:101]
	v_mfma_f32_16x16x32_bf16 v[98:101], v[170:173], v[186:189], v[98:101]
	v_mfma_f32_16x16x32_bf16 v[102:105], v[162:165], v[186:189], v[102:105]
	v_mfma_f32_16x16x32_bf16 v[102:105], v[158:161], v[182:185], v[102:105]
	v_mfma_f32_16x16x32_bf16 v[86:89], v[158:161], v[190:193], v[86:89]
	v_mfma_f32_16x16x32_bf16 v[86:89], v[162:165], v[198:201], v[86:89]
	v_mfma_f32_16x16x32_bf16 v[82:85], v[170:173], v[198:201], v[82:85]
	v_mfma_f32_16x16x32_bf16 v[82:85], v[166:169], v[190:193], v[82:85]
	v_mfma_f32_16x16x32_bf16 v[66:69], v[166:169], v[202:205], v[66:69]
	v_mfma_f32_16x16x32_bf16 v[66:69], v[170:173], v[206:209], v[66:69]
	v_mfma_f32_16x16x32_bf16 v[70:73], v[162:165], v[206:209], v[70:73]
	v_mfma_f32_16x16x32_bf16 v[70:73], v[158:161], v[202:205], v[70:73]
	s_setprio 0
	s_barrier
	s_add_i32 s18, s44, s9
	v_lshl_add_u64 v[194:195], v[194:195], 0, s[2:3]
	s_mov_b32 m0, s18
	ds_read_b128 v[174:177], v153 offset:49152
	ds_read_b128 v[178:181], v153 offset:50176
	ds_read_b128 v[182:185], v153 offset:51200
	ds_read_b128 v[186:189], v153 offset:52224
	ds_read_b128 v[190:193], v153 offset:53248
	ds_read_b128 v[198:201], v153 offset:54272
	ds_read_b128 v[202:205], v153 offset:55296
	ds_read_b128 v[206:209], v153 offset:56320
	global_load_lds_dwordx4 v[194:195], off
	s_add_i32 m0, s18, 0x2000
	s_add_u32 s4, s4, 0x80080
	v_lshl_add_u64 v[194:195], v[210:211], 0, s[2:3]
	s_addc_u32 s5, s5, 0
	s_add_i32 s18, s47, s9
	global_load_lds_dwordx4 v[194:195], off
	v_lshl_add_u64 v[194:195], s[4:5], 0, v[132:133]
	s_mov_b32 m0, s18
	s_nop 0
	global_load_lds_dwordx4 v[194:195], off
	v_lshl_add_u64 v[194:195], s[4:5], 0, v[136:137]
	s_add_i32 m0, s18, 0x2000
	s_nop 0
	global_load_lds_dwordx4 v[194:195], off
	v_lshl_add_u64 v[194:195], v[212:213], 0, s[2:3]
	s_mov_b32 m0, s51
	s_nop 0
	global_load_lds_dwordx4 v[194:195], off
	v_lshl_add_u64 v[194:195], v[214:215], 0, s[2:3]
	s_mov_b32 m0, s52
	s_nop 0
	global_load_lds_dwordx4 v[194:195], off
	s_waitcnt vmcnt(8)
	s_waitcnt lgkmcnt(0)
	s_barrier
	s_setprio 1
	s_waitcnt lgkmcnt(0)
	v_mfma_f32_16x16x32_bf16 v[62:65], v[140:143], v[174:177], v[62:65]
	v_mfma_f32_16x16x32_bf16 v[62:65], v[144:147], v[178:181], v[62:65]
	v_mfma_f32_16x16x32_bf16 v[58:61], v[154:157], v[178:181], v[58:61]
	v_mfma_f32_16x16x32_bf16 v[58:61], v[148:151], v[174:177], v[58:61]
	v_mfma_f32_16x16x32_bf16 v[42:45], v[148:151], v[182:185], v[42:45]
	v_mfma_f32_16x16x32_bf16 v[42:45], v[154:157], v[186:189], v[42:45]
	v_mfma_f32_16x16x32_bf16 v[46:49], v[144:147], v[186:189], v[46:49]
	v_mfma_f32_16x16x32_bf16 v[46:49], v[140:143], v[182:185], v[46:49]
	v_mfma_f32_16x16x32_bf16 v[30:33], v[140:143], v[190:193], v[30:33]
	v_mfma_f32_16x16x32_bf16 v[30:33], v[144:147], v[198:201], v[30:33]
	v_mfma_f32_16x16x32_bf16 v[26:29], v[154:157], v[198:201], v[26:29]
	v_mfma_f32_16x16x32_bf16 v[26:29], v[148:151], v[190:193], v[26:29]
	v_mfma_f32_16x16x32_bf16 v[10:13], v[148:151], v[202:205], v[10:13]
	v_mfma_f32_16x16x32_bf16 v[10:13], v[154:157], v[206:209], v[10:13]
	v_mfma_f32_16x16x32_bf16 v[14:17], v[144:147], v[206:209], v[14:17]
	v_mfma_f32_16x16x32_bf16 v[14:17], v[140:143], v[202:205], v[14:17]
	s_setprio 0
	s_setprio 1
	v_mfma_f32_16x16x32_bf16 v[54:57], v[158:161], v[174:177], v[54:57]
	v_mfma_f32_16x16x32_bf16 v[54:57], v[162:165], v[178:181], v[54:57]
	v_mfma_f32_16x16x32_bf16 v[50:53], v[170:173], v[178:181], v[50:53]
	v_mfma_f32_16x16x32_bf16 v[50:53], v[166:169], v[174:177], v[50:53]
	v_mfma_f32_16x16x32_bf16 v[34:37], v[166:169], v[182:185], v[34:37]
	v_mfma_f32_16x16x32_bf16 v[34:37], v[170:173], v[186:189], v[34:37]
	v_mfma_f32_16x16x32_bf16 v[38:41], v[162:165], v[186:189], v[38:41]
	v_mfma_f32_16x16x32_bf16 v[38:41], v[158:161], v[182:185], v[38:41]
	v_mfma_f32_16x16x32_bf16 v[22:25], v[158:161], v[190:193], v[22:25]
	v_mfma_f32_16x16x32_bf16 v[22:25], v[162:165], v[198:201], v[22:25]
	v_mfma_f32_16x16x32_bf16 v[18:21], v[170:173], v[198:201], v[18:21]
	v_mfma_f32_16x16x32_bf16 v[18:21], v[166:169], v[190:193], v[18:21]
	v_mfma_f32_16x16x32_bf16 v[2:5], v[166:169], v[202:205], v[2:5]
	v_mfma_f32_16x16x32_bf16 v[2:5], v[170:173], v[206:209], v[2:5]
	v_mfma_f32_16x16x32_bf16 v[6:9], v[162:165], v[206:209], v[6:9]
	v_mfma_f32_16x16x32_bf16 v[6:9], v[158:161], v[202:205], v[6:9]
	s_setprio 0
	s_barrier
	s_cmp_gt_u32 s43, 29
	s_mov_b64 s[4:5], s[16:17]
	s_mov_b32 s18, s43
	s_cbranch_scc1 .Lpeel_exit_proj
.LBB0_225:
	s_add_i32 s43, s18, 2
	s_lshr_b32 s44, s43, 2
	s_add_i32 s16, s18, 4
	s_lshl_b64 s[60:61], s[44:45], 9
	s_lshr_b32 s44, s16, 2
	s_and_b32 s47, s4, 0x100
	s_lshl_b64 s[16:17], s[44:45], 9
	s_add_u32 s19, s14, s16
	s_addc_u32 s44, s15, s17
	s_add_u32 s16, s4, 0x100
	s_addc_u32 s17, s5, 0
	s_and_b32 s49, s16, 0x100
	s_add_u32 s49, s19, s49
	s_addc_u32 s19, s44, 0
	s_add_u32 s4, s33, s4
	s_addc_u32 s5, s42, s5
	s_add_i32 s44, 0, 0x10000
	s_add_u32 s59, s14, s60
	s_addc_u32 s60, s15, s61
	s_cmp_eq_u32 s18, 28
	s_cselect_b32 s19, s11, s19
	s_cselect_b32 s18, s10, s49
	s_cselect_b32 s5, s13, s5
	s_cselect_b32 s4, s12, s4
	s_add_i32 s49, 0, 0x14000
	v_add_u32_e32 v154, s44, v152
	v_add_u32_e32 v170, s49, v152
	ds_read_b128 v[140:143], v154
	ds_read_b128 v[144:147], v154 offset:1024
	ds_read_b128 v[148:151], v154 offset:2048
	ds_read_b128 v[154:157], v154 offset:3072
	ds_read_b128 v[158:161], v170
	ds_read_b128 v[162:165], v170 offset:1024
	ds_read_b128 v[166:169], v170 offset:2048
	ds_read_b128 v[170:173], v170 offset:3072
	s_add_u32 s47, s59, s47
	s_addc_u32 s59, s60, 0
	s_add_u32 s60, s47, 0x80080
	s_addc_u32 s61, s59, 0
	v_lshl_add_u64 v[194:195], s[60:61], 0, v[130:131]
	s_add_i32 m0, s27, 0xc000
	ds_read_b128 v[174:177], v153
	ds_read_b128 v[178:181], v153 offset:1024
	ds_read_b128 v[182:185], v153 offset:2048
	ds_read_b128 v[186:189], v153 offset:3072
	ds_read_b128 v[190:193], v153 offset:4096
	ds_read_b128 v[198:201], v153 offset:5120
	ds_read_b128 v[202:205], v153 offset:6144
	ds_read_b128 v[206:209], v153 offset:7168
	global_load_lds_dwordx4 v[194:195], off
	v_lshl_add_u64 v[194:195], s[60:61], 0, v[134:135]
	s_add_i32 m0, s27, 0xe000
	s_nop 0
	global_load_lds_dwordx4 v[194:195], off
	s_waitcnt vmcnt(8)
	s_waitcnt lgkmcnt(0)
	s_barrier
	s_setprio 1
	s_waitcnt lgkmcnt(0)
	v_mfma_f32_16x16x32_bf16 v[126:129], v[140:143], v[174:177], v[126:129]
	v_mfma_f32_16x16x32_bf16 v[126:129], v[144:147], v[178:181], v[126:129]
	v_mfma_f32_16x16x32_bf16 v[122:125], v[154:157], v[178:181], v[122:125]
	v_mfma_f32_16x16x32_bf16 v[122:125], v[148:151], v[174:177], v[122:125]
	v_mfma_f32_16x16x32_bf16 v[106:109], v[148:151], v[182:185], v[106:109]
	v_mfma_f32_16x16x32_bf16 v[106:109], v[154:157], v[186:189], v[106:109]
	v_mfma_f32_16x16x32_bf16 v[110:113], v[144:147], v[186:189], v[110:113]
	v_mfma_f32_16x16x32_bf16 v[110:113], v[140:143], v[182:185], v[110:113]
	v_mfma_f32_16x16x32_bf16 v[94:97], v[140:143], v[190:193], v[94:97]
	v_mfma_f32_16x16x32_bf16 v[94:97], v[144:147], v[198:201], v[94:97]
	v_mfma_f32_16x16x32_bf16 v[90:93], v[154:157], v[198:201], v[90:93]
	v_mfma_f32_16x16x32_bf16 v[90:93], v[148:151], v[190:193], v[90:93]
	v_mfma_f32_16x16x32_bf16 v[74:77], v[148:151], v[202:205], v[74:77]
	v_mfma_f32_16x16x32_bf16 v[74:77], v[154:157], v[206:209], v[74:77]
	v_mfma_f32_16x16x32_bf16 v[78:81], v[144:147], v[206:209], v[78:81]
	v_mfma_f32_16x16x32_bf16 v[78:81], v[140:143], v[202:205], v[78:81]
	s_setprio 0
	s_setprio 1
	v_mfma_f32_16x16x32_bf16 v[118:121], v[158:161], v[174:177], v[118:121]
	v_mfma_f32_16x16x32_bf16 v[118:121], v[162:165], v[178:181], v[118:121]
	v_mfma_f32_16x16x32_bf16 v[114:117], v[170:173], v[178:181], v[114:117]
	v_mfma_f32_16x16x32_bf16 v[114:117], v[166:169], v[174:177], v[114:117]
	v_mfma_f32_16x16x32_bf16 v[98:101], v[166:169], v[182:185], v[98:101]
	v_mfma_f32_16x16x32_bf16 v[98:101], v[170:173], v[186:189], v[98:101]
	v_mfma_f32_16x16x32_bf16 v[102:105], v[162:165], v[186:189], v[102:105]
	v_mfma_f32_16x16x32_bf16 v[102:105], v[158:161], v[182:185], v[102:105]
	v_mfma_f32_16x16x32_bf16 v[86:89], v[158:161], v[190:193], v[86:89]
	v_mfma_f32_16x16x32_bf16 v[86:89], v[162:165], v[198:201], v[86:89]
	v_mfma_f32_16x16x32_bf16 v[82:85], v[170:173], v[198:201], v[82:85]
	v_mfma_f32_16x16x32_bf16 v[82:85], v[166:169], v[190:193], v[82:85]
	v_mfma_f32_16x16x32_bf16 v[66:69], v[166:169], v[202:205], v[66:69]
	v_mfma_f32_16x16x32_bf16 v[66:69], v[170:173], v[206:209], v[66:69]
	v_mfma_f32_16x16x32_bf16 v[70:73], v[162:165], v[206:209], v[70:73]
	v_mfma_f32_16x16x32_bf16 v[70:73], v[158:161], v[202:205], v[70:73]
	s_setprio 0
	s_barrier
	s_add_i32 s44, s44, s9
	v_lshl_add_u64 v[194:195], s[4:5], 0, v[132:133]
	s_mov_b32 m0, s44
	ds_read_b128 v[174:177], v153 offset:16384
	ds_read_b128 v[178:181], v153 offset:17408
	ds_read_b128 v[182:185], v153 offset:18432
	ds_read_b128 v[186:189], v153 offset:19456
	ds_read_b128 v[190:193], v153 offset:20480
	ds_read_b128 v[198:201], v153 offset:21504
	ds_read_b128 v[202:205], v153 offset:22528
	ds_read_b128 v[206:209], v153 offset:23552
	global_load_lds_dwordx4 v[194:195], off
	s_add_i32 m0, s44, 0x2000
	s_add_u32 s60, s4, 0x80000
	v_lshl_add_u64 v[210:211], s[4:5], 0, v[136:137]
	s_addc_u32 s61, s5, 0
	s_add_i32 s44, s49, s9
	global_load_lds_dwordx4 v[210:211], off
	v_lshl_add_u64 v[212:213], s[60:61], 0, v[132:133]
	s_mov_b32 m0, s44
	v_lshl_add_u64 v[214:215], s[18:19], 0, v[134:135]
	global_load_lds_dwordx4 v[212:213], off
	v_lshl_add_u64 v[212:213], s[60:61], 0, v[136:137]
	s_add_i32 m0, s44, 0x2000
	s_nop 0
	global_load_lds_dwordx4 v[212:213], off
	v_lshl_add_u64 v[212:213], s[18:19], 0, v[130:131]
	s_mov_b32 m0, s27
	s_nop 0
	global_load_lds_dwordx4 v[212:213], off
	s_mov_b32 m0, s28
	s_nop 0
	global_load_lds_dwordx4 v[214:215], off
	s_waitcnt vmcnt(8)
	s_waitcnt lgkmcnt(0)
	s_barrier
	s_setprio 1
	s_waitcnt lgkmcnt(0)
	v_mfma_f32_16x16x32_bf16 v[62:65], v[140:143], v[174:177], v[62:65]
	v_mfma_f32_16x16x32_bf16 v[62:65], v[144:147], v[178:181], v[62:65]
	v_mfma_f32_16x16x32_bf16 v[58:61], v[154:157], v[178:181], v[58:61]
	v_mfma_f32_16x16x32_bf16 v[58:61], v[148:151], v[174:177], v[58:61]
	v_mfma_f32_16x16x32_bf16 v[42:45], v[148:151], v[182:185], v[42:45]
	v_mfma_f32_16x16x32_bf16 v[42:45], v[154:157], v[186:189], v[42:45]
	v_mfma_f32_16x16x32_bf16 v[46:49], v[144:147], v[186:189], v[46:49]
	v_mfma_f32_16x16x32_bf16 v[46:49], v[140:143], v[182:185], v[46:49]
	v_mfma_f32_16x16x32_bf16 v[30:33], v[140:143], v[190:193], v[30:33]
	v_mfma_f32_16x16x32_bf16 v[30:33], v[144:147], v[198:201], v[30:33]
	v_mfma_f32_16x16x32_bf16 v[26:29], v[154:157], v[198:201], v[26:29]
	v_mfma_f32_16x16x32_bf16 v[26:29], v[148:151], v[190:193], v[26:29]
	v_mfma_f32_16x16x32_bf16 v[10:13], v[148:151], v[202:205], v[10:13]
	v_mfma_f32_16x16x32_bf16 v[10:13], v[154:157], v[206:209], v[10:13]
	v_mfma_f32_16x16x32_bf16 v[14:17], v[144:147], v[206:209], v[14:17]
	v_mfma_f32_16x16x32_bf16 v[14:17], v[140:143], v[202:205], v[14:17]
	s_setprio 0
	s_setprio 1
	v_mfma_f32_16x16x32_bf16 v[54:57], v[158:161], v[174:177], v[54:57]
	v_mfma_f32_16x16x32_bf16 v[54:57], v[162:165], v[178:181], v[54:57]
	v_mfma_f32_16x16x32_bf16 v[50:53], v[170:173], v[178:181], v[50:53]
	v_mfma_f32_16x16x32_bf16 v[50:53], v[166:169], v[174:177], v[50:53]
	v_mfma_f32_16x16x32_bf16 v[34:37], v[166:169], v[182:185], v[34:37]
	v_mfma_f32_16x16x32_bf16 v[34:37], v[170:173], v[186:189], v[34:37]
	v_mfma_f32_16x16x32_bf16 v[38:41], v[162:165], v[186:189], v[38:41]
	v_mfma_f32_16x16x32_bf16 v[38:41], v[158:161], v[182:185], v[38:41]
	v_mfma_f32_16x16x32_bf16 v[22:25], v[158:161], v[190:193], v[22:25]
	v_mfma_f32_16x16x32_bf16 v[22:25], v[162:165], v[198:201], v[22:25]
	v_mfma_f32_16x16x32_bf16 v[18:21], v[170:173], v[198:201], v[18:21]
	v_mfma_f32_16x16x32_bf16 v[18:21], v[166:169], v[190:193], v[18:21]
	v_mfma_f32_16x16x32_bf16 v[2:5], v[166:169], v[202:205], v[2:5]
	v_mfma_f32_16x16x32_bf16 v[2:5], v[170:173], v[206:209], v[2:5]
	v_mfma_f32_16x16x32_bf16 v[6:9], v[162:165], v[206:209], v[6:9]
	v_mfma_f32_16x16x32_bf16 v[6:9], v[158:161], v[202:205], v[6:9]
	s_setprio 0
	s_barrier
	s_add_i32 s44, 0, 0x18000
	s_add_i32 s47, 0, 0x1c000
	v_add_u32_e32 v154, s44, v152
	v_add_u32_e32 v170, s47, v152
	ds_read_b128 v[140:143], v154
	ds_read_b128 v[144:147], v154 offset:1024
	ds_read_b128 v[148:151], v154 offset:2048
	ds_read_b128 v[154:157], v154 offset:3072
	ds_read_b128 v[158:161], v170
	ds_read_b128 v[162:165], v170 offset:1024
	ds_read_b128 v[166:169], v170 offset:2048
	ds_read_b128 v[170:173], v170 offset:3072
	s_add_u32 s18, s18, 0x80000
	s_addc_u32 s19, s19, 0
	s_mov_b32 m0, s29
	v_lshl_add_u64 v[216:217], s[18:19], 0, v[130:131]
	ds_read_b128 v[174:177], v153 offset:32768
	ds_read_b128 v[178:181], v153 offset:33792
	ds_read_b128 v[182:185], v153 offset:34816
	ds_read_b128 v[186:189], v153 offset:35840
	ds_read_b128 v[190:193], v153 offset:36864
	ds_read_b128 v[198:201], v153 offset:37888
	ds_read_b128 v[202:205], v153 offset:38912
	ds_read_b128 v[206:209], v153 offset:39936
	global_load_lds_dwordx4 v[216:217], off
	v_lshl_add_u64 v[216:217], s[18:19], 0, v[134:135]
	s_mov_b32 m0, s30
	s_nop 0
	global_load_lds_dwordx4 v[216:217], off
	s_waitcnt vmcnt(8)
	s_waitcnt lgkmcnt(0)
	s_barrier
	s_setprio 1
	s_waitcnt lgkmcnt(0)
	v_mfma_f32_16x16x32_bf16 v[126:129], v[140:143], v[174:177], v[126:129]
	v_mfma_f32_16x16x32_bf16 v[126:129], v[144:147], v[178:181], v[126:129]
	v_mfma_f32_16x16x32_bf16 v[122:125], v[154:157], v[178:181], v[122:125]
	v_mfma_f32_16x16x32_bf16 v[122:125], v[148:151], v[174:177], v[122:125]
	v_mfma_f32_16x16x32_bf16 v[106:109], v[148:151], v[182:185], v[106:109]
	v_mfma_f32_16x16x32_bf16 v[106:109], v[154:157], v[186:189], v[106:109]
	v_mfma_f32_16x16x32_bf16 v[110:113], v[144:147], v[186:189], v[110:113]
	v_mfma_f32_16x16x32_bf16 v[110:113], v[140:143], v[182:185], v[110:113]
	v_mfma_f32_16x16x32_bf16 v[94:97], v[140:143], v[190:193], v[94:97]
	v_mfma_f32_16x16x32_bf16 v[94:97], v[144:147], v[198:201], v[94:97]
	v_mfma_f32_16x16x32_bf16 v[90:93], v[154:157], v[198:201], v[90:93]
	v_mfma_f32_16x16x32_bf16 v[90:93], v[148:151], v[190:193], v[90:93]
	v_mfma_f32_16x16x32_bf16 v[74:77], v[148:151], v[202:205], v[74:77]
	v_mfma_f32_16x16x32_bf16 v[74:77], v[154:157], v[206:209], v[74:77]
	v_mfma_f32_16x16x32_bf16 v[78:81], v[144:147], v[206:209], v[78:81]
	v_mfma_f32_16x16x32_bf16 v[78:81], v[140:143], v[202:205], v[78:81]
	s_setprio 0
	s_setprio 1
	v_mfma_f32_16x16x32_bf16 v[118:121], v[158:161], v[174:177], v[118:121]
	v_mfma_f32_16x16x32_bf16 v[118:121], v[162:165], v[178:181], v[118:121]
	v_mfma_f32_16x16x32_bf16 v[114:117], v[170:173], v[178:181], v[114:117]
	v_mfma_f32_16x16x32_bf16 v[114:117], v[166:169], v[174:177], v[114:117]
	v_mfma_f32_16x16x32_bf16 v[98:101], v[166:169], v[182:185], v[98:101]
	v_mfma_f32_16x16x32_bf16 v[98:101], v[170:173], v[186:189], v[98:101]
	v_mfma_f32_16x16x32_bf16 v[102:105], v[162:165], v[186:189], v[102:105]
	v_mfma_f32_16x16x32_bf16 v[102:105], v[158:161], v[182:185], v[102:105]
	v_mfma_f32_16x16x32_bf16 v[86:89], v[158:161], v[190:193], v[86:89]
	v_mfma_f32_16x16x32_bf16 v[86:89], v[162:165], v[198:201], v[86:89]
	v_mfma_f32_16x16x32_bf16 v[82:85], v[170:173], v[198:201], v[82:85]
	v_mfma_f32_16x16x32_bf16 v[82:85], v[166:169], v[190:193], v[82:85]
	v_mfma_f32_16x16x32_bf16 v[66:69], v[166:169], v[202:205], v[66:69]
	v_mfma_f32_16x16x32_bf16 v[66:69], v[170:173], v[206:209], v[66:69]
	v_mfma_f32_16x16x32_bf16 v[70:73], v[162:165], v[206:209], v[70:73]
	v_mfma_f32_16x16x32_bf16 v[70:73], v[158:161], v[202:205], v[70:73]
	s_setprio 0
	s_barrier
	s_add_i32 s18, s44, s9
	v_lshl_add_u64 v[194:195], v[194:195], 0, s[2:3]
	s_mov_b32 m0, s18
	ds_read_b128 v[174:177], v153 offset:49152
	ds_read_b128 v[178:181], v153 offset:50176
	ds_read_b128 v[182:185], v153 offset:51200
	ds_read_b128 v[186:189], v153 offset:52224
	ds_read_b128 v[190:193], v153 offset:53248
	ds_read_b128 v[198:201], v153 offset:54272
	ds_read_b128 v[202:205], v153 offset:55296
	ds_read_b128 v[206:209], v153 offset:56320
	global_load_lds_dwordx4 v[194:195], off
	s_add_i32 m0, s18, 0x2000
	s_add_u32 s4, s4, 0x80080
	v_lshl_add_u64 v[194:195], v[210:211], 0, s[2:3]
	s_addc_u32 s5, s5, 0
	s_add_i32 s18, s47, s9
	global_load_lds_dwordx4 v[194:195], off
	v_lshl_add_u64 v[194:195], s[4:5], 0, v[132:133]
	s_mov_b32 m0, s18
	s_nop 0
	global_load_lds_dwordx4 v[194:195], off
	v_lshl_add_u64 v[194:195], s[4:5], 0, v[136:137]
	s_add_i32 m0, s18, 0x2000
	s_nop 0
	global_load_lds_dwordx4 v[194:195], off
	v_lshl_add_u64 v[194:195], v[212:213], 0, s[2:3]
	s_mov_b32 m0, s51
	s_nop 0
	global_load_lds_dwordx4 v[194:195], off
	v_lshl_add_u64 v[194:195], v[214:215], 0, s[2:3]
	s_mov_b32 m0, s52
	s_nop 0
	global_load_lds_dwordx4 v[194:195], off
	s_waitcnt vmcnt(8)
	s_waitcnt lgkmcnt(0)
	s_barrier
	s_setprio 1
	s_waitcnt lgkmcnt(0)
	v_mfma_f32_16x16x32_bf16 v[62:65], v[140:143], v[174:177], v[62:65]
	v_mfma_f32_16x16x32_bf16 v[62:65], v[144:147], v[178:181], v[62:65]
	v_mfma_f32_16x16x32_bf16 v[58:61], v[154:157], v[178:181], v[58:61]
	v_mfma_f32_16x16x32_bf16 v[58:61], v[148:151], v[174:177], v[58:61]
	v_mfma_f32_16x16x32_bf16 v[42:45], v[148:151], v[182:185], v[42:45]
	v_mfma_f32_16x16x32_bf16 v[42:45], v[154:157], v[186:189], v[42:45]
	v_mfma_f32_16x16x32_bf16 v[46:49], v[144:147], v[186:189], v[46:49]
	v_mfma_f32_16x16x32_bf16 v[46:49], v[140:143], v[182:185], v[46:49]
	v_mfma_f32_16x16x32_bf16 v[30:33], v[140:143], v[190:193], v[30:33]
	v_mfma_f32_16x16x32_bf16 v[30:33], v[144:147], v[198:201], v[30:33]
	v_mfma_f32_16x16x32_bf16 v[26:29], v[154:157], v[198:201], v[26:29]
	v_mfma_f32_16x16x32_bf16 v[26:29], v[148:151], v[190:193], v[26:29]
	v_mfma_f32_16x16x32_bf16 v[10:13], v[148:151], v[202:205], v[10:13]
	v_mfma_f32_16x16x32_bf16 v[10:13], v[154:157], v[206:209], v[10:13]
	v_mfma_f32_16x16x32_bf16 v[14:17], v[144:147], v[206:209], v[14:17]
	v_mfma_f32_16x16x32_bf16 v[14:17], v[140:143], v[202:205], v[14:17]
	s_setprio 0
	s_setprio 1
	v_mfma_f32_16x16x32_bf16 v[54:57], v[158:161], v[174:177], v[54:57]
	v_mfma_f32_16x16x32_bf16 v[54:57], v[162:165], v[178:181], v[54:57]
	v_mfma_f32_16x16x32_bf16 v[50:53], v[170:173], v[178:181], v[50:53]
	v_mfma_f32_16x16x32_bf16 v[50:53], v[166:169], v[174:177], v[50:53]
	v_mfma_f32_16x16x32_bf16 v[34:37], v[166:169], v[182:185], v[34:37]
	v_mfma_f32_16x16x32_bf16 v[34:37], v[170:173], v[186:189], v[34:37]
	v_mfma_f32_16x16x32_bf16 v[38:41], v[162:165], v[186:189], v[38:41]
	v_mfma_f32_16x16x32_bf16 v[38:41], v[158:161], v[182:185], v[38:41]
	v_mfma_f32_16x16x32_bf16 v[22:25], v[158:161], v[190:193], v[22:25]
	v_mfma_f32_16x16x32_bf16 v[22:25], v[162:165], v[198:201], v[22:25]
	v_mfma_f32_16x16x32_bf16 v[18:21], v[170:173], v[198:201], v[18:21]
	v_mfma_f32_16x16x32_bf16 v[18:21], v[166:169], v[190:193], v[18:21]
	v_mfma_f32_16x16x32_bf16 v[2:5], v[166:169], v[202:205], v[2:5]
	v_mfma_f32_16x16x32_bf16 v[2:5], v[170:173], v[206:209], v[2:5]
	v_mfma_f32_16x16x32_bf16 v[6:9], v[162:165], v[206:209], v[6:9]
	v_mfma_f32_16x16x32_bf16 v[6:9], v[158:161], v[202:205], v[6:9]
	s_setprio 0
	s_barrier
	s_cmp_gt_u32 s43, 29
	s_mov_b64 s[4:5], s[16:17]
	s_mov_b32 s18, s43
	s_cbranch_scc0 .LBB0_225

.LBB0_325:
	s_add_i32 s15, s14, 0x100
	s_and_b32 s16, s15, 0x200
	s_add_u32 s16, s8, s16
	s_addc_u32 s17, s9, 0
	s_and_b32 s18, s15, 0x100
	s_add_u32 s18, s16, s18
	s_addc_u32 s19, s17, 0
	s_and_b64 s[16:17], s[12:13], exec
	s_cselect_b32 s17, s9, s19
	s_cselect_b32 s16, s8, s18
	s_add_i32 s50, 0, 0x10000
	s_and_b64 s[12:13], s[12:13], exec
	s_cselect_b32 s13, 0, s15
	s_cselect_b32 s12, 0, 0
	s_add_u32 s18, s6, s13
	s_addc_u32 s19, s7, s12
	s_add_i32 s13, 0, 0x14000
	s_add_u32 s12, s8, s14
	s_addc_u32 s14, s9, 0
	s_add_u32 s22, s12, 0x20080
	s_addc_u32 s23, s14, 0
	s_add_i32 s49, s50, s26
	s_add_i32 m0, s30, 0xc000
	s_add_i32 s52, s30, 0xe000
	s_add_i32 s43, s49, 0x2000
	s_add_u32 s20, s18, 0x1e0000
	v_add_u32_e32 v152, s50, v138
	v_add_u32_e32 v168, s13, v138
	s_addc_u32 s21, s19, 0
	s_add_i32 s47, s13, s26
	ds_read_b128 v[140:143], v152
	ds_read_b128 v[144:147], v152 offset:1024
	ds_read_b128 v[148:151], v152 offset:2048
	ds_read_b128 v[152:155], v152 offset:3072
	ds_read_b128 v[156:159], v168
	ds_read_b128 v[160:163], v168 offset:1024
	ds_read_b128 v[164:167], v168 offset:2048
	ds_read_b128 v[168:171], v168 offset:3072
	s_add_i32 s44, s47, 0x2000
	s_add_i32 s42, 0, 0x18000
	s_add_i32 s41, 0, 0x1c000
	s_add_u32 s14, s16, 0x20000
	s_addc_u32 s15, s17, 0
	s_add_i32 s40, s42, s26
	s_add_i32 s39, s40, 0x2000
	s_add_u32 s12, s18, 0x1e0080
	s_addc_u32 s13, s19, 0
	s_add_i32 s51, s41, s26
	s_add_i32 s50, s51, 0x2000
	v_lshl_add_u64 v[206:207], s[22:23], 0, v[134:135]
	ds_read_b128 v[172:175], v139
	ds_read_b128 v[176:179], v139 offset:1024
	ds_read_b128 v[180:183], v139 offset:2048
	ds_read_b128 v[184:187], v139 offset:3072
	ds_read_b128 v[188:191], v139 offset:4096
	ds_read_b128 v[192:195], v139 offset:5120
	ds_read_b128 v[198:201], v139 offset:6144
	ds_read_b128 v[202:205], v139 offset:7168
	global_load_lds_dwordx4 v[206:207], off
	v_lshl_add_u64 v[206:207], s[22:23], 0, v[132:133]
	s_mov_b32 m0, s52
	s_nop 0
	global_load_lds_dwordx4 v[206:207], off
	s_waitcnt vmcnt(8)
	s_waitcnt lgkmcnt(0)
	s_barrier
	s_setprio 1
	s_waitcnt lgkmcnt(0)
	v_mfma_f32_16x16x32_bf16 v[126:129], v[140:143], v[172:175], v[126:129]
	v_mfma_f32_16x16x32_bf16 v[126:129], v[144:147], v[176:179], v[126:129]
	v_mfma_f32_16x16x32_bf16 v[122:125], v[152:155], v[176:179], v[122:125]
	v_mfma_f32_16x16x32_bf16 v[122:125], v[148:151], v[172:175], v[122:125]
	v_mfma_f32_16x16x32_bf16 v[114:117], v[148:151], v[180:183], v[114:117]
	v_mfma_f32_16x16x32_bf16 v[114:117], v[152:155], v[184:187], v[114:117]
	v_mfma_f32_16x16x32_bf16 v[118:121], v[144:147], v[184:187], v[118:121]
	v_mfma_f32_16x16x32_bf16 v[118:121], v[140:143], v[180:183], v[118:121]
	v_mfma_f32_16x16x32_bf16 v[110:113], v[140:143], v[188:191], v[110:113]
	v_mfma_f32_16x16x32_bf16 v[110:113], v[144:147], v[192:195], v[110:113]
	v_mfma_f32_16x16x32_bf16 v[106:109], v[152:155], v[192:195], v[106:109]
	v_mfma_f32_16x16x32_bf16 v[106:109], v[148:151], v[188:191], v[106:109]
	v_mfma_f32_16x16x32_bf16 v[98:101], v[148:151], v[198:201], v[98:101]
	v_mfma_f32_16x16x32_bf16 v[98:101], v[152:155], v[202:205], v[98:101]
	v_mfma_f32_16x16x32_bf16 v[102:105], v[144:147], v[202:205], v[102:105]
	v_mfma_f32_16x16x32_bf16 v[102:105], v[140:143], v[198:201], v[102:105]
	s_setprio 0
	s_setprio 1
	v_mfma_f32_16x16x32_bf16 v[62:65], v[156:159], v[172:175], v[62:65]
	v_mfma_f32_16x16x32_bf16 v[62:65], v[160:163], v[176:179], v[62:65]
	v_mfma_f32_16x16x32_bf16 v[58:61], v[168:171], v[176:179], v[58:61]
	v_mfma_f32_16x16x32_bf16 v[58:61], v[164:167], v[172:175], v[58:61]
	v_mfma_f32_16x16x32_bf16 v[50:53], v[164:167], v[180:183], v[50:53]
	v_mfma_f32_16x16x32_bf16 v[50:53], v[168:171], v[184:187], v[50:53]
	v_mfma_f32_16x16x32_bf16 v[54:57], v[160:163], v[184:187], v[54:57]
	v_mfma_f32_16x16x32_bf16 v[54:57], v[156:159], v[180:183], v[54:57]
	v_mfma_f32_16x16x32_bf16 v[46:49], v[156:159], v[188:191], v[46:49]
	v_mfma_f32_16x16x32_bf16 v[46:49], v[160:163], v[192:195], v[46:49]
	v_mfma_f32_16x16x32_bf16 v[42:45], v[168:171], v[192:195], v[42:45]
	v_mfma_f32_16x16x32_bf16 v[42:45], v[164:167], v[188:191], v[42:45]
	v_mfma_f32_16x16x32_bf16 v[34:37], v[164:167], v[198:201], v[34:37]
	v_mfma_f32_16x16x32_bf16 v[34:37], v[168:171], v[202:205], v[34:37]
	v_mfma_f32_16x16x32_bf16 v[38:41], v[160:163], v[202:205], v[38:41]
	v_mfma_f32_16x16x32_bf16 v[38:41], v[156:159], v[198:201], v[38:41]
	s_setprio 0
	s_barrier
	s_mov_b32 m0, s49
	v_lshl_add_u64 v[206:207], s[18:19], 0, v[196:197]
	ds_read_b128 v[172:175], v139 offset:16384
	ds_read_b128 v[176:179], v139 offset:17408
	ds_read_b128 v[180:183], v139 offset:18432
	ds_read_b128 v[184:187], v139 offset:19456
	ds_read_b128 v[188:191], v139 offset:20480
	ds_read_b128 v[192:195], v139 offset:21504
	ds_read_b128 v[198:201], v139 offset:22528
	ds_read_b128 v[202:205], v139 offset:23552
	global_load_lds_dwordx4 v[206:207], off
	v_lshl_add_u64 v[208:209], s[18:19], 0, v[130:131]
	s_mov_b32 m0, s43
	v_lshl_add_u64 v[210:211], s[20:21], 0, v[196:197]
	global_load_lds_dwordx4 v[208:209], off
	s_mov_b32 m0, s47
	v_lshl_add_u64 v[212:213], s[16:17], 0, v[132:133]
	global_load_lds_dwordx4 v[210:211], off
	v_lshl_add_u64 v[210:211], s[20:21], 0, v[130:131]
	s_mov_b32 m0, s44
	s_nop 0
	global_load_lds_dwordx4 v[210:211], off
	v_lshl_add_u64 v[210:211], s[16:17], 0, v[134:135]
	s_mov_b32 m0, s30
	s_nop 0
	global_load_lds_dwordx4 v[210:211], off
	s_mov_b32 m0, s31
	s_nop 0
	global_load_lds_dwordx4 v[212:213], off
	s_waitcnt vmcnt(8)
	s_waitcnt lgkmcnt(0)
	s_barrier
	s_setprio 1
	s_waitcnt lgkmcnt(0)
	v_mfma_f32_16x16x32_bf16 v[94:97], v[140:143], v[172:175], v[94:97]
	v_mfma_f32_16x16x32_bf16 v[94:97], v[144:147], v[176:179], v[94:97]
	v_mfma_f32_16x16x32_bf16 v[90:93], v[152:155], v[176:179], v[90:93]
	v_mfma_f32_16x16x32_bf16 v[90:93], v[148:151], v[172:175], v[90:93]
	v_mfma_f32_16x16x32_bf16 v[82:85], v[148:151], v[180:183], v[82:85]
	v_mfma_f32_16x16x32_bf16 v[82:85], v[152:155], v[184:187], v[82:85]
	v_mfma_f32_16x16x32_bf16 v[86:89], v[144:147], v[184:187], v[86:89]
	v_mfma_f32_16x16x32_bf16 v[86:89], v[140:143], v[180:183], v[86:89]
	v_mfma_f32_16x16x32_bf16 v[78:81], v[140:143], v[188:191], v[78:81]
	v_mfma_f32_16x16x32_bf16 v[78:81], v[144:147], v[192:195], v[78:81]
	v_mfma_f32_16x16x32_bf16 v[74:77], v[152:155], v[192:195], v[74:77]
	v_mfma_f32_16x16x32_bf16 v[74:77], v[148:151], v[188:191], v[74:77]
	v_mfma_f32_16x16x32_bf16 v[66:69], v[148:151], v[198:201], v[66:69]
	v_mfma_f32_16x16x32_bf16 v[66:69], v[152:155], v[202:205], v[66:69]
	v_mfma_f32_16x16x32_bf16 v[70:73], v[144:147], v[202:205], v[70:73]
	v_mfma_f32_16x16x32_bf16 v[70:73], v[140:143], v[198:201], v[70:73]
	s_setprio 0
	s_setprio 1
	v_mfma_f32_16x16x32_bf16 v[30:33], v[156:159], v[172:175], v[30:33]
	v_mfma_f32_16x16x32_bf16 v[30:33], v[160:163], v[176:179], v[30:33]
	v_mfma_f32_16x16x32_bf16 v[26:29], v[168:171], v[176:179], v[26:29]
	v_mfma_f32_16x16x32_bf16 v[26:29], v[164:167], v[172:175], v[26:29]
	v_mfma_f32_16x16x32_bf16 v[18:21], v[164:167], v[180:183], v[18:21]
	v_mfma_f32_16x16x32_bf16 v[18:21], v[168:171], v[184:187], v[18:21]
	v_mfma_f32_16x16x32_bf16 v[22:25], v[160:163], v[184:187], v[22:25]
	v_mfma_f32_16x16x32_bf16 v[22:25], v[156:159], v[180:183], v[22:25]
	v_mfma_f32_16x16x32_bf16 v[14:17], v[156:159], v[188:191], v[14:17]
	v_mfma_f32_16x16x32_bf16 v[14:17], v[160:163], v[192:195], v[14:17]
	v_mfma_f32_16x16x32_bf16 v[10:13], v[168:171], v[192:195], v[10:13]
	v_mfma_f32_16x16x32_bf16 v[10:13], v[164:167], v[188:191], v[10:13]
	v_mfma_f32_16x16x32_bf16 v[2:5], v[164:167], v[198:201], v[2:5]
	v_mfma_f32_16x16x32_bf16 v[2:5], v[168:171], v[202:205], v[2:5]
	v_mfma_f32_16x16x32_bf16 v[6:9], v[160:163], v[202:205], v[6:9]
	v_mfma_f32_16x16x32_bf16 v[6:9], v[156:159], v[198:201], v[6:9]
	s_setprio 0
	s_barrier
	v_add_u32_e32 v152, s42, v138
	v_add_u32_e32 v168, s41, v138
	ds_read_b128 v[140:143], v152
	ds_read_b128 v[144:147], v152 offset:1024
	ds_read_b128 v[148:151], v152 offset:2048
	ds_read_b128 v[152:155], v152 offset:3072
	ds_read_b128 v[156:159], v168
	ds_read_b128 v[160:163], v168 offset:1024
	ds_read_b128 v[164:167], v168 offset:2048
	ds_read_b128 v[168:171], v168 offset:3072
	s_mov_b32 m0, s33
	v_lshl_add_u64 v[214:215], s[14:15], 0, v[134:135]
	ds_read_b128 v[172:175], v139 offset:32768
	ds_read_b128 v[176:179], v139 offset:33792
	ds_read_b128 v[180:183], v139 offset:34816
	ds_read_b128 v[184:187], v139 offset:35840
	ds_read_b128 v[188:191], v139 offset:36864
	ds_read_b128 v[192:195], v139 offset:37888
	ds_read_b128 v[198:201], v139 offset:38912
	ds_read_b128 v[202:205], v139 offset:39936
	global_load_lds_dwordx4 v[214:215], off
	v_lshl_add_u64 v[214:215], s[14:15], 0, v[132:133]
	s_mov_b32 m0, s35
	s_nop 0
	global_load_lds_dwordx4 v[214:215], off
	s_waitcnt vmcnt(8)
	s_waitcnt lgkmcnt(0)
	s_barrier
	s_setprio 1
	s_waitcnt lgkmcnt(0)
	v_mfma_f32_16x16x32_bf16 v[126:129], v[140:143], v[172:175], v[126:129]
	v_mfma_f32_16x16x32_bf16 v[126:129], v[144:147], v[176:179], v[126:129]
	v_mfma_f32_16x16x32_bf16 v[122:125], v[152:155], v[176:179], v[122:125]
	v_mfma_f32_16x16x32_bf16 v[122:125], v[148:151], v[172:175], v[122:125]
	v_mfma_f32_16x16x32_bf16 v[114:117], v[148:151], v[180:183], v[114:117]
	v_mfma_f32_16x16x32_bf16 v[114:117], v[152:155], v[184:187], v[114:117]
	v_mfma_f32_16x16x32_bf16 v[118:121], v[144:147], v[184:187], v[118:121]
	v_mfma_f32_16x16x32_bf16 v[118:121], v[140:143], v[180:183], v[118:121]
	v_mfma_f32_16x16x32_bf16 v[110:113], v[140:143], v[188:191], v[110:113]
	v_mfma_f32_16x16x32_bf16 v[110:113], v[144:147], v[192:195], v[110:113]
	v_mfma_f32_16x16x32_bf16 v[106:109], v[152:155], v[192:195], v[106:109]
	v_mfma_f32_16x16x32_bf16 v[106:109], v[148:151], v[188:191], v[106:109]
	v_mfma_f32_16x16x32_bf16 v[98:101], v[148:151], v[198:201], v[98:101]
	v_mfma_f32_16x16x32_bf16 v[98:101], v[152:155], v[202:205], v[98:101]
	v_mfma_f32_16x16x32_bf16 v[102:105], v[144:147], v[202:205], v[102:105]
	v_mfma_f32_16x16x32_bf16 v[102:105], v[140:143], v[198:201], v[102:105]
	s_setprio 0
	s_setprio 1
	v_mfma_f32_16x16x32_bf16 v[62:65], v[156:159], v[172:175], v[62:65]
	v_mfma_f32_16x16x32_bf16 v[62:65], v[160:163], v[176:179], v[62:65]
	v_mfma_f32_16x16x32_bf16 v[58:61], v[168:171], v[176:179], v[58:61]
	v_mfma_f32_16x16x32_bf16 v[58:61], v[164:167], v[172:175], v[58:61]
	v_mfma_f32_16x16x32_bf16 v[50:53], v[164:167], v[180:183], v[50:53]
	v_mfma_f32_16x16x32_bf16 v[50:53], v[168:171], v[184:187], v[50:53]
	v_mfma_f32_16x16x32_bf16 v[54:57], v[160:163], v[184:187], v[54:57]
	v_mfma_f32_16x16x32_bf16 v[54:57], v[156:159], v[180:183], v[54:57]
	v_mfma_f32_16x16x32_bf16 v[46:49], v[156:159], v[188:191], v[46:49]
	v_mfma_f32_16x16x32_bf16 v[46:49], v[160:163], v[192:195], v[46:49]
	v_mfma_f32_16x16x32_bf16 v[42:45], v[168:171], v[192:195], v[42:45]
	v_mfma_f32_16x16x32_bf16 v[42:45], v[164:167], v[188:191], v[42:45]
	v_mfma_f32_16x16x32_bf16 v[34:37], v[164:167], v[198:201], v[34:37]
	v_mfma_f32_16x16x32_bf16 v[34:37], v[168:171], v[202:205], v[34:37]
	v_mfma_f32_16x16x32_bf16 v[38:41], v[160:163], v[202:205], v[38:41]
	v_mfma_f32_16x16x32_bf16 v[38:41], v[156:159], v[198:201], v[38:41]
	s_setprio 0
	s_barrier
	s_mov_b32 m0, s40
	v_lshl_add_u64 v[206:207], v[206:207], 0, s[2:3]
	ds_read_b128 v[172:175], v139 offset:49152
	ds_read_b128 v[176:179], v139 offset:50176
	ds_read_b128 v[180:183], v139 offset:51200
	ds_read_b128 v[184:187], v139 offset:52224
	ds_read_b128 v[188:191], v139 offset:53248
	ds_read_b128 v[192:195], v139 offset:54272
	ds_read_b128 v[198:201], v139 offset:55296
	ds_read_b128 v[202:205], v139 offset:56320
	global_load_lds_dwordx4 v[206:207], off
	v_lshl_add_u64 v[206:207], v[208:209], 0, s[2:3]
	s_mov_b32 m0, s39
	s_nop 0
	global_load_lds_dwordx4 v[206:207], off
	v_lshl_add_u64 v[206:207], s[12:13], 0, v[196:197]
	s_mov_b32 m0, s51
	s_nop 0
	global_load_lds_dwordx4 v[206:207], off
	v_lshl_add_u64 v[206:207], s[12:13], 0, v[130:131]
	s_mov_b32 m0, s50
	s_nop 0
	global_load_lds_dwordx4 v[206:207], off
	v_lshl_add_u64 v[206:207], v[210:211], 0, s[2:3]
	s_mov_b32 m0, s37
	s_nop 0
	global_load_lds_dwordx4 v[206:207], off
	v_lshl_add_u64 v[206:207], v[212:213], 0, s[2:3]
	s_mov_b32 m0, s38
	s_nop 0
	global_load_lds_dwordx4 v[206:207], off
	s_waitcnt vmcnt(8)
	s_waitcnt lgkmcnt(0)
	s_barrier
	s_setprio 1
	s_waitcnt lgkmcnt(0)
	v_mfma_f32_16x16x32_bf16 v[94:97], v[140:143], v[172:175], v[94:97]
	v_mfma_f32_16x16x32_bf16 v[94:97], v[144:147], v[176:179], v[94:97]
	v_mfma_f32_16x16x32_bf16 v[90:93], v[152:155], v[176:179], v[90:93]
	v_mfma_f32_16x16x32_bf16 v[90:93], v[148:151], v[172:175], v[90:93]
	v_mfma_f32_16x16x32_bf16 v[82:85], v[148:151], v[180:183], v[82:85]
	v_mfma_f32_16x16x32_bf16 v[82:85], v[152:155], v[184:187], v[82:85]
	v_mfma_f32_16x16x32_bf16 v[86:89], v[144:147], v[184:187], v[86:89]
	v_mfma_f32_16x16x32_bf16 v[86:89], v[140:143], v[180:183], v[86:89]
	v_mfma_f32_16x16x32_bf16 v[78:81], v[140:143], v[188:191], v[78:81]
	v_mfma_f32_16x16x32_bf16 v[78:81], v[144:147], v[192:195], v[78:81]
	v_mfma_f32_16x16x32_bf16 v[74:77], v[152:155], v[192:195], v[74:77]
	v_mfma_f32_16x16x32_bf16 v[74:77], v[148:151], v[188:191], v[74:77]
	v_mfma_f32_16x16x32_bf16 v[66:69], v[148:151], v[198:201], v[66:69]
	v_mfma_f32_16x16x32_bf16 v[66:69], v[152:155], v[202:205], v[66:69]
	v_mfma_f32_16x16x32_bf16 v[70:73], v[144:147], v[202:205], v[70:73]
	v_mfma_f32_16x16x32_bf16 v[70:73], v[140:143], v[198:201], v[70:73]
	s_setprio 0
	s_setprio 1
	v_mfma_f32_16x16x32_bf16 v[30:33], v[156:159], v[172:175], v[30:33]
	v_mfma_f32_16x16x32_bf16 v[30:33], v[160:163], v[176:179], v[30:33]
	v_mfma_f32_16x16x32_bf16 v[26:29], v[168:171], v[176:179], v[26:29]
	v_mfma_f32_16x16x32_bf16 v[26:29], v[164:167], v[172:175], v[26:29]
	v_mfma_f32_16x16x32_bf16 v[18:21], v[164:167], v[180:183], v[18:21]
	v_mfma_f32_16x16x32_bf16 v[18:21], v[168:171], v[184:187], v[18:21]
	v_mfma_f32_16x16x32_bf16 v[22:25], v[160:163], v[184:187], v[22:25]
	v_mfma_f32_16x16x32_bf16 v[22:25], v[156:159], v[180:183], v[22:25]
	v_mfma_f32_16x16x32_bf16 v[14:17], v[156:159], v[188:191], v[14:17]
	v_mfma_f32_16x16x32_bf16 v[14:17], v[160:163], v[192:195], v[14:17]
	v_mfma_f32_16x16x32_bf16 v[10:13], v[168:171], v[192:195], v[10:13]
	v_mfma_f32_16x16x32_bf16 v[10:13], v[164:167], v[188:191], v[10:13]
	v_mfma_f32_16x16x32_bf16 v[2:5], v[164:167], v[198:201], v[2:5]
	v_mfma_f32_16x16x32_bf16 v[2:5], v[168:171], v[202:205], v[2:5]
	v_mfma_f32_16x16x32_bf16 v[6:9], v[160:163], v[202:205], v[6:9]
	v_mfma_f32_16x16x32_bf16 v[6:9], v[156:159], v[198:201], v[6:9]
	s_setprio 0
	s_barrier
	s_andn2_b64 vcc, exec, s[10:11]
	s_mov_b64 s[12:13], -1
	s_mov_b64 s[10:11], 0
	s_movk_i32 s14, 0x100
	s_cbranch_vccz .LBB0_325
	s_cmpk_lt_u32 s25, 0x100
	s_cbranch_scc0 .LBB0_328
	s_barrier

.LBB0_398:
	s_add_i32 s52, s24, 2
	s_lshr_b32 s44, s52, 2
	s_lshl_b64 s[22:23], s[44:45], 9
	s_add_u32 s22, s14, s22
	s_addc_u32 s23, s15, s23
	s_and_b32 s25, s20, 0x100
	s_add_u32 s53, s22, s25
	s_addc_u32 s55, s23, 0
	s_add_i32 s22, s24, 4
	s_lshr_b32 s44, s22, 2
	s_lshl_b64 s[22:23], s[44:45], 9
	s_add_u32 s25, s14, s22
	s_addc_u32 s44, s15, s23
	s_add_u32 s22, s20, 0x100
	s_addc_u32 s23, s21, 0
	s_and_b32 s54, s22, 0x100
	s_add_u32 s54, s25, s54
	s_addc_u32 s25, s44, 0
	s_add_u32 s20, s50, s20
	s_addc_u32 s21, s51, s21
	s_add_i32 s44, 0, 0x10000
	s_cmp_eq_u32 s24, 28
	s_cselect_b32 s25, s17, s25
	s_cselect_b32 s24, s16, s54
	v_add_u32_e32 v136, s44, v139
	s_cselect_b32 s21, s19, s21
	s_cselect_b32 s20, s18, s20
	s_add_i32 s56, 0, 0x14000
	ds_read_b128 v[142:145], v136
	ds_read_b128 v[146:149], v136 offset:1024
	ds_read_b128 v[150:153], v136 offset:2048
	ds_read_b128 v[154:157], v136 offset:3072
	v_add_u32_e32 v136, s56, v139
	ds_read_b128 v[158:161], v136
	ds_read_b128 v[162:165], v136 offset:1024
	ds_read_b128 v[166:169], v136 offset:2048
	ds_read_b128 v[170:173], v136 offset:3072
	s_add_u32 s54, s53, 0x80080
	s_addc_u32 s55, s55, 0
	v_lshl_add_u64 v[136:137], s[54:55], 0, v[134:135]
	s_add_i32 m0, s34, 0xc000
	ds_read_b128 v[174:177], v141
	ds_read_b128 v[178:181], v141 offset:1024
	ds_read_b128 v[182:185], v141 offset:2048
	ds_read_b128 v[186:189], v141 offset:3072
	ds_read_b128 v[190:193], v141 offset:4096
	ds_read_b128 v[198:201], v141 offset:5120
	ds_read_b128 v[202:205], v141 offset:6144
	ds_read_b128 v[206:209], v141 offset:7168
	global_load_lds_dwordx4 v[136:137], off
	v_lshl_add_u64 v[136:137], s[54:55], 0, v[132:133]
	s_add_i32 m0, s34, 0xe000
	s_nop 0
	global_load_lds_dwordx4 v[136:137], off
	s_waitcnt vmcnt(8)
	s_waitcnt lgkmcnt(0)
	s_barrier
	s_setprio 1
	s_waitcnt lgkmcnt(0)
	v_mfma_f32_16x16x32_bf16 v[126:129], v[142:145], v[174:177], v[126:129]
	v_mfma_f32_16x16x32_bf16 v[126:129], v[146:149], v[178:181], v[126:129]
	v_mfma_f32_16x16x32_bf16 v[122:125], v[154:157], v[178:181], v[122:125]
	v_mfma_f32_16x16x32_bf16 v[122:125], v[150:153], v[174:177], v[122:125]
	v_mfma_f32_16x16x32_bf16 v[106:109], v[150:153], v[182:185], v[106:109]
	v_mfma_f32_16x16x32_bf16 v[106:109], v[154:157], v[186:189], v[106:109]
	v_mfma_f32_16x16x32_bf16 v[114:117], v[146:149], v[186:189], v[114:117]
	v_mfma_f32_16x16x32_bf16 v[114:117], v[142:145], v[182:185], v[114:117]
	v_mfma_f32_16x16x32_bf16 v[98:101], v[142:145], v[190:193], v[98:101]
	v_mfma_f32_16x16x32_bf16 v[98:101], v[146:149], v[198:201], v[98:101]
	v_mfma_f32_16x16x32_bf16 v[90:93], v[154:157], v[198:201], v[90:93]
	v_mfma_f32_16x16x32_bf16 v[90:93], v[150:153], v[190:193], v[90:93]
	v_mfma_f32_16x16x32_bf16 v[74:77], v[150:153], v[202:205], v[74:77]
	v_mfma_f32_16x16x32_bf16 v[74:77], v[154:157], v[206:209], v[74:77]
	v_mfma_f32_16x16x32_bf16 v[82:85], v[146:149], v[206:209], v[82:85]
	v_mfma_f32_16x16x32_bf16 v[82:85], v[142:145], v[202:205], v[82:85]
	s_setprio 0
	s_setprio 1
	v_mfma_f32_16x16x32_bf16 v[118:121], v[158:161], v[174:177], v[118:121]
	v_mfma_f32_16x16x32_bf16 v[118:121], v[162:165], v[178:181], v[118:121]
	v_mfma_f32_16x16x32_bf16 v[110:113], v[170:173], v[178:181], v[110:113]
	v_mfma_f32_16x16x32_bf16 v[110:113], v[166:169], v[174:177], v[110:113]
	v_mfma_f32_16x16x32_bf16 v[94:97], v[166:169], v[182:185], v[94:97]
	v_mfma_f32_16x16x32_bf16 v[94:97], v[170:173], v[186:189], v[94:97]
	v_mfma_f32_16x16x32_bf16 v[102:105], v[162:165], v[186:189], v[102:105]
	v_mfma_f32_16x16x32_bf16 v[102:105], v[158:161], v[182:185], v[102:105]
	v_mfma_f32_16x16x32_bf16 v[86:89], v[158:161], v[190:193], v[86:89]
	v_mfma_f32_16x16x32_bf16 v[86:89], v[162:165], v[198:201], v[86:89]
	v_mfma_f32_16x16x32_bf16 v[78:81], v[170:173], v[198:201], v[78:81]
	v_mfma_f32_16x16x32_bf16 v[78:81], v[166:169], v[190:193], v[78:81]
	v_mfma_f32_16x16x32_bf16 v[66:69], v[166:169], v[202:205], v[66:69]
	v_mfma_f32_16x16x32_bf16 v[66:69], v[170:173], v[206:209], v[66:69]
	v_mfma_f32_16x16x32_bf16 v[70:73], v[162:165], v[206:209], v[70:73]
	v_mfma_f32_16x16x32_bf16 v[70:73], v[158:161], v[202:205], v[70:73]
	s_setprio 0
	s_barrier
	s_add_i32 s44, s44, s33
	v_lshl_add_u64 v[136:137], s[20:21], 0, v[196:197]
	s_mov_b32 m0, s44
	ds_read_b128 v[174:177], v141 offset:16384
	ds_read_b128 v[178:181], v141 offset:17408
	ds_read_b128 v[182:185], v141 offset:18432
	ds_read_b128 v[186:189], v141 offset:19456
	ds_read_b128 v[190:193], v141 offset:20480
	ds_read_b128 v[198:201], v141 offset:21504
	ds_read_b128 v[202:205], v141 offset:22528
	ds_read_b128 v[206:209], v141 offset:23552
	global_load_lds_dwordx4 v[136:137], off
	s_add_i32 m0, s44, 0x2000
	s_add_u32 s54, s20, 0x80000
	v_lshl_add_u64 v[194:195], s[20:21], 0, v[130:131]
	s_addc_u32 s55, s21, 0
	s_add_i32 s44, s56, s33
	global_load_lds_dwordx4 v[194:195], off
	v_lshl_add_u64 v[210:211], s[54:55], 0, v[196:197]
	s_mov_b32 m0, s44
	v_lshl_add_u64 v[212:213], s[24:25], 0, v[132:133]
	global_load_lds_dwordx4 v[210:211], off
	v_lshl_add_u64 v[210:211], s[54:55], 0, v[130:131]
	s_add_i32 m0, s44, 0x2000
	s_nop 0
	global_load_lds_dwordx4 v[210:211], off
	v_lshl_add_u64 v[210:211], s[24:25], 0, v[134:135]
	s_mov_b32 m0, s34
	s_nop 0
	global_load_lds_dwordx4 v[210:211], off
	s_mov_b32 m0, s35
	s_nop 0
	global_load_lds_dwordx4 v[212:213], off
	s_waitcnt vmcnt(8)
	s_waitcnt lgkmcnt(0)
	s_barrier
	s_setprio 1
	s_waitcnt lgkmcnt(0)
	v_mfma_f32_16x16x32_bf16 v[62:65], v[142:145], v[174:177], v[62:65]
	v_mfma_f32_16x16x32_bf16 v[62:65], v[146:149], v[178:181], v[62:65]
	v_mfma_f32_16x16x32_bf16 v[58:61], v[154:157], v[178:181], v[58:61]
	v_mfma_f32_16x16x32_bf16 v[58:61], v[150:153], v[174:177], v[58:61]
	v_mfma_f32_16x16x32_bf16 v[42:45], v[150:153], v[182:185], v[42:45]
	v_mfma_f32_16x16x32_bf16 v[42:45], v[154:157], v[186:189], v[42:45]
	v_mfma_f32_16x16x32_bf16 v[50:53], v[146:149], v[186:189], v[50:53]
	v_mfma_f32_16x16x32_bf16 v[50:53], v[142:145], v[182:185], v[50:53]
	v_mfma_f32_16x16x32_bf16 v[34:37], v[142:145], v[190:193], v[34:37]
	v_mfma_f32_16x16x32_bf16 v[34:37], v[146:149], v[198:201], v[34:37]
	v_mfma_f32_16x16x32_bf16 v[26:29], v[154:157], v[198:201], v[26:29]
	v_mfma_f32_16x16x32_bf16 v[26:29], v[150:153], v[190:193], v[26:29]
	v_mfma_f32_16x16x32_bf16 v[10:13], v[150:153], v[202:205], v[10:13]
	v_mfma_f32_16x16x32_bf16 v[10:13], v[154:157], v[206:209], v[10:13]
	v_mfma_f32_16x16x32_bf16 v[18:21], v[146:149], v[206:209], v[18:21]
	v_mfma_f32_16x16x32_bf16 v[18:21], v[142:145], v[202:205], v[18:21]
	s_setprio 0
	s_setprio 1
	v_mfma_f32_16x16x32_bf16 v[54:57], v[158:161], v[174:177], v[54:57]
	v_mfma_f32_16x16x32_bf16 v[54:57], v[162:165], v[178:181], v[54:57]
	v_mfma_f32_16x16x32_bf16 v[46:49], v[170:173], v[178:181], v[46:49]
	v_mfma_f32_16x16x32_bf16 v[46:49], v[166:169], v[174:177], v[46:49]
	v_mfma_f32_16x16x32_bf16 v[30:33], v[166:169], v[182:185], v[30:33]
	v_mfma_f32_16x16x32_bf16 v[30:33], v[170:173], v[186:189], v[30:33]
	v_mfma_f32_16x16x32_bf16 v[38:41], v[162:165], v[186:189], v[38:41]
	v_mfma_f32_16x16x32_bf16 v[38:41], v[158:161], v[182:185], v[38:41]
	v_mfma_f32_16x16x32_bf16 v[22:25], v[158:161], v[190:193], v[22:25]
	v_mfma_f32_16x16x32_bf16 v[22:25], v[162:165], v[198:201], v[22:25]
	v_mfma_f32_16x16x32_bf16 v[14:17], v[170:173], v[198:201], v[14:17]
	v_mfma_f32_16x16x32_bf16 v[14:17], v[166:169], v[190:193], v[14:17]
	v_mfma_f32_16x16x32_bf16 v[2:5], v[166:169], v[202:205], v[2:5]
	v_mfma_f32_16x16x32_bf16 v[2:5], v[170:173], v[206:209], v[2:5]
	v_mfma_f32_16x16x32_bf16 v[6:9], v[162:165], v[206:209], v[6:9]
	v_mfma_f32_16x16x32_bf16 v[6:9], v[158:161], v[202:205], v[6:9]
	s_setprio 0
	s_barrier
	s_add_i32 s44, 0, 0x18000
	s_add_i32 s53, 0, 0x1c000
	v_add_u32_e32 v154, s44, v139
	v_add_u32_e32 v170, s53, v139
	ds_read_b128 v[142:145], v154
	ds_read_b128 v[146:149], v154 offset:1024
	ds_read_b128 v[150:153], v154 offset:2048
	ds_read_b128 v[154:157], v154 offset:3072
	ds_read_b128 v[158:161], v170
	ds_read_b128 v[162:165], v170 offset:1024
	ds_read_b128 v[166:169], v170 offset:2048
	ds_read_b128 v[170:173], v170 offset:3072
	s_add_u32 s24, s24, 0x80000
	s_addc_u32 s25, s25, 0
	s_mov_b32 m0, s36
	v_lshl_add_u64 v[214:215], s[24:25], 0, v[134:135]
	ds_read_b128 v[174:177], v141 offset:32768
	ds_read_b128 v[178:181], v141 offset:33792
	ds_read_b128 v[182:185], v141 offset:34816
	ds_read_b128 v[186:189], v141 offset:35840
	ds_read_b128 v[190:193], v141 offset:36864
	ds_read_b128 v[198:201], v141 offset:37888
	ds_read_b128 v[202:205], v141 offset:38912
	ds_read_b128 v[206:209], v141 offset:39936
	global_load_lds_dwordx4 v[214:215], off
	v_lshl_add_u64 v[214:215], s[24:25], 0, v[132:133]
	s_mov_b32 m0, s37
	s_nop 0
	global_load_lds_dwordx4 v[214:215], off
	s_waitcnt vmcnt(8)
	s_waitcnt lgkmcnt(0)
	s_barrier
	s_setprio 1
	s_waitcnt lgkmcnt(0)
	v_mfma_f32_16x16x32_bf16 v[126:129], v[142:145], v[174:177], v[126:129]
	v_mfma_f32_16x16x32_bf16 v[126:129], v[146:149], v[178:181], v[126:129]
	v_mfma_f32_16x16x32_bf16 v[122:125], v[154:157], v[178:181], v[122:125]
	v_mfma_f32_16x16x32_bf16 v[122:125], v[150:153], v[174:177], v[122:125]
	v_mfma_f32_16x16x32_bf16 v[106:109], v[150:153], v[182:185], v[106:109]
	v_mfma_f32_16x16x32_bf16 v[106:109], v[154:157], v[186:189], v[106:109]
	v_mfma_f32_16x16x32_bf16 v[114:117], v[146:149], v[186:189], v[114:117]
	v_mfma_f32_16x16x32_bf16 v[114:117], v[142:145], v[182:185], v[114:117]
	v_mfma_f32_16x16x32_bf16 v[98:101], v[142:145], v[190:193], v[98:101]
	v_mfma_f32_16x16x32_bf16 v[98:101], v[146:149], v[198:201], v[98:101]
	v_mfma_f32_16x16x32_bf16 v[90:93], v[154:157], v[198:201], v[90:93]
	v_mfma_f32_16x16x32_bf16 v[90:93], v[150:153], v[190:193], v[90:93]
	v_mfma_f32_16x16x32_bf16 v[74:77], v[150:153], v[202:205], v[74:77]
	v_mfma_f32_16x16x32_bf16 v[74:77], v[154:157], v[206:209], v[74:77]
	v_mfma_f32_16x16x32_bf16 v[82:85], v[146:149], v[206:209], v[82:85]
	v_mfma_f32_16x16x32_bf16 v[82:85], v[142:145], v[202:205], v[82:85]
	s_setprio 0
	s_setprio 1
	v_mfma_f32_16x16x32_bf16 v[118:121], v[158:161], v[174:177], v[118:121]
	v_mfma_f32_16x16x32_bf16 v[118:121], v[162:165], v[178:181], v[118:121]
	v_mfma_f32_16x16x32_bf16 v[110:113], v[170:173], v[178:181], v[110:113]
	v_mfma_f32_16x16x32_bf16 v[110:113], v[166:169], v[174:177], v[110:113]
	v_mfma_f32_16x16x32_bf16 v[94:97], v[166:169], v[182:185], v[94:97]
	v_mfma_f32_16x16x32_bf16 v[94:97], v[170:173], v[186:189], v[94:97]
	v_mfma_f32_16x16x32_bf16 v[102:105], v[162:165], v[186:189], v[102:105]
	v_mfma_f32_16x16x32_bf16 v[102:105], v[158:161], v[182:185], v[102:105]
	v_mfma_f32_16x16x32_bf16 v[86:89], v[158:161], v[190:193], v[86:89]
	v_mfma_f32_16x16x32_bf16 v[86:89], v[162:165], v[198:201], v[86:89]
	v_mfma_f32_16x16x32_bf16 v[78:81], v[170:173], v[198:201], v[78:81]
	v_mfma_f32_16x16x32_bf16 v[78:81], v[166:169], v[190:193], v[78:81]
	v_mfma_f32_16x16x32_bf16 v[66:69], v[166:169], v[202:205], v[66:69]
	v_mfma_f32_16x16x32_bf16 v[66:69], v[170:173], v[206:209], v[66:69]
	v_mfma_f32_16x16x32_bf16 v[70:73], v[162:165], v[206:209], v[70:73]
	v_mfma_f32_16x16x32_bf16 v[70:73], v[158:161], v[202:205], v[70:73]
	s_setprio 0
	s_barrier
	s_add_i32 s24, s44, s33
	v_lshl_add_u64 v[136:137], v[136:137], 0, s[2:3]
	s_mov_b32 m0, s24
	ds_read_b128 v[174:177], v141 offset:49152
	ds_read_b128 v[178:181], v141 offset:50176
	ds_read_b128 v[182:185], v141 offset:51200
	ds_read_b128 v[186:189], v141 offset:52224
	ds_read_b128 v[190:193], v141 offset:53248
	ds_read_b128 v[198:201], v141 offset:54272
	ds_read_b128 v[202:205], v141 offset:55296
	ds_read_b128 v[206:209], v141 offset:56320
	global_load_lds_dwordx4 v[136:137], off
	s_add_i32 m0, s24, 0x2000
	s_add_u32 s20, s20, 0x80080
	v_lshl_add_u64 v[136:137], v[194:195], 0, s[2:3]
	s_addc_u32 s21, s21, 0
	s_add_i32 s24, s53, s33
	global_load_lds_dwordx4 v[136:137], off
	v_lshl_add_u64 v[136:137], s[20:21], 0, v[196:197]
	s_mov_b32 m0, s24
	s_nop 0
	global_load_lds_dwordx4 v[136:137], off
	v_lshl_add_u64 v[136:137], s[20:21], 0, v[130:131]
	s_add_i32 m0, s24, 0x2000
	s_nop 0
	global_load_lds_dwordx4 v[136:137], off
	v_lshl_add_u64 v[136:137], v[210:211], 0, s[2:3]
	s_mov_b32 m0, s38
	s_nop 0
	global_load_lds_dwordx4 v[136:137], off
	v_lshl_add_u64 v[136:137], v[212:213], 0, s[2:3]
	s_mov_b32 m0, s39
	s_nop 0
	global_load_lds_dwordx4 v[136:137], off
	s_waitcnt vmcnt(8)
	s_waitcnt lgkmcnt(0)
	s_barrier
	s_setprio 1
	s_waitcnt lgkmcnt(0)
	v_mfma_f32_16x16x32_bf16 v[62:65], v[142:145], v[174:177], v[62:65]
	v_mfma_f32_16x16x32_bf16 v[62:65], v[146:149], v[178:181], v[62:65]
	v_mfma_f32_16x16x32_bf16 v[58:61], v[154:157], v[178:181], v[58:61]
	v_mfma_f32_16x16x32_bf16 v[58:61], v[150:153], v[174:177], v[58:61]
	v_mfma_f32_16x16x32_bf16 v[42:45], v[150:153], v[182:185], v[42:45]
	v_mfma_f32_16x16x32_bf16 v[42:45], v[154:157], v[186:189], v[42:45]
	v_mfma_f32_16x16x32_bf16 v[50:53], v[146:149], v[186:189], v[50:53]
	v_mfma_f32_16x16x32_bf16 v[50:53], v[142:145], v[182:185], v[50:53]
	v_mfma_f32_16x16x32_bf16 v[34:37], v[142:145], v[190:193], v[34:37]
	v_mfma_f32_16x16x32_bf16 v[34:37], v[146:149], v[198:201], v[34:37]
	v_mfma_f32_16x16x32_bf16 v[26:29], v[154:157], v[198:201], v[26:29]
	v_mfma_f32_16x16x32_bf16 v[26:29], v[150:153], v[190:193], v[26:29]
	v_mfma_f32_16x16x32_bf16 v[10:13], v[150:153], v[202:205], v[10:13]
	v_mfma_f32_16x16x32_bf16 v[10:13], v[154:157], v[206:209], v[10:13]
	v_mfma_f32_16x16x32_bf16 v[18:21], v[146:149], v[206:209], v[18:21]
	v_mfma_f32_16x16x32_bf16 v[18:21], v[142:145], v[202:205], v[18:21]
	s_setprio 0
	s_setprio 1
	v_mfma_f32_16x16x32_bf16 v[54:57], v[158:161], v[174:177], v[54:57]
	v_mfma_f32_16x16x32_bf16 v[54:57], v[162:165], v[178:181], v[54:57]
	v_mfma_f32_16x16x32_bf16 v[46:49], v[170:173], v[178:181], v[46:49]
	v_mfma_f32_16x16x32_bf16 v[46:49], v[166:169], v[174:177], v[46:49]
	v_mfma_f32_16x16x32_bf16 v[30:33], v[166:169], v[182:185], v[30:33]
	v_mfma_f32_16x16x32_bf16 v[30:33], v[170:173], v[186:189], v[30:33]
	v_mfma_f32_16x16x32_bf16 v[38:41], v[162:165], v[186:189], v[38:41]
	v_mfma_f32_16x16x32_bf16 v[38:41], v[158:161], v[182:185], v[38:41]
	v_mfma_f32_16x16x32_bf16 v[22:25], v[158:161], v[190:193], v[22:25]
	v_mfma_f32_16x16x32_bf16 v[22:25], v[162:165], v[198:201], v[22:25]
	v_mfma_f32_16x16x32_bf16 v[14:17], v[170:173], v[198:201], v[14:17]
	v_mfma_f32_16x16x32_bf16 v[14:17], v[166:169], v[190:193], v[14:17]
	v_mfma_f32_16x16x32_bf16 v[2:5], v[166:169], v[202:205], v[2:5]
	v_mfma_f32_16x16x32_bf16 v[2:5], v[170:173], v[206:209], v[2:5]
	v_mfma_f32_16x16x32_bf16 v[6:9], v[162:165], v[206:209], v[6:9]
	v_mfma_f32_16x16x32_bf16 v[6:9], v[158:161], v[202:205], v[6:9]
	s_setprio 0
	s_barrier
	s_cmp_gt_u32 s52, 29
	s_mov_b64 s[20:21], s[22:23]
	s_mov_b32 s24, s52
	s_cbranch_scc0 .LBB0_398
	s_and_b64 vcc, exec, s[6:7]
	s_cbranch_vccz .LBB0_401
	s_barrier

.LBB0_414:
	s_add_i32 s42, s24, 2
	s_lshr_b32 s44, s42, 2
	s_lshl_b64 s[22:23], s[44:45], 9
	s_add_u32 s22, s0, s22
	s_addc_u32 s23, s1, s23
	s_and_b32 s25, s20, 0x100
	s_add_u32 s43, s22, s25
	s_addc_u32 s47, s23, 0
	s_add_i32 s22, s24, 4
	s_lshr_b32 s44, s22, 2
	s_lshl_b64 s[22:23], s[44:45], 9
	s_add_u32 s25, s0, s22
	s_addc_u32 s44, s1, s23
	s_add_u32 s22, s20, 0x100
	s_addc_u32 s23, s21, 0
	s_and_b32 s49, s22, 0x100
	s_add_u32 s49, s25, s49
	s_addc_u32 s25, s44, 0
	s_add_u32 s20, s11, s20
	s_addc_u32 s21, s13, s21
	s_add_i32 s44, 0, 0x10000
	s_cmp_eq_u32 s24, 4
	s_cselect_b32 s25, s1, s25
	s_cselect_b32 s24, s0, s49
	v_add_u32_e32 v136, s44, v139
	s_cselect_b32 s21, s19, s21
	s_cselect_b32 s20, s18, s20
	s_add_i32 s49, 0, 0x14000
	ds_read_b128 v[142:145], v136
	ds_read_b128 v[146:149], v136 offset:1024
	ds_read_b128 v[150:153], v136 offset:2048
	ds_read_b128 v[154:157], v136 offset:3072
	v_add_u32_e32 v136, s49, v139
	ds_read_b128 v[158:161], v136
	ds_read_b128 v[162:165], v136 offset:1024
	ds_read_b128 v[166:169], v136 offset:2048
	ds_read_b128 v[170:173], v136 offset:3072
	s_add_u32 s50, s43, 0x20080
	s_addc_u32 s51, s47, 0
	v_lshl_add_u64 v[136:137], s[50:51], 0, v[134:135]
	s_add_i32 m0, s31, 0xc000
	ds_read_b128 v[174:177], v141
	ds_read_b128 v[178:181], v141 offset:1024
	ds_read_b128 v[182:185], v141 offset:2048
	ds_read_b128 v[186:189], v141 offset:3072
	ds_read_b128 v[190:193], v141 offset:4096
	ds_read_b128 v[198:201], v141 offset:5120
	ds_read_b128 v[202:205], v141 offset:6144
	ds_read_b128 v[206:209], v141 offset:7168
	global_load_lds_dwordx4 v[136:137], off
	v_lshl_add_u64 v[136:137], s[50:51], 0, v[132:133]
	s_add_i32 m0, s31, 0xe000
	s_nop 0
	global_load_lds_dwordx4 v[136:137], off
	s_waitcnt vmcnt(8)
	s_waitcnt lgkmcnt(0)
	s_barrier
	s_setprio 1
	s_waitcnt lgkmcnt(0)
	v_mfma_f32_16x16x32_bf16 v[126:129], v[142:145], v[174:177], v[126:129]
	v_mfma_f32_16x16x32_bf16 v[126:129], v[146:149], v[178:181], v[126:129]
	v_mfma_f32_16x16x32_bf16 v[122:125], v[154:157], v[178:181], v[122:125]
	v_mfma_f32_16x16x32_bf16 v[122:125], v[150:153], v[174:177], v[122:125]
	v_mfma_f32_16x16x32_bf16 v[106:109], v[150:153], v[182:185], v[106:109]
	v_mfma_f32_16x16x32_bf16 v[106:109], v[154:157], v[186:189], v[106:109]
	v_mfma_f32_16x16x32_bf16 v[114:117], v[146:149], v[186:189], v[114:117]
	v_mfma_f32_16x16x32_bf16 v[114:117], v[142:145], v[182:185], v[114:117]
	v_mfma_f32_16x16x32_bf16 v[98:101], v[142:145], v[190:193], v[98:101]
	v_mfma_f32_16x16x32_bf16 v[98:101], v[146:149], v[198:201], v[98:101]
	v_mfma_f32_16x16x32_bf16 v[90:93], v[154:157], v[198:201], v[90:93]
	v_mfma_f32_16x16x32_bf16 v[90:93], v[150:153], v[190:193], v[90:93]
	v_mfma_f32_16x16x32_bf16 v[74:77], v[150:153], v[202:205], v[74:77]
	v_mfma_f32_16x16x32_bf16 v[74:77], v[154:157], v[206:209], v[74:77]
	v_mfma_f32_16x16x32_bf16 v[82:85], v[146:149], v[206:209], v[82:85]
	v_mfma_f32_16x16x32_bf16 v[82:85], v[142:145], v[202:205], v[82:85]
	s_setprio 0
	s_setprio 1
	v_mfma_f32_16x16x32_bf16 v[118:121], v[158:161], v[174:177], v[118:121]
	v_mfma_f32_16x16x32_bf16 v[118:121], v[162:165], v[178:181], v[118:121]
	v_mfma_f32_16x16x32_bf16 v[110:113], v[170:173], v[178:181], v[110:113]
	v_mfma_f32_16x16x32_bf16 v[110:113], v[166:169], v[174:177], v[110:113]
	v_mfma_f32_16x16x32_bf16 v[94:97], v[166:169], v[182:185], v[94:97]
	v_mfma_f32_16x16x32_bf16 v[94:97], v[170:173], v[186:189], v[94:97]
	v_mfma_f32_16x16x32_bf16 v[102:105], v[162:165], v[186:189], v[102:105]
	v_mfma_f32_16x16x32_bf16 v[102:105], v[158:161], v[182:185], v[102:105]
	v_mfma_f32_16x16x32_bf16 v[86:89], v[158:161], v[190:193], v[86:89]
	v_mfma_f32_16x16x32_bf16 v[86:89], v[162:165], v[198:201], v[86:89]
	v_mfma_f32_16x16x32_bf16 v[78:81], v[170:173], v[198:201], v[78:81]
	v_mfma_f32_16x16x32_bf16 v[78:81], v[166:169], v[190:193], v[78:81]
	v_mfma_f32_16x16x32_bf16 v[66:69], v[166:169], v[202:205], v[66:69]
	v_mfma_f32_16x16x32_bf16 v[66:69], v[170:173], v[206:209], v[66:69]
	v_mfma_f32_16x16x32_bf16 v[70:73], v[162:165], v[206:209], v[70:73]
	v_mfma_f32_16x16x32_bf16 v[70:73], v[158:161], v[202:205], v[70:73]
	s_setprio 0
	s_barrier
	s_add_i32 s43, s44, s30
	v_lshl_add_u64 v[136:137], s[20:21], 0, v[196:197]
	s_mov_b32 m0, s43
	ds_read_b128 v[174:177], v141 offset:16384
	ds_read_b128 v[178:181], v141 offset:17408
	ds_read_b128 v[182:185], v141 offset:18432
	ds_read_b128 v[186:189], v141 offset:19456
	ds_read_b128 v[190:193], v141 offset:20480
	ds_read_b128 v[198:201], v141 offset:21504
	ds_read_b128 v[202:205], v141 offset:22528
	ds_read_b128 v[206:209], v141 offset:23552
	global_load_lds_dwordx4 v[136:137], off
	s_add_i32 m0, s43, 0x2000
	s_add_u32 s50, s20, 0x20000
	v_lshl_add_u64 v[194:195], s[20:21], 0, v[130:131]
	s_addc_u32 s51, s21, 0
	s_add_i32 s43, s49, s30
	global_load_lds_dwordx4 v[194:195], off
	v_lshl_add_u64 v[210:211], s[50:51], 0, v[196:197]
	s_mov_b32 m0, s43
	v_lshl_add_u64 v[212:213], s[24:25], 0, v[132:133]
	global_load_lds_dwordx4 v[210:211], off
	v_lshl_add_u64 v[210:211], s[50:51], 0, v[130:131]
	s_add_i32 m0, s43, 0x2000
	s_nop 0
	global_load_lds_dwordx4 v[210:211], off
	v_lshl_add_u64 v[210:211], s[24:25], 0, v[134:135]
	s_mov_b32 m0, s31
	s_nop 0
	global_load_lds_dwordx4 v[210:211], off
	s_mov_b32 m0, s33
	s_nop 0
	global_load_lds_dwordx4 v[212:213], off
	s_waitcnt vmcnt(8)
	s_waitcnt lgkmcnt(0)
	s_barrier
	s_setprio 1
	s_waitcnt lgkmcnt(0)
	v_mfma_f32_16x16x32_bf16 v[62:65], v[142:145], v[174:177], v[62:65]
	v_mfma_f32_16x16x32_bf16 v[62:65], v[146:149], v[178:181], v[62:65]
	v_mfma_f32_16x16x32_bf16 v[58:61], v[154:157], v[178:181], v[58:61]
	v_mfma_f32_16x16x32_bf16 v[58:61], v[150:153], v[174:177], v[58:61]
	v_mfma_f32_16x16x32_bf16 v[42:45], v[150:153], v[182:185], v[42:45]
	v_mfma_f32_16x16x32_bf16 v[42:45], v[154:157], v[186:189], v[42:45]
	v_mfma_f32_16x16x32_bf16 v[50:53], v[146:149], v[186:189], v[50:53]
	v_mfma_f32_16x16x32_bf16 v[50:53], v[142:145], v[182:185], v[50:53]
	v_mfma_f32_16x16x32_bf16 v[34:37], v[142:145], v[190:193], v[34:37]
	v_mfma_f32_16x16x32_bf16 v[34:37], v[146:149], v[198:201], v[34:37]
	v_mfma_f32_16x16x32_bf16 v[26:29], v[154:157], v[198:201], v[26:29]
	v_mfma_f32_16x16x32_bf16 v[26:29], v[150:153], v[190:193], v[26:29]
	v_mfma_f32_16x16x32_bf16 v[10:13], v[150:153], v[202:205], v[10:13]
	v_mfma_f32_16x16x32_bf16 v[10:13], v[154:157], v[206:209], v[10:13]
	v_mfma_f32_16x16x32_bf16 v[18:21], v[146:149], v[206:209], v[18:21]
	v_mfma_f32_16x16x32_bf16 v[18:21], v[142:145], v[202:205], v[18:21]
	s_setprio 0
	s_setprio 1
	v_mfma_f32_16x16x32_bf16 v[54:57], v[158:161], v[174:177], v[54:57]
	v_mfma_f32_16x16x32_bf16 v[54:57], v[162:165], v[178:181], v[54:57]
	v_mfma_f32_16x16x32_bf16 v[46:49], v[170:173], v[178:181], v[46:49]
	v_mfma_f32_16x16x32_bf16 v[46:49], v[166:169], v[174:177], v[46:49]
	v_mfma_f32_16x16x32_bf16 v[30:33], v[166:169], v[182:185], v[30:33]
	v_mfma_f32_16x16x32_bf16 v[30:33], v[170:173], v[186:189], v[30:33]
	v_mfma_f32_16x16x32_bf16 v[38:41], v[162:165], v[186:189], v[38:41]
	v_mfma_f32_16x16x32_bf16 v[38:41], v[158:161], v[182:185], v[38:41]
	v_mfma_f32_16x16x32_bf16 v[22:25], v[158:161], v[190:193], v[22:25]
	v_mfma_f32_16x16x32_bf16 v[22:25], v[162:165], v[198:201], v[22:25]
	v_mfma_f32_16x16x32_bf16 v[14:17], v[170:173], v[198:201], v[14:17]
	v_mfma_f32_16x16x32_bf16 v[14:17], v[166:169], v[190:193], v[14:17]
	v_mfma_f32_16x16x32_bf16 v[2:5], v[166:169], v[202:205], v[2:5]
	v_mfma_f32_16x16x32_bf16 v[2:5], v[170:173], v[206:209], v[2:5]
	v_mfma_f32_16x16x32_bf16 v[6:9], v[162:165], v[206:209], v[6:9]
	v_mfma_f32_16x16x32_bf16 v[6:9], v[158:161], v[202:205], v[6:9]
	s_setprio 0
	s_barrier
	s_add_i32 s43, 0, 0x18000
	s_add_i32 s44, 0, 0x1c000
	v_add_u32_e32 v154, s43, v139
	v_add_u32_e32 v170, s44, v139
	ds_read_b128 v[142:145], v154
	ds_read_b128 v[146:149], v154 offset:1024
	ds_read_b128 v[150:153], v154 offset:2048
	ds_read_b128 v[154:157], v154 offset:3072
	ds_read_b128 v[158:161], v170
	ds_read_b128 v[162:165], v170 offset:1024
	ds_read_b128 v[166:169], v170 offset:2048
	ds_read_b128 v[170:173], v170 offset:3072
	s_add_u32 s24, s24, 0x20000
	s_addc_u32 s25, s25, 0
	s_mov_b32 m0, s34
	v_lshl_add_u64 v[214:215], s[24:25], 0, v[134:135]
	ds_read_b128 v[174:177], v141 offset:32768
	ds_read_b128 v[178:181], v141 offset:33792
	ds_read_b128 v[182:185], v141 offset:34816
	ds_read_b128 v[186:189], v141 offset:35840
	ds_read_b128 v[190:193], v141 offset:36864
	ds_read_b128 v[198:201], v141 offset:37888
	ds_read_b128 v[202:205], v141 offset:38912
	ds_read_b128 v[206:209], v141 offset:39936
	global_load_lds_dwordx4 v[214:215], off
	v_lshl_add_u64 v[214:215], s[24:25], 0, v[132:133]
	s_mov_b32 m0, s35
	s_nop 0
	global_load_lds_dwordx4 v[214:215], off
	s_waitcnt vmcnt(8)
	s_waitcnt lgkmcnt(0)
	s_barrier
	s_setprio 1
	s_waitcnt lgkmcnt(0)
	v_mfma_f32_16x16x32_bf16 v[126:129], v[142:145], v[174:177], v[126:129]
	v_mfma_f32_16x16x32_bf16 v[126:129], v[146:149], v[178:181], v[126:129]
	v_mfma_f32_16x16x32_bf16 v[122:125], v[154:157], v[178:181], v[122:125]
	v_mfma_f32_16x16x32_bf16 v[122:125], v[150:153], v[174:177], v[122:125]
	v_mfma_f32_16x16x32_bf16 v[106:109], v[150:153], v[182:185], v[106:109]
	v_mfma_f32_16x16x32_bf16 v[106:109], v[154:157], v[186:189], v[106:109]
	v_mfma_f32_16x16x32_bf16 v[114:117], v[146:149], v[186:189], v[114:117]
	v_mfma_f32_16x16x32_bf16 v[114:117], v[142:145], v[182:185], v[114:117]
	v_mfma_f32_16x16x32_bf16 v[98:101], v[142:145], v[190:193], v[98:101]
	v_mfma_f32_16x16x32_bf16 v[98:101], v[146:149], v[198:201], v[98:101]
	v_mfma_f32_16x16x32_bf16 v[90:93], v[154:157], v[198:201], v[90:93]
	v_mfma_f32_16x16x32_bf16 v[90:93], v[150:153], v[190:193], v[90:93]
	v_mfma_f32_16x16x32_bf16 v[74:77], v[150:153], v[202:205], v[74:77]
	v_mfma_f32_16x16x32_bf16 v[74:77], v[154:157], v[206:209], v[74:77]
	v_mfma_f32_16x16x32_bf16 v[82:85], v[146:149], v[206:209], v[82:85]
	v_mfma_f32_16x16x32_bf16 v[82:85], v[142:145], v[202:205], v[82:85]
	s_setprio 0
	s_setprio 1
	v_mfma_f32_16x16x32_bf16 v[118:121], v[158:161], v[174:177], v[118:121]
	v_mfma_f32_16x16x32_bf16 v[118:121], v[162:165], v[178:181], v[118:121]
	v_mfma_f32_16x16x32_bf16 v[110:113], v[170:173], v[178:181], v[110:113]
	v_mfma_f32_16x16x32_bf16 v[110:113], v[166:169], v[174:177], v[110:113]
	v_mfma_f32_16x16x32_bf16 v[94:97], v[166:169], v[182:185], v[94:97]
	v_mfma_f32_16x16x32_bf16 v[94:97], v[170:173], v[186:189], v[94:97]
	v_mfma_f32_16x16x32_bf16 v[102:105], v[162:165], v[186:189], v[102:105]
	v_mfma_f32_16x16x32_bf16 v[102:105], v[158:161], v[182:185], v[102:105]
	v_mfma_f32_16x16x32_bf16 v[86:89], v[158:161], v[190:193], v[86:89]
	v_mfma_f32_16x16x32_bf16 v[86:89], v[162:165], v[198:201], v[86:89]
	v_mfma_f32_16x16x32_bf16 v[78:81], v[170:173], v[198:201], v[78:81]
	v_mfma_f32_16x16x32_bf16 v[78:81], v[166:169], v[190:193], v[78:81]
	v_mfma_f32_16x16x32_bf16 v[66:69], v[166:169], v[202:205], v[66:69]
	v_mfma_f32_16x16x32_bf16 v[66:69], v[170:173], v[206:209], v[66:69]
	v_mfma_f32_16x16x32_bf16 v[70:73], v[162:165], v[206:209], v[70:73]
	v_mfma_f32_16x16x32_bf16 v[70:73], v[158:161], v[202:205], v[70:73]
	s_setprio 0
	s_barrier
	s_add_i32 s24, s43, s30
	v_lshl_add_u64 v[136:137], v[136:137], 0, s[2:3]
	s_mov_b32 m0, s24
	ds_read_b128 v[174:177], v141 offset:49152
	ds_read_b128 v[178:181], v141 offset:50176
	ds_read_b128 v[182:185], v141 offset:51200
	ds_read_b128 v[186:189], v141 offset:52224
	ds_read_b128 v[190:193], v141 offset:53248
	ds_read_b128 v[198:201], v141 offset:54272
	ds_read_b128 v[202:205], v141 offset:55296
	ds_read_b128 v[206:209], v141 offset:56320
	global_load_lds_dwordx4 v[136:137], off
	s_add_i32 m0, s24, 0x2000
	s_add_u32 s20, s20, 0x20080
	v_lshl_add_u64 v[136:137], v[194:195], 0, s[2:3]
	s_addc_u32 s21, s21, 0
	s_add_i32 s24, s44, s30
	global_load_lds_dwordx4 v[136:137], off
	v_lshl_add_u64 v[136:137], s[20:21], 0, v[196:197]
	s_mov_b32 m0, s24
	s_nop 0
	global_load_lds_dwordx4 v[136:137], off
	v_lshl_add_u64 v[136:137], s[20:21], 0, v[130:131]
	s_add_i32 m0, s24, 0x2000
	s_nop 0
	global_load_lds_dwordx4 v[136:137], off
	v_lshl_add_u64 v[136:137], v[210:211], 0, s[2:3]
	s_mov_b32 m0, s36
	s_nop 0
	global_load_lds_dwordx4 v[136:137], off
	v_lshl_add_u64 v[136:137], v[212:213], 0, s[2:3]
	s_mov_b32 m0, s37
	s_nop 0
	global_load_lds_dwordx4 v[136:137], off
	s_waitcnt vmcnt(8)
	s_waitcnt lgkmcnt(0)
	s_barrier
	s_setprio 1
	s_waitcnt lgkmcnt(0)
	v_mfma_f32_16x16x32_bf16 v[62:65], v[142:145], v[174:177], v[62:65]
	v_mfma_f32_16x16x32_bf16 v[62:65], v[146:149], v[178:181], v[62:65]
	v_mfma_f32_16x16x32_bf16 v[58:61], v[154:157], v[178:181], v[58:61]
	v_mfma_f32_16x16x32_bf16 v[58:61], v[150:153], v[174:177], v[58:61]
	v_mfma_f32_16x16x32_bf16 v[42:45], v[150:153], v[182:185], v[42:45]
	v_mfma_f32_16x16x32_bf16 v[42:45], v[154:157], v[186:189], v[42:45]
	v_mfma_f32_16x16x32_bf16 v[50:53], v[146:149], v[186:189], v[50:53]
	v_mfma_f32_16x16x32_bf16 v[50:53], v[142:145], v[182:185], v[50:53]
	v_mfma_f32_16x16x32_bf16 v[34:37], v[142:145], v[190:193], v[34:37]
	v_mfma_f32_16x16x32_bf16 v[34:37], v[146:149], v[198:201], v[34:37]
	v_mfma_f32_16x16x32_bf16 v[26:29], v[154:157], v[198:201], v[26:29]
	v_mfma_f32_16x16x32_bf16 v[26:29], v[150:153], v[190:193], v[26:29]
	v_mfma_f32_16x16x32_bf16 v[10:13], v[150:153], v[202:205], v[10:13]
	v_mfma_f32_16x16x32_bf16 v[10:13], v[154:157], v[206:209], v[10:13]
	v_mfma_f32_16x16x32_bf16 v[18:21], v[146:149], v[206:209], v[18:21]
	v_mfma_f32_16x16x32_bf16 v[18:21], v[142:145], v[202:205], v[18:21]
	s_setprio 0
	s_setprio 1
	v_mfma_f32_16x16x32_bf16 v[54:57], v[158:161], v[174:177], v[54:57]
	v_mfma_f32_16x16x32_bf16 v[54:57], v[162:165], v[178:181], v[54:57]
	v_mfma_f32_16x16x32_bf16 v[46:49], v[170:173], v[178:181], v[46:49]
	v_mfma_f32_16x16x32_bf16 v[46:49], v[166:169], v[174:177], v[46:49]
	v_mfma_f32_16x16x32_bf16 v[30:33], v[166:169], v[182:185], v[30:33]
	v_mfma_f32_16x16x32_bf16 v[30:33], v[170:173], v[186:189], v[30:33]
	v_mfma_f32_16x16x32_bf16 v[38:41], v[162:165], v[186:189], v[38:41]
	v_mfma_f32_16x16x32_bf16 v[38:41], v[158:161], v[182:185], v[38:41]
	v_mfma_f32_16x16x32_bf16 v[22:25], v[158:161], v[190:193], v[22:25]
	v_mfma_f32_16x16x32_bf16 v[22:25], v[162:165], v[198:201], v[22:25]
	v_mfma_f32_16x16x32_bf16 v[14:17], v[170:173], v[198:201], v[14:17]
	v_mfma_f32_16x16x32_bf16 v[14:17], v[166:169], v[190:193], v[14:17]
	v_mfma_f32_16x16x32_bf16 v[2:5], v[166:169], v[202:205], v[2:5]
	v_mfma_f32_16x16x32_bf16 v[2:5], v[170:173], v[206:209], v[2:5]
	v_mfma_f32_16x16x32_bf16 v[6:9], v[162:165], v[206:209], v[6:9]
	v_mfma_f32_16x16x32_bf16 v[6:9], v[158:161], v[202:205], v[6:9]
	s_setprio 0
	s_barrier
	s_cmp_gt_u32 s42, 5
	s_mov_b64 s[20:21], s[22:23]
	s_mov_b32 s24, s42
	s_cbranch_scc0 .LBB0_414
	s_and_b64 vcc, exec, s[8:9]
	s_cbranch_vccz .LBB0_417
	s_barrier

.LBB0_630:
	s_cmp_lt_i32 s5, 1
	s_cbranch_scc1 .LBB0_670
	s_add_u32 s7, s30, 0x100
	s_addc_u32 s47, s31, 0
	s_mov_b32 s49, 2
	s_mov_b64 s[30:31], 0
	s_add_i32 s34, s49, -2
	s_lshr_b32 s44, s34, 2
	s_lshl_b64 s[36:37], s[44:45], 9
	s_lshr_b32 s44, s49, 2
	s_and_b32 s64, s30, 0x100
	s_lshl_b64 s[34:35], s[44:45], 9
	s_add_u32 s44, s28, s34
	s_addc_u32 s65, s29, s35
	s_add_u32 s34, s30, 0x100
	s_addc_u32 s35, s31, 0
	s_and_b32 s66, s34, 0x100
	s_add_u32 s44, s44, s66
	s_addc_u32 s65, s65, 0
	s_add_u32 s30, s7, s30
	s_addc_u32 s31, s47, s31
	s_add_i32 s66, 0, 0x10000
	s_add_u32 s67, s28, s36
	s_addc_u32 s68, s29, s37
	s_cmp_eq_u32 s5, s49
	s_cselect_b32 s37, s25, s65
	s_cselect_b32 s36, s24, s44
	s_cselect_b32 s31, s27, s31
	s_cselect_b32 s30, s26, s30
	s_add_i32 s44, 0, 0x14000
	v_add_u32_e32 v142, s66, v227
	v_add_u32_e32 v158, s44, v227
	ds_read_b128 v[130:133], v142
	ds_read_b128 v[134:137], v142 offset:1024
	ds_read_b128 v[138:141], v142 offset:2048
	ds_read_b128 v[142:145], v142 offset:3072
	ds_read_b128 v[146:149], v158
	ds_read_b128 v[150:153], v158 offset:1024
	ds_read_b128 v[154:157], v158 offset:2048
	ds_read_b128 v[158:161], v158 offset:3072
	s_add_u32 s64, s67, s64
	s_addc_u32 s65, s68, 0
	s_add_u32 s64, s64, 0x80080
	s_addc_u32 s65, s65, 0
	v_lshl_add_u64 v[194:195], s[64:65], 0, v[198:199]
	s_add_i32 m0, s40, 0xc000
	ds_read_b128 v[162:165], v229
	ds_read_b128 v[166:169], v229 offset:1024
	ds_read_b128 v[170:173], v229 offset:2048
	ds_read_b128 v[174:177], v229 offset:3072
	ds_read_b128 v[178:181], v229 offset:4096
	ds_read_b128 v[182:185], v229 offset:5120
	ds_read_b128 v[186:189], v229 offset:6144
	ds_read_b128 v[190:193], v229 offset:7168
	global_load_lds_dwordx4 v[194:195], off
	v_lshl_add_u64 v[194:195], s[64:65], 0, v[202:203]
	s_add_i32 m0, s40, 0xe000
	s_nop 0
	global_load_lds_dwordx4 v[194:195], off
	s_waitcnt vmcnt(8)
	s_waitcnt lgkmcnt(0)
	s_barrier
	s_setprio 1
	s_waitcnt lgkmcnt(0)
	v_mfma_f32_16x16x32_bf16 v[126:129], v[130:133], v[162:165], 0
	v_mfma_f32_16x16x32_bf16 v[126:129], v[134:137], v[166:169], v[126:129]
	v_mfma_f32_16x16x32_bf16 v[122:125], v[142:145], v[166:169], 0
	v_mfma_f32_16x16x32_bf16 v[122:125], v[138:141], v[162:165], v[122:125]
	v_mfma_f32_16x16x32_bf16 v[106:109], v[138:141], v[170:173], 0
	v_mfma_f32_16x16x32_bf16 v[106:109], v[142:145], v[174:177], v[106:109]
	v_mfma_f32_16x16x32_bf16 v[110:113], v[134:137], v[174:177], 0
	v_mfma_f32_16x16x32_bf16 v[110:113], v[130:133], v[170:173], v[110:113]
	v_mfma_f32_16x16x32_bf16 v[94:97], v[130:133], v[178:181], 0
	v_mfma_f32_16x16x32_bf16 v[94:97], v[134:137], v[182:185], v[94:97]
	v_mfma_f32_16x16x32_bf16 v[90:93], v[142:145], v[182:185], 0
	v_mfma_f32_16x16x32_bf16 v[90:93], v[138:141], v[178:181], v[90:93]
	v_mfma_f32_16x16x32_bf16 v[74:77], v[138:141], v[186:189], 0
	v_mfma_f32_16x16x32_bf16 v[74:77], v[142:145], v[190:193], v[74:77]
	v_mfma_f32_16x16x32_bf16 v[78:81], v[134:137], v[190:193], 0
	v_mfma_f32_16x16x32_bf16 v[78:81], v[130:133], v[186:189], v[78:81]
	s_setprio 0
	s_setprio 1
	v_mfma_f32_16x16x32_bf16 v[118:121], v[146:149], v[162:165], 0
	v_mfma_f32_16x16x32_bf16 v[118:121], v[150:153], v[166:169], v[118:121]
	v_mfma_f32_16x16x32_bf16 v[114:117], v[158:161], v[166:169], 0
	v_mfma_f32_16x16x32_bf16 v[114:117], v[154:157], v[162:165], v[114:117]
	v_mfma_f32_16x16x32_bf16 v[98:101], v[154:157], v[170:173], 0
	v_mfma_f32_16x16x32_bf16 v[98:101], v[158:161], v[174:177], v[98:101]
	v_mfma_f32_16x16x32_bf16 v[102:105], v[150:153], v[174:177], 0
	v_mfma_f32_16x16x32_bf16 v[102:105], v[146:149], v[170:173], v[102:105]
	v_mfma_f32_16x16x32_bf16 v[86:89], v[146:149], v[178:181], 0
	v_mfma_f32_16x16x32_bf16 v[86:89], v[150:153], v[182:185], v[86:89]
	v_mfma_f32_16x16x32_bf16 v[82:85], v[158:161], v[182:185], 0
	v_mfma_f32_16x16x32_bf16 v[82:85], v[154:157], v[178:181], v[82:85]
	v_mfma_f32_16x16x32_bf16 v[66:69], v[154:157], v[186:189], 0
	v_mfma_f32_16x16x32_bf16 v[66:69], v[158:161], v[190:193], v[66:69]
	v_mfma_f32_16x16x32_bf16 v[70:73], v[150:153], v[190:193], 0
	v_mfma_f32_16x16x32_bf16 v[70:73], v[146:149], v[186:189], v[70:73]
	s_setprio 0
	s_barrier
	s_add_i32 s64, s66, s39
	v_lshl_add_u64 v[194:195], s[30:31], 0, v[200:201]
	s_mov_b32 m0, s64
	ds_read_b128 v[162:165], v229 offset:16384
	ds_read_b128 v[166:169], v229 offset:17408
	ds_read_b128 v[170:173], v229 offset:18432
	ds_read_b128 v[174:177], v229 offset:19456
	ds_read_b128 v[178:181], v229 offset:20480
	ds_read_b128 v[182:185], v229 offset:21504
	ds_read_b128 v[186:189], v229 offset:22528
	ds_read_b128 v[190:193], v229 offset:23552
	global_load_lds_dwordx4 v[194:195], off
	s_add_i32 m0, s64, 0x2000
	s_add_u32 s64, s30, 0x80000
	v_lshl_add_u64 v[206:207], s[30:31], 0, v[204:205]
	s_addc_u32 s65, s31, 0
	s_add_i32 s44, s44, s39
	global_load_lds_dwordx4 v[206:207], off
	v_lshl_add_u64 v[208:209], s[64:65], 0, v[200:201]
	s_mov_b32 m0, s44
	v_lshl_add_u64 v[210:211], s[36:37], 0, v[202:203]
	global_load_lds_dwordx4 v[208:209], off
	v_lshl_add_u64 v[208:209], s[64:65], 0, v[204:205]
	s_add_i32 m0, s44, 0x2000
	s_nop 0
	global_load_lds_dwordx4 v[208:209], off
	v_lshl_add_u64 v[208:209], s[36:37], 0, v[198:199]
	s_mov_b32 m0, s40
	s_nop 0
	global_load_lds_dwordx4 v[208:209], off
	s_mov_b32 m0, s41
	s_nop 0
	global_load_lds_dwordx4 v[210:211], off
	s_waitcnt vmcnt(8)
	s_waitcnt lgkmcnt(0)
	s_barrier
	s_setprio 1
	s_waitcnt lgkmcnt(0)
	v_mfma_f32_16x16x32_bf16 v[62:65], v[130:133], v[162:165], 0
	v_mfma_f32_16x16x32_bf16 v[62:65], v[134:137], v[166:169], v[62:65]
	v_mfma_f32_16x16x32_bf16 v[58:61], v[142:145], v[166:169], 0
	v_mfma_f32_16x16x32_bf16 v[58:61], v[138:141], v[162:165], v[58:61]
	v_mfma_f32_16x16x32_bf16 v[42:45], v[138:141], v[170:173], 0
	v_mfma_f32_16x16x32_bf16 v[42:45], v[142:145], v[174:177], v[42:45]
	v_mfma_f32_16x16x32_bf16 v[46:49], v[134:137], v[174:177], 0
	v_mfma_f32_16x16x32_bf16 v[46:49], v[130:133], v[170:173], v[46:49]
	v_mfma_f32_16x16x32_bf16 v[30:33], v[130:133], v[178:181], 0
	v_mfma_f32_16x16x32_bf16 v[30:33], v[134:137], v[182:185], v[30:33]
	v_mfma_f32_16x16x32_bf16 v[26:29], v[142:145], v[182:185], 0
	v_mfma_f32_16x16x32_bf16 v[26:29], v[138:141], v[178:181], v[26:29]
	v_mfma_f32_16x16x32_bf16 v[10:13], v[138:141], v[186:189], 0
	v_mfma_f32_16x16x32_bf16 v[10:13], v[142:145], v[190:193], v[10:13]
	v_mfma_f32_16x16x32_bf16 v[14:17], v[134:137], v[190:193], 0
	v_mfma_f32_16x16x32_bf16 v[14:17], v[130:133], v[186:189], v[14:17]
	s_setprio 0
	s_setprio 1
	v_mfma_f32_16x16x32_bf16 v[54:57], v[146:149], v[162:165], 0
	v_mfma_f32_16x16x32_bf16 v[54:57], v[150:153], v[166:169], v[54:57]
	v_mfma_f32_16x16x32_bf16 v[50:53], v[158:161], v[166:169], 0
	v_mfma_f32_16x16x32_bf16 v[50:53], v[154:157], v[162:165], v[50:53]
	v_mfma_f32_16x16x32_bf16 v[34:37], v[154:157], v[170:173], 0
	v_mfma_f32_16x16x32_bf16 v[34:37], v[158:161], v[174:177], v[34:37]
	v_mfma_f32_16x16x32_bf16 v[38:41], v[150:153], v[174:177], 0
	v_mfma_f32_16x16x32_bf16 v[38:41], v[146:149], v[170:173], v[38:41]
	v_mfma_f32_16x16x32_bf16 v[22:25], v[146:149], v[178:181], 0
	v_mfma_f32_16x16x32_bf16 v[22:25], v[150:153], v[182:185], v[22:25]
	v_mfma_f32_16x16x32_bf16 v[18:21], v[158:161], v[182:185], 0
	v_mfma_f32_16x16x32_bf16 v[18:21], v[154:157], v[178:181], v[18:21]
	v_mfma_f32_16x16x32_bf16 v[2:5], v[154:157], v[186:189], 0
	v_mfma_f32_16x16x32_bf16 v[2:5], v[158:161], v[190:193], v[2:5]
	v_mfma_f32_16x16x32_bf16 v[6:9], v[150:153], v[190:193], 0
	v_mfma_f32_16x16x32_bf16 v[6:9], v[146:149], v[186:189], v[6:9]
	s_setprio 0
	s_barrier
	s_add_i32 s44, 0, 0x18000
	s_add_i32 s64, 0, 0x1c000
	v_add_u32_e32 v142, s44, v227
	v_add_u32_e32 v158, s64, v227
	ds_read_b128 v[130:133], v142
	ds_read_b128 v[134:137], v142 offset:1024
	ds_read_b128 v[138:141], v142 offset:2048
	ds_read_b128 v[142:145], v142 offset:3072
	ds_read_b128 v[146:149], v158
	ds_read_b128 v[150:153], v158 offset:1024
	ds_read_b128 v[154:157], v158 offset:2048
	ds_read_b128 v[158:161], v158 offset:3072
	s_add_u32 s36, s36, 0x80000
	s_addc_u32 s37, s37, 0
	s_mov_b32 m0, s42
	v_lshl_add_u64 v[212:213], s[36:37], 0, v[198:199]
	ds_read_b128 v[162:165], v229 offset:32768
	ds_read_b128 v[166:169], v229 offset:33792
	ds_read_b128 v[170:173], v229 offset:34816
	ds_read_b128 v[174:177], v229 offset:35840
	ds_read_b128 v[178:181], v229 offset:36864
	ds_read_b128 v[182:185], v229 offset:37888
	ds_read_b128 v[186:189], v229 offset:38912
	ds_read_b128 v[190:193], v229 offset:39936
	global_load_lds_dwordx4 v[212:213], off
	v_lshl_add_u64 v[212:213], s[36:37], 0, v[202:203]
	s_mov_b32 m0, s43
	s_nop 0
	global_load_lds_dwordx4 v[212:213], off
	s_waitcnt vmcnt(8)
	s_waitcnt lgkmcnt(0)
	s_barrier
	s_setprio 1
	s_waitcnt lgkmcnt(0)
	v_mfma_f32_16x16x32_bf16 v[126:129], v[130:133], v[162:165], v[126:129]
	v_mfma_f32_16x16x32_bf16 v[126:129], v[134:137], v[166:169], v[126:129]
	v_mfma_f32_16x16x32_bf16 v[122:125], v[142:145], v[166:169], v[122:125]
	v_mfma_f32_16x16x32_bf16 v[122:125], v[138:141], v[162:165], v[122:125]
	v_mfma_f32_16x16x32_bf16 v[106:109], v[138:141], v[170:173], v[106:109]
	v_mfma_f32_16x16x32_bf16 v[106:109], v[142:145], v[174:177], v[106:109]
	v_mfma_f32_16x16x32_bf16 v[110:113], v[134:137], v[174:177], v[110:113]
	v_mfma_f32_16x16x32_bf16 v[110:113], v[130:133], v[170:173], v[110:113]
	v_mfma_f32_16x16x32_bf16 v[94:97], v[130:133], v[178:181], v[94:97]
	v_mfma_f32_16x16x32_bf16 v[94:97], v[134:137], v[182:185], v[94:97]
	v_mfma_f32_16x16x32_bf16 v[90:93], v[142:145], v[182:185], v[90:93]
	v_mfma_f32_16x16x32_bf16 v[90:93], v[138:141], v[178:181], v[90:93]
	v_mfma_f32_16x16x32_bf16 v[74:77], v[138:141], v[186:189], v[74:77]
	v_mfma_f32_16x16x32_bf16 v[74:77], v[142:145], v[190:193], v[74:77]
	v_mfma_f32_16x16x32_bf16 v[78:81], v[134:137], v[190:193], v[78:81]
	v_mfma_f32_16x16x32_bf16 v[78:81], v[130:133], v[186:189], v[78:81]
	s_setprio 0
	s_setprio 1
	v_mfma_f32_16x16x32_bf16 v[118:121], v[146:149], v[162:165], v[118:121]
	v_mfma_f32_16x16x32_bf16 v[118:121], v[150:153], v[166:169], v[118:121]
	v_mfma_f32_16x16x32_bf16 v[114:117], v[158:161], v[166:169], v[114:117]
	v_mfma_f32_16x16x32_bf16 v[114:117], v[154:157], v[162:165], v[114:117]
	v_mfma_f32_16x16x32_bf16 v[98:101], v[154:157], v[170:173], v[98:101]
	v_mfma_f32_16x16x32_bf16 v[98:101], v[158:161], v[174:177], v[98:101]
	v_mfma_f32_16x16x32_bf16 v[102:105], v[150:153], v[174:177], v[102:105]
	v_mfma_f32_16x16x32_bf16 v[102:105], v[146:149], v[170:173], v[102:105]
	v_mfma_f32_16x16x32_bf16 v[86:89], v[146:149], v[178:181], v[86:89]
	v_mfma_f32_16x16x32_bf16 v[86:89], v[150:153], v[182:185], v[86:89]
	v_mfma_f32_16x16x32_bf16 v[82:85], v[158:161], v[182:185], v[82:85]
	v_mfma_f32_16x16x32_bf16 v[82:85], v[154:157], v[178:181], v[82:85]
	v_mfma_f32_16x16x32_bf16 v[66:69], v[154:157], v[186:189], v[66:69]
	v_mfma_f32_16x16x32_bf16 v[66:69], v[158:161], v[190:193], v[66:69]
	v_mfma_f32_16x16x32_bf16 v[70:73], v[150:153], v[190:193], v[70:73]
	v_mfma_f32_16x16x32_bf16 v[70:73], v[146:149], v[186:189], v[70:73]
	s_setprio 0
	s_barrier
	s_add_i32 s36, s44, s39
	v_lshl_add_u64 v[194:195], v[194:195], 0, s[2:3]
	s_mov_b32 m0, s36
	ds_read_b128 v[162:165], v229 offset:49152
	ds_read_b128 v[166:169], v229 offset:50176
	ds_read_b128 v[170:173], v229 offset:51200
	ds_read_b128 v[174:177], v229 offset:52224
	ds_read_b128 v[178:181], v229 offset:53248
	ds_read_b128 v[182:185], v229 offset:54272
	ds_read_b128 v[186:189], v229 offset:55296
	ds_read_b128 v[190:193], v229 offset:56320
	global_load_lds_dwordx4 v[194:195], off
	s_add_i32 m0, s36, 0x2000
	s_add_u32 s30, s30, 0x80080
	v_lshl_add_u64 v[194:195], v[206:207], 0, s[2:3]
	s_addc_u32 s31, s31, 0
	s_add_i32 s36, s64, s39
	global_load_lds_dwordx4 v[194:195], off
	v_lshl_add_u64 v[194:195], s[30:31], 0, v[200:201]
	s_mov_b32 m0, s36
	s_nop 0
	global_load_lds_dwordx4 v[194:195], off
	v_lshl_add_u64 v[194:195], s[30:31], 0, v[204:205]
	s_add_i32 m0, s36, 0x2000
	s_nop 0
	global_load_lds_dwordx4 v[194:195], off
	v_lshl_add_u64 v[194:195], v[208:209], 0, s[2:3]
	s_mov_b32 m0, s50
	s_nop 0
	global_load_lds_dwordx4 v[194:195], off
	v_lshl_add_u64 v[194:195], v[210:211], 0, s[2:3]
	s_mov_b32 m0, s51
	s_nop 0
	global_load_lds_dwordx4 v[194:195], off
	s_waitcnt vmcnt(8)
	s_waitcnt lgkmcnt(0)
	s_barrier
	s_setprio 1
	s_waitcnt lgkmcnt(0)
	v_mfma_f32_16x16x32_bf16 v[62:65], v[130:133], v[162:165], v[62:65]
	v_mfma_f32_16x16x32_bf16 v[62:65], v[134:137], v[166:169], v[62:65]
	v_mfma_f32_16x16x32_bf16 v[58:61], v[142:145], v[166:169], v[58:61]
	v_mfma_f32_16x16x32_bf16 v[58:61], v[138:141], v[162:165], v[58:61]
	v_mfma_f32_16x16x32_bf16 v[42:45], v[138:141], v[170:173], v[42:45]
	v_mfma_f32_16x16x32_bf16 v[42:45], v[142:145], v[174:177], v[42:45]
	v_mfma_f32_16x16x32_bf16 v[46:49], v[134:137], v[174:177], v[46:49]
	v_mfma_f32_16x16x32_bf16 v[46:49], v[130:133], v[170:173], v[46:49]
	v_mfma_f32_16x16x32_bf16 v[30:33], v[130:133], v[178:181], v[30:33]
	v_mfma_f32_16x16x32_bf16 v[30:33], v[134:137], v[182:185], v[30:33]
	v_mfma_f32_16x16x32_bf16 v[26:29], v[142:145], v[182:185], v[26:29]
	v_mfma_f32_16x16x32_bf16 v[26:29], v[138:141], v[178:181], v[26:29]
	v_mfma_f32_16x16x32_bf16 v[10:13], v[138:141], v[186:189], v[10:13]
	v_mfma_f32_16x16x32_bf16 v[10:13], v[142:145], v[190:193], v[10:13]
	v_mfma_f32_16x16x32_bf16 v[14:17], v[134:137], v[190:193], v[14:17]
	v_mfma_f32_16x16x32_bf16 v[14:17], v[130:133], v[186:189], v[14:17]
	s_setprio 0
	s_setprio 1
	v_mfma_f32_16x16x32_bf16 v[54:57], v[146:149], v[162:165], v[54:57]
	v_mfma_f32_16x16x32_bf16 v[54:57], v[150:153], v[166:169], v[54:57]
	v_mfma_f32_16x16x32_bf16 v[50:53], v[158:161], v[166:169], v[50:53]
	v_mfma_f32_16x16x32_bf16 v[50:53], v[154:157], v[162:165], v[50:53]
	v_mfma_f32_16x16x32_bf16 v[34:37], v[154:157], v[170:173], v[34:37]
	v_mfma_f32_16x16x32_bf16 v[34:37], v[158:161], v[174:177], v[34:37]
	v_mfma_f32_16x16x32_bf16 v[38:41], v[150:153], v[174:177], v[38:41]
	v_mfma_f32_16x16x32_bf16 v[38:41], v[146:149], v[170:173], v[38:41]
	v_mfma_f32_16x16x32_bf16 v[22:25], v[146:149], v[178:181], v[22:25]
	v_mfma_f32_16x16x32_bf16 v[22:25], v[150:153], v[182:185], v[22:25]
	v_mfma_f32_16x16x32_bf16 v[18:21], v[158:161], v[182:185], v[18:21]
	v_mfma_f32_16x16x32_bf16 v[18:21], v[154:157], v[178:181], v[18:21]
	v_mfma_f32_16x16x32_bf16 v[2:5], v[154:157], v[186:189], v[2:5]
	v_mfma_f32_16x16x32_bf16 v[2:5], v[158:161], v[190:193], v[2:5]
	v_mfma_f32_16x16x32_bf16 v[6:9], v[150:153], v[190:193], v[6:9]
	v_mfma_f32_16x16x32_bf16 v[6:9], v[146:149], v[186:189], v[6:9]
	s_setprio 0
	s_barrier
	s_add_i32 s36, s49, 2
	s_cmp_ge_i32 s49, s5
	s_mov_b64 s[30:31], s[34:35]
	s_mov_b32 s49, s36
	s_cbranch_scc1 .Lpeel_exit_branch
.LBB0_632:
	s_add_i32 s34, s49, -2
	s_lshr_b32 s44, s34, 2
	s_lshl_b64 s[36:37], s[44:45], 9
	s_lshr_b32 s44, s49, 2
	s_and_b32 s64, s30, 0x100
	s_lshl_b64 s[34:35], s[44:45], 9
	s_add_u32 s44, s28, s34
	s_addc_u32 s65, s29, s35
	s_add_u32 s34, s30, 0x100
	s_addc_u32 s35, s31, 0
	s_and_b32 s66, s34, 0x100
	s_add_u32 s44, s44, s66
	s_addc_u32 s65, s65, 0
	s_add_u32 s30, s7, s30
	s_addc_u32 s31, s47, s31
	s_add_i32 s66, 0, 0x10000
	s_add_u32 s67, s28, s36
	s_addc_u32 s68, s29, s37
	s_cmp_eq_u32 s5, s49
	s_cselect_b32 s37, s25, s65
	s_cselect_b32 s36, s24, s44
	s_cselect_b32 s31, s27, s31
	s_cselect_b32 s30, s26, s30
	s_add_i32 s44, 0, 0x14000
	v_add_u32_e32 v142, s66, v227
	v_add_u32_e32 v158, s44, v227
	ds_read_b128 v[130:133], v142
	ds_read_b128 v[134:137], v142 offset:1024
	ds_read_b128 v[138:141], v142 offset:2048
	ds_read_b128 v[142:145], v142 offset:3072
	ds_read_b128 v[146:149], v158
	ds_read_b128 v[150:153], v158 offset:1024
	ds_read_b128 v[154:157], v158 offset:2048
	ds_read_b128 v[158:161], v158 offset:3072
	s_add_u32 s64, s67, s64
	s_addc_u32 s65, s68, 0
	s_add_u32 s64, s64, 0x80080
	s_addc_u32 s65, s65, 0
	v_lshl_add_u64 v[194:195], s[64:65], 0, v[198:199]
	s_add_i32 m0, s40, 0xc000
	ds_read_b128 v[162:165], v229
	ds_read_b128 v[166:169], v229 offset:1024
	ds_read_b128 v[170:173], v229 offset:2048
	ds_read_b128 v[174:177], v229 offset:3072
	ds_read_b128 v[178:181], v229 offset:4096
	ds_read_b128 v[182:185], v229 offset:5120
	ds_read_b128 v[186:189], v229 offset:6144
	ds_read_b128 v[190:193], v229 offset:7168
	global_load_lds_dwordx4 v[194:195], off
	v_lshl_add_u64 v[194:195], s[64:65], 0, v[202:203]
	s_add_i32 m0, s40, 0xe000
	s_nop 0
	global_load_lds_dwordx4 v[194:195], off
	s_waitcnt vmcnt(8)
	s_waitcnt lgkmcnt(0)
	s_barrier
	s_setprio 1
	s_waitcnt lgkmcnt(0)
	v_mfma_f32_16x16x32_bf16 v[126:129], v[130:133], v[162:165], v[126:129]
	v_mfma_f32_16x16x32_bf16 v[126:129], v[134:137], v[166:169], v[126:129]
	v_mfma_f32_16x16x32_bf16 v[122:125], v[142:145], v[166:169], v[122:125]
	v_mfma_f32_16x16x32_bf16 v[122:125], v[138:141], v[162:165], v[122:125]
	v_mfma_f32_16x16x32_bf16 v[106:109], v[138:141], v[170:173], v[106:109]
	v_mfma_f32_16x16x32_bf16 v[106:109], v[142:145], v[174:177], v[106:109]
	v_mfma_f32_16x16x32_bf16 v[110:113], v[134:137], v[174:177], v[110:113]
	v_mfma_f32_16x16x32_bf16 v[110:113], v[130:133], v[170:173], v[110:113]
	v_mfma_f32_16x16x32_bf16 v[94:97], v[130:133], v[178:181], v[94:97]
	v_mfma_f32_16x16x32_bf16 v[94:97], v[134:137], v[182:185], v[94:97]
	v_mfma_f32_16x16x32_bf16 v[90:93], v[142:145], v[182:185], v[90:93]
	v_mfma_f32_16x16x32_bf16 v[90:93], v[138:141], v[178:181], v[90:93]
	v_mfma_f32_16x16x32_bf16 v[74:77], v[138:141], v[186:189], v[74:77]
	v_mfma_f32_16x16x32_bf16 v[74:77], v[142:145], v[190:193], v[74:77]
	v_mfma_f32_16x16x32_bf16 v[78:81], v[134:137], v[190:193], v[78:81]
	v_mfma_f32_16x16x32_bf16 v[78:81], v[130:133], v[186:189], v[78:81]
	s_setprio 0
	s_setprio 1
	v_mfma_f32_16x16x32_bf16 v[118:121], v[146:149], v[162:165], v[118:121]
	v_mfma_f32_16x16x32_bf16 v[118:121], v[150:153], v[166:169], v[118:121]
	v_mfma_f32_16x16x32_bf16 v[114:117], v[158:161], v[166:169], v[114:117]
	v_mfma_f32_16x16x32_bf16 v[114:117], v[154:157], v[162:165], v[114:117]
	v_mfma_f32_16x16x32_bf16 v[98:101], v[154:157], v[170:173], v[98:101]
	v_mfma_f32_16x16x32_bf16 v[98:101], v[158:161], v[174:177], v[98:101]
	v_mfma_f32_16x16x32_bf16 v[102:105], v[150:153], v[174:177], v[102:105]
	v_mfma_f32_16x16x32_bf16 v[102:105], v[146:149], v[170:173], v[102:105]
	v_mfma_f32_16x16x32_bf16 v[86:89], v[146:149], v[178:181], v[86:89]
	v_mfma_f32_16x16x32_bf16 v[86:89], v[150:153], v[182:185], v[86:89]
	v_mfma_f32_16x16x32_bf16 v[82:85], v[158:161], v[182:185], v[82:85]
	v_mfma_f32_16x16x32_bf16 v[82:85], v[154:157], v[178:181], v[82:85]
	v_mfma_f32_16x16x32_bf16 v[66:69], v[154:157], v[186:189], v[66:69]
	v_mfma_f32_16x16x32_bf16 v[66:69], v[158:161], v[190:193], v[66:69]
	v_mfma_f32_16x16x32_bf16 v[70:73], v[150:153], v[190:193], v[70:73]
	v_mfma_f32_16x16x32_bf16 v[70:73], v[146:149], v[186:189], v[70:73]
	s_setprio 0
	s_barrier
	s_add_i32 s64, s66, s39
	v_lshl_add_u64 v[194:195], s[30:31], 0, v[200:201]
	s_mov_b32 m0, s64
	ds_read_b128 v[162:165], v229 offset:16384
	ds_read_b128 v[166:169], v229 offset:17408
	ds_read_b128 v[170:173], v229 offset:18432
	ds_read_b128 v[174:177], v229 offset:19456
	ds_read_b128 v[178:181], v229 offset:20480
	ds_read_b128 v[182:185], v229 offset:21504
	ds_read_b128 v[186:189], v229 offset:22528
	ds_read_b128 v[190:193], v229 offset:23552
	global_load_lds_dwordx4 v[194:195], off
	s_add_i32 m0, s64, 0x2000
	s_add_u32 s64, s30, 0x80000
	v_lshl_add_u64 v[206:207], s[30:31], 0, v[204:205]
	s_addc_u32 s65, s31, 0
	s_add_i32 s44, s44, s39
	global_load_lds_dwordx4 v[206:207], off
	v_lshl_add_u64 v[208:209], s[64:65], 0, v[200:201]
	s_mov_b32 m0, s44
	v_lshl_add_u64 v[210:211], s[36:37], 0, v[202:203]
	global_load_lds_dwordx4 v[208:209], off
	v_lshl_add_u64 v[208:209], s[64:65], 0, v[204:205]
	s_add_i32 m0, s44, 0x2000
	s_nop 0
	global_load_lds_dwordx4 v[208:209], off
	v_lshl_add_u64 v[208:209], s[36:37], 0, v[198:199]
	s_mov_b32 m0, s40
	s_nop 0
	global_load_lds_dwordx4 v[208:209], off
	s_mov_b32 m0, s41
	s_nop 0
	global_load_lds_dwordx4 v[210:211], off
	s_waitcnt vmcnt(8)
	s_waitcnt lgkmcnt(0)
	s_barrier
	s_setprio 1
	s_waitcnt lgkmcnt(0)
	v_mfma_f32_16x16x32_bf16 v[62:65], v[130:133], v[162:165], v[62:65]
	v_mfma_f32_16x16x32_bf16 v[62:65], v[134:137], v[166:169], v[62:65]
	v_mfma_f32_16x16x32_bf16 v[58:61], v[142:145], v[166:169], v[58:61]
	v_mfma_f32_16x16x32_bf16 v[58:61], v[138:141], v[162:165], v[58:61]
	v_mfma_f32_16x16x32_bf16 v[42:45], v[138:141], v[170:173], v[42:45]
	v_mfma_f32_16x16x32_bf16 v[42:45], v[142:145], v[174:177], v[42:45]
	v_mfma_f32_16x16x32_bf16 v[46:49], v[134:137], v[174:177], v[46:49]
	v_mfma_f32_16x16x32_bf16 v[46:49], v[130:133], v[170:173], v[46:49]
	v_mfma_f32_16x16x32_bf16 v[30:33], v[130:133], v[178:181], v[30:33]
	v_mfma_f32_16x16x32_bf16 v[30:33], v[134:137], v[182:185], v[30:33]
	v_mfma_f32_16x16x32_bf16 v[26:29], v[142:145], v[182:185], v[26:29]
	v_mfma_f32_16x16x32_bf16 v[26:29], v[138:141], v[178:181], v[26:29]
	v_mfma_f32_16x16x32_bf16 v[10:13], v[138:141], v[186:189], v[10:13]
	v_mfma_f32_16x16x32_bf16 v[10:13], v[142:145], v[190:193], v[10:13]
	v_mfma_f32_16x16x32_bf16 v[14:17], v[134:137], v[190:193], v[14:17]
	v_mfma_f32_16x16x32_bf16 v[14:17], v[130:133], v[186:189], v[14:17]
	s_setprio 0
	s_setprio 1
	v_mfma_f32_16x16x32_bf16 v[54:57], v[146:149], v[162:165], v[54:57]
	v_mfma_f32_16x16x32_bf16 v[54:57], v[150:153], v[166:169], v[54:57]
	v_mfma_f32_16x16x32_bf16 v[50:53], v[158:161], v[166:169], v[50:53]
	v_mfma_f32_16x16x32_bf16 v[50:53], v[154:157], v[162:165], v[50:53]
	v_mfma_f32_16x16x32_bf16 v[34:37], v[154:157], v[170:173], v[34:37]
	v_mfma_f32_16x16x32_bf16 v[34:37], v[158:161], v[174:177], v[34:37]
	v_mfma_f32_16x16x32_bf16 v[38:41], v[150:153], v[174:177], v[38:41]
	v_mfma_f32_16x16x32_bf16 v[38:41], v[146:149], v[170:173], v[38:41]
	v_mfma_f32_16x16x32_bf16 v[22:25], v[146:149], v[178:181], v[22:25]
	v_mfma_f32_16x16x32_bf16 v[22:25], v[150:153], v[182:185], v[22:25]
	v_mfma_f32_16x16x32_bf16 v[18:21], v[158:161], v[182:185], v[18:21]
	v_mfma_f32_16x16x32_bf16 v[18:21], v[154:157], v[178:181], v[18:21]
	v_mfma_f32_16x16x32_bf16 v[2:5], v[154:157], v[186:189], v[2:5]
	v_mfma_f32_16x16x32_bf16 v[2:5], v[158:161], v[190:193], v[2:5]
	v_mfma_f32_16x16x32_bf16 v[6:9], v[150:153], v[190:193], v[6:9]
	v_mfma_f32_16x16x32_bf16 v[6:9], v[146:149], v[186:189], v[6:9]
	s_setprio 0
	s_barrier
	s_add_i32 s44, 0, 0x18000
	s_add_i32 s64, 0, 0x1c000
	v_add_u32_e32 v142, s44, v227
	v_add_u32_e32 v158, s64, v227
	ds_read_b128 v[130:133], v142
	ds_read_b128 v[134:137], v142 offset:1024
	ds_read_b128 v[138:141], v142 offset:2048
	ds_read_b128 v[142:145], v142 offset:3072
	ds_read_b128 v[146:149], v158
	ds_read_b128 v[150:153], v158 offset:1024
	ds_read_b128 v[154:157], v158 offset:2048
	ds_read_b128 v[158:161], v158 offset:3072
	s_add_u32 s36, s36, 0x80000
	s_addc_u32 s37, s37, 0
	s_mov_b32 m0, s42
	v_lshl_add_u64 v[212:213], s[36:37], 0, v[198:199]
	ds_read_b128 v[162:165], v229 offset:32768
	ds_read_b128 v[166:169], v229 offset:33792
	ds_read_b128 v[170:173], v229 offset:34816
	ds_read_b128 v[174:177], v229 offset:35840
	ds_read_b128 v[178:181], v229 offset:36864
	ds_read_b128 v[182:185], v229 offset:37888
	ds_read_b128 v[186:189], v229 offset:38912
	ds_read_b128 v[190:193], v229 offset:39936
	global_load_lds_dwordx4 v[212:213], off
	v_lshl_add_u64 v[212:213], s[36:37], 0, v[202:203]
	s_mov_b32 m0, s43
	s_nop 0
	global_load_lds_dwordx4 v[212:213], off
	s_waitcnt vmcnt(8)
	s_waitcnt lgkmcnt(0)
	s_barrier
	s_setprio 1
	s_waitcnt lgkmcnt(0)
	v_mfma_f32_16x16x32_bf16 v[126:129], v[130:133], v[162:165], v[126:129]
	v_mfma_f32_16x16x32_bf16 v[126:129], v[134:137], v[166:169], v[126:129]
	v_mfma_f32_16x16x32_bf16 v[122:125], v[142:145], v[166:169], v[122:125]
	v_mfma_f32_16x16x32_bf16 v[122:125], v[138:141], v[162:165], v[122:125]
	v_mfma_f32_16x16x32_bf16 v[106:109], v[138:141], v[170:173], v[106:109]
	v_mfma_f32_16x16x32_bf16 v[106:109], v[142:145], v[174:177], v[106:109]
	v_mfma_f32_16x16x32_bf16 v[110:113], v[134:137], v[174:177], v[110:113]
	v_mfma_f32_16x16x32_bf16 v[110:113], v[130:133], v[170:173], v[110:113]
	v_mfma_f32_16x16x32_bf16 v[94:97], v[130:133], v[178:181], v[94:97]
	v_mfma_f32_16x16x32_bf16 v[94:97], v[134:137], v[182:185], v[94:97]
	v_mfma_f32_16x16x32_bf16 v[90:93], v[142:145], v[182:185], v[90:93]
	v_mfma_f32_16x16x32_bf16 v[90:93], v[138:141], v[178:181], v[90:93]
	v_mfma_f32_16x16x32_bf16 v[74:77], v[138:141], v[186:189], v[74:77]
	v_mfma_f32_16x16x32_bf16 v[74:77], v[142:145], v[190:193], v[74:77]
	v_mfma_f32_16x16x32_bf16 v[78:81], v[134:137], v[190:193], v[78:81]
	v_mfma_f32_16x16x32_bf16 v[78:81], v[130:133], v[186:189], v[78:81]
	s_setprio 0
	s_setprio 1
	v_mfma_f32_16x16x32_bf16 v[118:121], v[146:149], v[162:165], v[118:121]
	v_mfma_f32_16x16x32_bf16 v[118:121], v[150:153], v[166:169], v[118:121]
	v_mfma_f32_16x16x32_bf16 v[114:117], v[158:161], v[166:169], v[114:117]
	v_mfma_f32_16x16x32_bf16 v[114:117], v[154:157], v[162:165], v[114:117]
	v_mfma_f32_16x16x32_bf16 v[98:101], v[154:157], v[170:173], v[98:101]
	v_mfma_f32_16x16x32_bf16 v[98:101], v[158:161], v[174:177], v[98:101]
	v_mfma_f32_16x16x32_bf16 v[102:105], v[150:153], v[174:177], v[102:105]
	v_mfma_f32_16x16x32_bf16 v[102:105], v[146:149], v[170:173], v[102:105]
	v_mfma_f32_16x16x32_bf16 v[86:89], v[146:149], v[178:181], v[86:89]
	v_mfma_f32_16x16x32_bf16 v[86:89], v[150:153], v[182:185], v[86:89]
	v_mfma_f32_16x16x32_bf16 v[82:85], v[158:161], v[182:185], v[82:85]
	v_mfma_f32_16x16x32_bf16 v[82:85], v[154:157], v[178:181], v[82:85]
	v_mfma_f32_16x16x32_bf16 v[66:69], v[154:157], v[186:189], v[66:69]
	v_mfma_f32_16x16x32_bf16 v[66:69], v[158:161], v[190:193], v[66:69]
	v_mfma_f32_16x16x32_bf16 v[70:73], v[150:153], v[190:193], v[70:73]
	v_mfma_f32_16x16x32_bf16 v[70:73], v[146:149], v[186:189], v[70:73]
	s_setprio 0
	s_barrier
	s_add_i32 s36, s44, s39
	v_lshl_add_u64 v[194:195], v[194:195], 0, s[2:3]
	s_mov_b32 m0, s36
	ds_read_b128 v[162:165], v229 offset:49152
	ds_read_b128 v[166:169], v229 offset:50176
	ds_read_b128 v[170:173], v229 offset:51200
	ds_read_b128 v[174:177], v229 offset:52224
	ds_read_b128 v[178:181], v229 offset:53248
	ds_read_b128 v[182:185], v229 offset:54272
	ds_read_b128 v[186:189], v229 offset:55296
	ds_read_b128 v[190:193], v229 offset:56320
	global_load_lds_dwordx4 v[194:195], off
	s_add_i32 m0, s36, 0x2000
	s_add_u32 s30, s30, 0x80080
	v_lshl_add_u64 v[194:195], v[206:207], 0, s[2:3]
	s_addc_u32 s31, s31, 0
	s_add_i32 s36, s64, s39
	global_load_lds_dwordx4 v[194:195], off
	v_lshl_add_u64 v[194:195], s[30:31], 0, v[200:201]
	s_mov_b32 m0, s36
	s_nop 0
	global_load_lds_dwordx4 v[194:195], off
	v_lshl_add_u64 v[194:195], s[30:31], 0, v[204:205]
	s_add_i32 m0, s36, 0x2000
	s_nop 0
	global_load_lds_dwordx4 v[194:195], off
	v_lshl_add_u64 v[194:195], v[208:209], 0, s[2:3]
	s_mov_b32 m0, s50
	s_nop 0
	global_load_lds_dwordx4 v[194:195], off
	v_lshl_add_u64 v[194:195], v[210:211], 0, s[2:3]
	s_mov_b32 m0, s51
	s_nop 0
	global_load_lds_dwordx4 v[194:195], off
	s_waitcnt vmcnt(8)
	s_waitcnt lgkmcnt(0)
	s_barrier
	s_setprio 1
	s_waitcnt lgkmcnt(0)
	v_mfma_f32_16x16x32_bf16 v[62:65], v[130:133], v[162:165], v[62:65]
	v_mfma_f32_16x16x32_bf16 v[62:65], v[134:137], v[166:169], v[62:65]
	v_mfma_f32_16x16x32_bf16 v[58:61], v[142:145], v[166:169], v[58:61]
	v_mfma_f32_16x16x32_bf16 v[58:61], v[138:141], v[162:165], v[58:61]
	v_mfma_f32_16x16x32_bf16 v[42:45], v[138:141], v[170:173], v[42:45]
	v_mfma_f32_16x16x32_bf16 v[42:45], v[142:145], v[174:177], v[42:45]
	v_mfma_f32_16x16x32_bf16 v[46:49], v[134:137], v[174:177], v[46:49]
	v_mfma_f32_16x16x32_bf16 v[46:49], v[130:133], v[170:173], v[46:49]
	v_mfma_f32_16x16x32_bf16 v[30:33], v[130:133], v[178:181], v[30:33]
	v_mfma_f32_16x16x32_bf16 v[30:33], v[134:137], v[182:185], v[30:33]
	v_mfma_f32_16x16x32_bf16 v[26:29], v[142:145], v[182:185], v[26:29]
	v_mfma_f32_16x16x32_bf16 v[26:29], v[138:141], v[178:181], v[26:29]
	v_mfma_f32_16x16x32_bf16 v[10:13], v[138:141], v[186:189], v[10:13]
	v_mfma_f32_16x16x32_bf16 v[10:13], v[142:145], v[190:193], v[10:13]
	v_mfma_f32_16x16x32_bf16 v[14:17], v[134:137], v[190:193], v[14:17]
	v_mfma_f32_16x16x32_bf16 v[14:17], v[130:133], v[186:189], v[14:17]
	s_setprio 0
	s_setprio 1
	v_mfma_f32_16x16x32_bf16 v[54:57], v[146:149], v[162:165], v[54:57]
	v_mfma_f32_16x16x32_bf16 v[54:57], v[150:153], v[166:169], v[54:57]
	v_mfma_f32_16x16x32_bf16 v[50:53], v[158:161], v[166:169], v[50:53]
	v_mfma_f32_16x16x32_bf16 v[50:53], v[154:157], v[162:165], v[50:53]
	v_mfma_f32_16x16x32_bf16 v[34:37], v[154:157], v[170:173], v[34:37]
	v_mfma_f32_16x16x32_bf16 v[34:37], v[158:161], v[174:177], v[34:37]
	v_mfma_f32_16x16x32_bf16 v[38:41], v[150:153], v[174:177], v[38:41]
	v_mfma_f32_16x16x32_bf16 v[38:41], v[146:149], v[170:173], v[38:41]
	v_mfma_f32_16x16x32_bf16 v[22:25], v[146:149], v[178:181], v[22:25]
	v_mfma_f32_16x16x32_bf16 v[22:25], v[150:153], v[182:185], v[22:25]
	v_mfma_f32_16x16x32_bf16 v[18:21], v[158:161], v[182:185], v[18:21]
	v_mfma_f32_16x16x32_bf16 v[18:21], v[154:157], v[178:181], v[18:21]
	v_mfma_f32_16x16x32_bf16 v[2:5], v[154:157], v[186:189], v[2:5]
	v_mfma_f32_16x16x32_bf16 v[2:5], v[158:161], v[190:193], v[2:5]
	v_mfma_f32_16x16x32_bf16 v[6:9], v[150:153], v[190:193], v[6:9]
	v_mfma_f32_16x16x32_bf16 v[6:9], v[146:149], v[186:189], v[6:9]
	s_setprio 0
	s_barrier
	s_add_i32 s36, s49, 2
	s_cmp_ge_i32 s49, s5
	s_mov_b64 s[30:31], s[34:35]
	s_mov_b32 s49, s36
	s_cbranch_scc0 .LBB0_632

.LBB0_782:
	s_add_u32 s58, s34, 0x100
	s_addc_u32 s59, s35, 0
	s_mov_b32 s60, 2
	s_mov_b64 s[34:35], 0
	s_add_i32 s36, s60, -2
	s_lshr_b32 s44, s36, 2
	s_lshl_b64 s[38:39], s[44:45], 9
	s_lshr_b32 s44, s60, 2
	s_and_b32 s61, s34, 0x100
	s_lshl_b64 s[36:37], s[44:45], 9
	s_add_u32 s44, s30, s36
	s_addc_u32 s62, s31, s37
	s_add_u32 s36, s34, 0x100
	s_addc_u32 s37, s35, 0
	s_and_b32 s63, s36, 0x100
	s_add_u32 s44, s44, s63
	s_addc_u32 s62, s62, 0
	s_add_u32 s34, s58, s34
	s_addc_u32 s35, s59, s35
	s_add_i32 s64, 0, 0x10000
	s_add_u32 s63, s30, s38
	s_addc_u32 s65, s31, s39
	s_cmp_eq_u32 s57, s60
	s_cselect_b32 s39, s27, s62
	s_cselect_b32 s38, s26, s44
	s_cselect_b32 s35, s29, s35
	s_cselect_b32 s34, s28, s34
	s_add_i32 s44, 0, 0x14000
	v_add_u32_e32 v152, s64, v137
	v_add_u32_e32 v168, s44, v137
	ds_read_b128 v[140:143], v152
	ds_read_b128 v[144:147], v152 offset:1024
	ds_read_b128 v[148:151], v152 offset:2048
	ds_read_b128 v[152:155], v152 offset:3072
	ds_read_b128 v[156:159], v168
	ds_read_b128 v[160:163], v168 offset:1024
	ds_read_b128 v[164:167], v168 offset:2048
	ds_read_b128 v[168:171], v168 offset:3072
	s_add_u32 s61, s63, s61
	s_addc_u32 s63, s65, 0
	s_add_u32 s62, s61, 0x80080
	s_addc_u32 s63, s63, 0
	v_lshl_add_u64 v[206:207], s[62:63], 0, v[130:131]
	s_add_i32 m0, s11, 0xc000
	ds_read_b128 v[172:175], v139
	ds_read_b128 v[176:179], v139 offset:1024
	ds_read_b128 v[180:183], v139 offset:2048
	ds_read_b128 v[184:187], v139 offset:3072
	ds_read_b128 v[188:191], v139 offset:4096
	ds_read_b128 v[192:195], v139 offset:5120
	ds_read_b128 v[198:201], v139 offset:6144
	ds_read_b128 v[202:205], v139 offset:7168
	global_load_lds_dwordx4 v[206:207], off
	v_lshl_add_u64 v[206:207], s[62:63], 0, v[132:133]
	s_add_i32 m0, s11, 0xe000
	s_nop 0
	global_load_lds_dwordx4 v[206:207], off
	s_waitcnt vmcnt(8)
	s_waitcnt lgkmcnt(0)
	s_barrier
	s_setprio 1
	s_waitcnt lgkmcnt(0)
	v_mfma_f32_16x16x32_bf16 v[126:129], v[140:143], v[172:175], 0
	v_mfma_f32_16x16x32_bf16 v[126:129], v[144:147], v[176:179], v[126:129]
	v_mfma_f32_16x16x32_bf16 v[122:125], v[152:155], v[176:179], 0
	v_mfma_f32_16x16x32_bf16 v[122:125], v[148:151], v[172:175], v[122:125]
	v_mfma_f32_16x16x32_bf16 v[106:109], v[148:151], v[180:183], 0
	v_mfma_f32_16x16x32_bf16 v[106:109], v[152:155], v[184:187], v[106:109]
	v_mfma_f32_16x16x32_bf16 v[110:113], v[144:147], v[184:187], 0
	v_mfma_f32_16x16x32_bf16 v[110:113], v[140:143], v[180:183], v[110:113]
	v_mfma_f32_16x16x32_bf16 v[94:97], v[140:143], v[188:191], 0
	v_mfma_f32_16x16x32_bf16 v[94:97], v[144:147], v[192:195], v[94:97]
	v_mfma_f32_16x16x32_bf16 v[90:93], v[152:155], v[192:195], 0
	v_mfma_f32_16x16x32_bf16 v[90:93], v[148:151], v[188:191], v[90:93]
	v_mfma_f32_16x16x32_bf16 v[74:77], v[148:151], v[198:201], 0
	v_mfma_f32_16x16x32_bf16 v[74:77], v[152:155], v[202:205], v[74:77]
	v_mfma_f32_16x16x32_bf16 v[78:81], v[144:147], v[202:205], 0
	v_mfma_f32_16x16x32_bf16 v[78:81], v[140:143], v[198:201], v[78:81]
	s_setprio 0
	s_setprio 1
	v_mfma_f32_16x16x32_bf16 v[118:121], v[156:159], v[172:175], 0
	v_mfma_f32_16x16x32_bf16 v[118:121], v[160:163], v[176:179], v[118:121]
	v_mfma_f32_16x16x32_bf16 v[114:117], v[168:171], v[176:179], 0
	v_mfma_f32_16x16x32_bf16 v[114:117], v[164:167], v[172:175], v[114:117]
	v_mfma_f32_16x16x32_bf16 v[98:101], v[164:167], v[180:183], 0
	v_mfma_f32_16x16x32_bf16 v[98:101], v[168:171], v[184:187], v[98:101]
	v_mfma_f32_16x16x32_bf16 v[102:105], v[160:163], v[184:187], 0
	v_mfma_f32_16x16x32_bf16 v[102:105], v[156:159], v[180:183], v[102:105]
	v_mfma_f32_16x16x32_bf16 v[86:89], v[156:159], v[188:191], 0
	v_mfma_f32_16x16x32_bf16 v[86:89], v[160:163], v[192:195], v[86:89]
	v_mfma_f32_16x16x32_bf16 v[82:85], v[168:171], v[192:195], 0
	v_mfma_f32_16x16x32_bf16 v[82:85], v[164:167], v[188:191], v[82:85]
	v_mfma_f32_16x16x32_bf16 v[66:69], v[164:167], v[198:201], 0
	v_mfma_f32_16x16x32_bf16 v[66:69], v[168:171], v[202:205], v[66:69]
	v_mfma_f32_16x16x32_bf16 v[70:73], v[160:163], v[202:205], 0
	v_mfma_f32_16x16x32_bf16 v[70:73], v[156:159], v[198:201], v[70:73]
	s_setprio 0
	s_barrier
	s_add_i32 s61, s64, s9
	v_lshl_add_u64 v[206:207], s[34:35], 0, v[196:197]
	s_mov_b32 m0, s61
	ds_read_b128 v[172:175], v139 offset:16384
	ds_read_b128 v[176:179], v139 offset:17408
	ds_read_b128 v[180:183], v139 offset:18432
	ds_read_b128 v[184:187], v139 offset:19456
	ds_read_b128 v[188:191], v139 offset:20480
	ds_read_b128 v[192:195], v139 offset:21504
	ds_read_b128 v[198:201], v139 offset:22528
	ds_read_b128 v[202:205], v139 offset:23552
	global_load_lds_dwordx4 v[206:207], off
	s_add_i32 m0, s61, 0x2000
	s_add_u32 s62, s34, 0x80000
	v_lshl_add_u64 v[208:209], s[34:35], 0, v[134:135]
	s_addc_u32 s63, s35, 0
	s_add_i32 s44, s44, s9
	global_load_lds_dwordx4 v[208:209], off
	v_lshl_add_u64 v[210:211], s[62:63], 0, v[196:197]
	s_mov_b32 m0, s44
	v_lshl_add_u64 v[212:213], s[38:39], 0, v[132:133]
	global_load_lds_dwordx4 v[210:211], off
	v_lshl_add_u64 v[210:211], s[62:63], 0, v[134:135]
	s_add_i32 m0, s44, 0x2000
	s_nop 0
	global_load_lds_dwordx4 v[210:211], off
	v_lshl_add_u64 v[210:211], s[38:39], 0, v[130:131]
	s_mov_b32 m0, s11
	s_nop 0
	global_load_lds_dwordx4 v[210:211], off
	s_mov_b32 m0, s33
	s_nop 0
	global_load_lds_dwordx4 v[212:213], off
	s_waitcnt vmcnt(8)
	s_waitcnt lgkmcnt(0)
	s_barrier
	s_setprio 1
	s_waitcnt lgkmcnt(0)
	v_mfma_f32_16x16x32_bf16 v[62:65], v[140:143], v[172:175], 0
	v_mfma_f32_16x16x32_bf16 v[62:65], v[144:147], v[176:179], v[62:65]
	v_mfma_f32_16x16x32_bf16 v[58:61], v[152:155], v[176:179], 0
	v_mfma_f32_16x16x32_bf16 v[58:61], v[148:151], v[172:175], v[58:61]
	v_mfma_f32_16x16x32_bf16 v[42:45], v[148:151], v[180:183], 0
	v_mfma_f32_16x16x32_bf16 v[42:45], v[152:155], v[184:187], v[42:45]
	v_mfma_f32_16x16x32_bf16 v[46:49], v[144:147], v[184:187], 0
	v_mfma_f32_16x16x32_bf16 v[46:49], v[140:143], v[180:183], v[46:49]
	v_mfma_f32_16x16x32_bf16 v[30:33], v[140:143], v[188:191], 0
	v_mfma_f32_16x16x32_bf16 v[30:33], v[144:147], v[192:195], v[30:33]
	v_mfma_f32_16x16x32_bf16 v[26:29], v[152:155], v[192:195], 0
	v_mfma_f32_16x16x32_bf16 v[26:29], v[148:151], v[188:191], v[26:29]
	v_mfma_f32_16x16x32_bf16 v[10:13], v[148:151], v[198:201], 0
	v_mfma_f32_16x16x32_bf16 v[10:13], v[152:155], v[202:205], v[10:13]
	v_mfma_f32_16x16x32_bf16 v[14:17], v[144:147], v[202:205], 0
	v_mfma_f32_16x16x32_bf16 v[14:17], v[140:143], v[198:201], v[14:17]
	s_setprio 0
	s_setprio 1
	v_mfma_f32_16x16x32_bf16 v[54:57], v[156:159], v[172:175], 0
	v_mfma_f32_16x16x32_bf16 v[54:57], v[160:163], v[176:179], v[54:57]
	v_mfma_f32_16x16x32_bf16 v[50:53], v[168:171], v[176:179], 0
	v_mfma_f32_16x16x32_bf16 v[50:53], v[164:167], v[172:175], v[50:53]
	v_mfma_f32_16x16x32_bf16 v[34:37], v[164:167], v[180:183], 0
	v_mfma_f32_16x16x32_bf16 v[34:37], v[168:171], v[184:187], v[34:37]
	v_mfma_f32_16x16x32_bf16 v[38:41], v[160:163], v[184:187], 0
	v_mfma_f32_16x16x32_bf16 v[38:41], v[156:159], v[180:183], v[38:41]
	v_mfma_f32_16x16x32_bf16 v[22:25], v[156:159], v[188:191], 0
	v_mfma_f32_16x16x32_bf16 v[22:25], v[160:163], v[192:195], v[22:25]
	v_mfma_f32_16x16x32_bf16 v[18:21], v[168:171], v[192:195], 0
	v_mfma_f32_16x16x32_bf16 v[18:21], v[164:167], v[188:191], v[18:21]
	v_mfma_f32_16x16x32_bf16 v[2:5], v[164:167], v[198:201], 0
	v_mfma_f32_16x16x32_bf16 v[2:5], v[168:171], v[202:205], v[2:5]
	v_mfma_f32_16x16x32_bf16 v[6:9], v[160:163], v[202:205], 0
	v_mfma_f32_16x16x32_bf16 v[6:9], v[156:159], v[198:201], v[6:9]
	s_setprio 0
	s_barrier
	s_add_i32 s44, 0, 0x18000
	s_add_i32 s61, 0, 0x1c000
	v_add_u32_e32 v152, s44, v137
	v_add_u32_e32 v168, s61, v137
	ds_read_b128 v[140:143], v152
	ds_read_b128 v[144:147], v152 offset:1024
	ds_read_b128 v[148:151], v152 offset:2048
	ds_read_b128 v[152:155], v152 offset:3072
	ds_read_b128 v[156:159], v168
	ds_read_b128 v[160:163], v168 offset:1024
	ds_read_b128 v[164:167], v168 offset:2048
	ds_read_b128 v[168:171], v168 offset:3072
	s_add_u32 s38, s38, 0x80000
	s_addc_u32 s39, s39, 0
	s_mov_b32 m0, s40
	v_lshl_add_u64 v[214:215], s[38:39], 0, v[130:131]
	ds_read_b128 v[172:175], v139 offset:32768
	ds_read_b128 v[176:179], v139 offset:33792
	ds_read_b128 v[180:183], v139 offset:34816
	ds_read_b128 v[184:187], v139 offset:35840
	ds_read_b128 v[188:191], v139 offset:36864
	ds_read_b128 v[192:195], v139 offset:37888
	ds_read_b128 v[198:201], v139 offset:38912
	ds_read_b128 v[202:205], v139 offset:39936
	global_load_lds_dwordx4 v[214:215], off
	v_lshl_add_u64 v[214:215], s[38:39], 0, v[132:133]
	s_mov_b32 m0, s41
	s_nop 0
	global_load_lds_dwordx4 v[214:215], off
	s_waitcnt vmcnt(8)
	s_waitcnt lgkmcnt(0)
	s_barrier
	s_setprio 1
	s_waitcnt lgkmcnt(0)
	v_mfma_f32_16x16x32_bf16 v[126:129], v[140:143], v[172:175], v[126:129]
	v_mfma_f32_16x16x32_bf16 v[126:129], v[144:147], v[176:179], v[126:129]
	v_mfma_f32_16x16x32_bf16 v[122:125], v[152:155], v[176:179], v[122:125]
	v_mfma_f32_16x16x32_bf16 v[122:125], v[148:151], v[172:175], v[122:125]
	v_mfma_f32_16x16x32_bf16 v[106:109], v[148:151], v[180:183], v[106:109]
	v_mfma_f32_16x16x32_bf16 v[106:109], v[152:155], v[184:187], v[106:109]
	v_mfma_f32_16x16x32_bf16 v[110:113], v[144:147], v[184:187], v[110:113]
	v_mfma_f32_16x16x32_bf16 v[110:113], v[140:143], v[180:183], v[110:113]
	v_mfma_f32_16x16x32_bf16 v[94:97], v[140:143], v[188:191], v[94:97]
	v_mfma_f32_16x16x32_bf16 v[94:97], v[144:147], v[192:195], v[94:97]
	v_mfma_f32_16x16x32_bf16 v[90:93], v[152:155], v[192:195], v[90:93]
	v_mfma_f32_16x16x32_bf16 v[90:93], v[148:151], v[188:191], v[90:93]
	v_mfma_f32_16x16x32_bf16 v[74:77], v[148:151], v[198:201], v[74:77]
	v_mfma_f32_16x16x32_bf16 v[74:77], v[152:155], v[202:205], v[74:77]
	v_mfma_f32_16x16x32_bf16 v[78:81], v[144:147], v[202:205], v[78:81]
	v_mfma_f32_16x16x32_bf16 v[78:81], v[140:143], v[198:201], v[78:81]
	s_setprio 0
	s_setprio 1
	v_mfma_f32_16x16x32_bf16 v[118:121], v[156:159], v[172:175], v[118:121]
	v_mfma_f32_16x16x32_bf16 v[118:121], v[160:163], v[176:179], v[118:121]
	v_mfma_f32_16x16x32_bf16 v[114:117], v[168:171], v[176:179], v[114:117]
	v_mfma_f32_16x16x32_bf16 v[114:117], v[164:167], v[172:175], v[114:117]
	v_mfma_f32_16x16x32_bf16 v[98:101], v[164:167], v[180:183], v[98:101]
	v_mfma_f32_16x16x32_bf16 v[98:101], v[168:171], v[184:187], v[98:101]
	v_mfma_f32_16x16x32_bf16 v[102:105], v[160:163], v[184:187], v[102:105]
	v_mfma_f32_16x16x32_bf16 v[102:105], v[156:159], v[180:183], v[102:105]
	v_mfma_f32_16x16x32_bf16 v[86:89], v[156:159], v[188:191], v[86:89]
	v_mfma_f32_16x16x32_bf16 v[86:89], v[160:163], v[192:195], v[86:89]
	v_mfma_f32_16x16x32_bf16 v[82:85], v[168:171], v[192:195], v[82:85]
	v_mfma_f32_16x16x32_bf16 v[82:85], v[164:167], v[188:191], v[82:85]
	v_mfma_f32_16x16x32_bf16 v[66:69], v[164:167], v[198:201], v[66:69]
	v_mfma_f32_16x16x32_bf16 v[66:69], v[168:171], v[202:205], v[66:69]
	v_mfma_f32_16x16x32_bf16 v[70:73], v[160:163], v[202:205], v[70:73]
	v_mfma_f32_16x16x32_bf16 v[70:73], v[156:159], v[198:201], v[70:73]
	s_setprio 0
	s_barrier
	s_add_i32 s38, s44, s9
	v_lshl_add_u64 v[206:207], v[206:207], 0, s[2:3]
	s_mov_b32 m0, s38
	ds_read_b128 v[172:175], v139 offset:49152
	ds_read_b128 v[176:179], v139 offset:50176
	ds_read_b128 v[180:183], v139 offset:51200
	ds_read_b128 v[184:187], v139 offset:52224
	ds_read_b128 v[188:191], v139 offset:53248
	ds_read_b128 v[192:195], v139 offset:54272
	ds_read_b128 v[198:201], v139 offset:55296
	ds_read_b128 v[202:205], v139 offset:56320
	global_load_lds_dwordx4 v[206:207], off
	s_add_i32 m0, s38, 0x2000
	s_add_u32 s34, s34, 0x80080
	v_lshl_add_u64 v[206:207], v[208:209], 0, s[2:3]
	s_addc_u32 s35, s35, 0
	s_add_i32 s38, s61, s9
	global_load_lds_dwordx4 v[206:207], off
	v_lshl_add_u64 v[206:207], s[34:35], 0, v[196:197]
	s_mov_b32 m0, s38
	s_nop 0
	global_load_lds_dwordx4 v[206:207], off
	v_lshl_add_u64 v[206:207], s[34:35], 0, v[134:135]
	s_add_i32 m0, s38, 0x2000
	s_nop 0
	global_load_lds_dwordx4 v[206:207], off
	v_lshl_add_u64 v[206:207], v[210:211], 0, s[2:3]
	s_mov_b32 m0, s50
	s_nop 0
	global_load_lds_dwordx4 v[206:207], off
	v_lshl_add_u64 v[206:207], v[212:213], 0, s[2:3]
	s_mov_b32 m0, s51
	s_nop 0
	global_load_lds_dwordx4 v[206:207], off
	s_waitcnt vmcnt(8)
	s_waitcnt lgkmcnt(0)
	s_barrier
	s_setprio 1
	s_waitcnt lgkmcnt(0)
	v_mfma_f32_16x16x32_bf16 v[62:65], v[140:143], v[172:175], v[62:65]
	v_mfma_f32_16x16x32_bf16 v[62:65], v[144:147], v[176:179], v[62:65]
	v_mfma_f32_16x16x32_bf16 v[58:61], v[152:155], v[176:179], v[58:61]
	v_mfma_f32_16x16x32_bf16 v[58:61], v[148:151], v[172:175], v[58:61]
	v_mfma_f32_16x16x32_bf16 v[42:45], v[148:151], v[180:183], v[42:45]
	v_mfma_f32_16x16x32_bf16 v[42:45], v[152:155], v[184:187], v[42:45]
	v_mfma_f32_16x16x32_bf16 v[46:49], v[144:147], v[184:187], v[46:49]
	v_mfma_f32_16x16x32_bf16 v[46:49], v[140:143], v[180:183], v[46:49]
	v_mfma_f32_16x16x32_bf16 v[30:33], v[140:143], v[188:191], v[30:33]
	v_mfma_f32_16x16x32_bf16 v[30:33], v[144:147], v[192:195], v[30:33]
	v_mfma_f32_16x16x32_bf16 v[26:29], v[152:155], v[192:195], v[26:29]
	v_mfma_f32_16x16x32_bf16 v[26:29], v[148:151], v[188:191], v[26:29]
	v_mfma_f32_16x16x32_bf16 v[10:13], v[148:151], v[198:201], v[10:13]
	v_mfma_f32_16x16x32_bf16 v[10:13], v[152:155], v[202:205], v[10:13]
	v_mfma_f32_16x16x32_bf16 v[14:17], v[144:147], v[202:205], v[14:17]
	v_mfma_f32_16x16x32_bf16 v[14:17], v[140:143], v[198:201], v[14:17]
	s_setprio 0
	s_setprio 1
	v_mfma_f32_16x16x32_bf16 v[54:57], v[156:159], v[172:175], v[54:57]
	v_mfma_f32_16x16x32_bf16 v[54:57], v[160:163], v[176:179], v[54:57]
	v_mfma_f32_16x16x32_bf16 v[50:53], v[168:171], v[176:179], v[50:53]
	v_mfma_f32_16x16x32_bf16 v[50:53], v[164:167], v[172:175], v[50:53]
	v_mfma_f32_16x16x32_bf16 v[34:37], v[164:167], v[180:183], v[34:37]
	v_mfma_f32_16x16x32_bf16 v[34:37], v[168:171], v[184:187], v[34:37]
	v_mfma_f32_16x16x32_bf16 v[38:41], v[160:163], v[184:187], v[38:41]
	v_mfma_f32_16x16x32_bf16 v[38:41], v[156:159], v[180:183], v[38:41]
	v_mfma_f32_16x16x32_bf16 v[22:25], v[156:159], v[188:191], v[22:25]
	v_mfma_f32_16x16x32_bf16 v[22:25], v[160:163], v[192:195], v[22:25]
	v_mfma_f32_16x16x32_bf16 v[18:21], v[168:171], v[192:195], v[18:21]
	v_mfma_f32_16x16x32_bf16 v[18:21], v[164:167], v[188:191], v[18:21]
	v_mfma_f32_16x16x32_bf16 v[2:5], v[164:167], v[198:201], v[2:5]
	v_mfma_f32_16x16x32_bf16 v[2:5], v[168:171], v[202:205], v[2:5]
	v_mfma_f32_16x16x32_bf16 v[6:9], v[160:163], v[202:205], v[6:9]
	v_mfma_f32_16x16x32_bf16 v[6:9], v[156:159], v[198:201], v[6:9]
	s_setprio 0
	s_barrier
	s_add_i32 s38, s60, 2
	s_cmp_ge_i32 s60, s57
	s_mov_b64 s[34:35], s[36:37]
	s_mov_b32 s60, s38
	s_cbranch_scc1 .Lpeel_exit_wout
.LBB0_783:
	s_add_i32 s36, s60, -2
	s_lshr_b32 s44, s36, 2
	s_lshl_b64 s[38:39], s[44:45], 9
	s_lshr_b32 s44, s60, 2
	s_and_b32 s61, s34, 0x100
	s_lshl_b64 s[36:37], s[44:45], 9
	s_add_u32 s44, s30, s36
	s_addc_u32 s62, s31, s37
	s_add_u32 s36, s34, 0x100
	s_addc_u32 s37, s35, 0
	s_and_b32 s63, s36, 0x100
	s_add_u32 s44, s44, s63
	s_addc_u32 s62, s62, 0
	s_add_u32 s34, s58, s34
	s_addc_u32 s35, s59, s35
	s_add_i32 s64, 0, 0x10000
	s_add_u32 s63, s30, s38
	s_addc_u32 s65, s31, s39
	s_cmp_eq_u32 s57, s60
	s_cselect_b32 s39, s27, s62
	s_cselect_b32 s38, s26, s44
	s_cselect_b32 s35, s29, s35
	s_cselect_b32 s34, s28, s34
	s_add_i32 s44, 0, 0x14000
	v_add_u32_e32 v152, s64, v137
	v_add_u32_e32 v168, s44, v137
	ds_read_b128 v[140:143], v152
	ds_read_b128 v[144:147], v152 offset:1024
	ds_read_b128 v[148:151], v152 offset:2048
	ds_read_b128 v[152:155], v152 offset:3072
	ds_read_b128 v[156:159], v168
	ds_read_b128 v[160:163], v168 offset:1024
	ds_read_b128 v[164:167], v168 offset:2048
	ds_read_b128 v[168:171], v168 offset:3072
	s_add_u32 s61, s63, s61
	s_addc_u32 s63, s65, 0
	s_add_u32 s62, s61, 0x80080
	s_addc_u32 s63, s63, 0
	v_lshl_add_u64 v[206:207], s[62:63], 0, v[130:131]
	s_add_i32 m0, s11, 0xc000
	ds_read_b128 v[172:175], v139
	ds_read_b128 v[176:179], v139 offset:1024
	ds_read_b128 v[180:183], v139 offset:2048
	ds_read_b128 v[184:187], v139 offset:3072
	ds_read_b128 v[188:191], v139 offset:4096
	ds_read_b128 v[192:195], v139 offset:5120
	ds_read_b128 v[198:201], v139 offset:6144
	ds_read_b128 v[202:205], v139 offset:7168
	global_load_lds_dwordx4 v[206:207], off
	v_lshl_add_u64 v[206:207], s[62:63], 0, v[132:133]
	s_add_i32 m0, s11, 0xe000
	s_nop 0
	global_load_lds_dwordx4 v[206:207], off
	s_waitcnt vmcnt(8)
	s_waitcnt lgkmcnt(0)
	s_barrier
	s_setprio 1
	s_waitcnt lgkmcnt(0)
	v_mfma_f32_16x16x32_bf16 v[126:129], v[140:143], v[172:175], v[126:129]
	v_mfma_f32_16x16x32_bf16 v[126:129], v[144:147], v[176:179], v[126:129]
	v_mfma_f32_16x16x32_bf16 v[122:125], v[152:155], v[176:179], v[122:125]
	v_mfma_f32_16x16x32_bf16 v[122:125], v[148:151], v[172:175], v[122:125]
	v_mfma_f32_16x16x32_bf16 v[106:109], v[148:151], v[180:183], v[106:109]
	v_mfma_f32_16x16x32_bf16 v[106:109], v[152:155], v[184:187], v[106:109]
	v_mfma_f32_16x16x32_bf16 v[110:113], v[144:147], v[184:187], v[110:113]
	v_mfma_f32_16x16x32_bf16 v[110:113], v[140:143], v[180:183], v[110:113]
	v_mfma_f32_16x16x32_bf16 v[94:97], v[140:143], v[188:191], v[94:97]
	v_mfma_f32_16x16x32_bf16 v[94:97], v[144:147], v[192:195], v[94:97]
	v_mfma_f32_16x16x32_bf16 v[90:93], v[152:155], v[192:195], v[90:93]
	v_mfma_f32_16x16x32_bf16 v[90:93], v[148:151], v[188:191], v[90:93]
	v_mfma_f32_16x16x32_bf16 v[74:77], v[148:151], v[198:201], v[74:77]
	v_mfma_f32_16x16x32_bf16 v[74:77], v[152:155], v[202:205], v[74:77]
	v_mfma_f32_16x16x32_bf16 v[78:81], v[144:147], v[202:205], v[78:81]
	v_mfma_f32_16x16x32_bf16 v[78:81], v[140:143], v[198:201], v[78:81]
	s_setprio 0
	s_setprio 1
	v_mfma_f32_16x16x32_bf16 v[118:121], v[156:159], v[172:175], v[118:121]
	v_mfma_f32_16x16x32_bf16 v[118:121], v[160:163], v[176:179], v[118:121]
	v_mfma_f32_16x16x32_bf16 v[114:117], v[168:171], v[176:179], v[114:117]
	v_mfma_f32_16x16x32_bf16 v[114:117], v[164:167], v[172:175], v[114:117]
	v_mfma_f32_16x16x32_bf16 v[98:101], v[164:167], v[180:183], v[98:101]
	v_mfma_f32_16x16x32_bf16 v[98:101], v[168:171], v[184:187], v[98:101]
	v_mfma_f32_16x16x32_bf16 v[102:105], v[160:163], v[184:187], v[102:105]
	v_mfma_f32_16x16x32_bf16 v[102:105], v[156:159], v[180:183], v[102:105]
	v_mfma_f32_16x16x32_bf16 v[86:89], v[156:159], v[188:191], v[86:89]
	v_mfma_f32_16x16x32_bf16 v[86:89], v[160:163], v[192:195], v[86:89]
	v_mfma_f32_16x16x32_bf16 v[82:85], v[168:171], v[192:195], v[82:85]
	v_mfma_f32_16x16x32_bf16 v[82:85], v[164:167], v[188:191], v[82:85]
	v_mfma_f32_16x16x32_bf16 v[66:69], v[164:167], v[198:201], v[66:69]
	v_mfma_f32_16x16x32_bf16 v[66:69], v[168:171], v[202:205], v[66:69]
	v_mfma_f32_16x16x32_bf16 v[70:73], v[160:163], v[202:205], v[70:73]
	v_mfma_f32_16x16x32_bf16 v[70:73], v[156:159], v[198:201], v[70:73]
	s_setprio 0
	s_barrier
	s_add_i32 s61, s64, s9
	v_lshl_add_u64 v[206:207], s[34:35], 0, v[196:197]
	s_mov_b32 m0, s61
	ds_read_b128 v[172:175], v139 offset:16384
	ds_read_b128 v[176:179], v139 offset:17408
	ds_read_b128 v[180:183], v139 offset:18432
	ds_read_b128 v[184:187], v139 offset:19456
	ds_read_b128 v[188:191], v139 offset:20480
	ds_read_b128 v[192:195], v139 offset:21504
	ds_read_b128 v[198:201], v139 offset:22528
	ds_read_b128 v[202:205], v139 offset:23552
	global_load_lds_dwordx4 v[206:207], off
	s_add_i32 m0, s61, 0x2000
	s_add_u32 s62, s34, 0x80000
	v_lshl_add_u64 v[208:209], s[34:35], 0, v[134:135]
	s_addc_u32 s63, s35, 0
	s_add_i32 s44, s44, s9
	global_load_lds_dwordx4 v[208:209], off
	v_lshl_add_u64 v[210:211], s[62:63], 0, v[196:197]
	s_mov_b32 m0, s44
	v_lshl_add_u64 v[212:213], s[38:39], 0, v[132:133]
	global_load_lds_dwordx4 v[210:211], off
	v_lshl_add_u64 v[210:211], s[62:63], 0, v[134:135]
	s_add_i32 m0, s44, 0x2000
	s_nop 0
	global_load_lds_dwordx4 v[210:211], off
	v_lshl_add_u64 v[210:211], s[38:39], 0, v[130:131]
	s_mov_b32 m0, s11
	s_nop 0
	global_load_lds_dwordx4 v[210:211], off
	s_mov_b32 m0, s33
	s_nop 0
	global_load_lds_dwordx4 v[212:213], off
	s_waitcnt vmcnt(8)
	s_waitcnt lgkmcnt(0)
	s_barrier
	s_setprio 1
	s_waitcnt lgkmcnt(0)
	v_mfma_f32_16x16x32_bf16 v[62:65], v[140:143], v[172:175], v[62:65]
	v_mfma_f32_16x16x32_bf16 v[62:65], v[144:147], v[176:179], v[62:65]
	v_mfma_f32_16x16x32_bf16 v[58:61], v[152:155], v[176:179], v[58:61]
	v_mfma_f32_16x16x32_bf16 v[58:61], v[148:151], v[172:175], v[58:61]
	v_mfma_f32_16x16x32_bf16 v[42:45], v[148:151], v[180:183], v[42:45]
	v_mfma_f32_16x16x32_bf16 v[42:45], v[152:155], v[184:187], v[42:45]
	v_mfma_f32_16x16x32_bf16 v[46:49], v[144:147], v[184:187], v[46:49]
	v_mfma_f32_16x16x32_bf16 v[46:49], v[140:143], v[180:183], v[46:49]
	v_mfma_f32_16x16x32_bf16 v[30:33], v[140:143], v[188:191], v[30:33]
	v_mfma_f32_16x16x32_bf16 v[30:33], v[144:147], v[192:195], v[30:33]
	v_mfma_f32_16x16x32_bf16 v[26:29], v[152:155], v[192:195], v[26:29]
	v_mfma_f32_16x16x32_bf16 v[26:29], v[148:151], v[188:191], v[26:29]
	v_mfma_f32_16x16x32_bf16 v[10:13], v[148:151], v[198:201], v[10:13]
	v_mfma_f32_16x16x32_bf16 v[10:13], v[152:155], v[202:205], v[10:13]
	v_mfma_f32_16x16x32_bf16 v[14:17], v[144:147], v[202:205], v[14:17]
	v_mfma_f32_16x16x32_bf16 v[14:17], v[140:143], v[198:201], v[14:17]
	s_setprio 0
	s_setprio 1
	v_mfma_f32_16x16x32_bf16 v[54:57], v[156:159], v[172:175], v[54:57]
	v_mfma_f32_16x16x32_bf16 v[54:57], v[160:163], v[176:179], v[54:57]
	v_mfma_f32_16x16x32_bf16 v[50:53], v[168:171], v[176:179], v[50:53]
	v_mfma_f32_16x16x32_bf16 v[50:53], v[164:167], v[172:175], v[50:53]
	v_mfma_f32_16x16x32_bf16 v[34:37], v[164:167], v[180:183], v[34:37]
	v_mfma_f32_16x16x32_bf16 v[34:37], v[168:171], v[184:187], v[34:37]
	v_mfma_f32_16x16x32_bf16 v[38:41], v[160:163], v[184:187], v[38:41]
	v_mfma_f32_16x16x32_bf16 v[38:41], v[156:159], v[180:183], v[38:41]
	v_mfma_f32_16x16x32_bf16 v[22:25], v[156:159], v[188:191], v[22:25]
	v_mfma_f32_16x16x32_bf16 v[22:25], v[160:163], v[192:195], v[22:25]
	v_mfma_f32_16x16x32_bf16 v[18:21], v[168:171], v[192:195], v[18:21]
	v_mfma_f32_16x16x32_bf16 v[18:21], v[164:167], v[188:191], v[18:21]
	v_mfma_f32_16x16x32_bf16 v[2:5], v[164:167], v[198:201], v[2:5]
	v_mfma_f32_16x16x32_bf16 v[2:5], v[168:171], v[202:205], v[2:5]
	v_mfma_f32_16x16x32_bf16 v[6:9], v[160:163], v[202:205], v[6:9]
	v_mfma_f32_16x16x32_bf16 v[6:9], v[156:159], v[198:201], v[6:9]
	s_setprio 0
	s_barrier
	s_add_i32 s44, 0, 0x18000
	s_add_i32 s61, 0, 0x1c000
	v_add_u32_e32 v152, s44, v137
	v_add_u32_e32 v168, s61, v137
	ds_read_b128 v[140:143], v152
	ds_read_b128 v[144:147], v152 offset:1024
	ds_read_b128 v[148:151], v152 offset:2048
	ds_read_b128 v[152:155], v152 offset:3072
	ds_read_b128 v[156:159], v168
	ds_read_b128 v[160:163], v168 offset:1024
	ds_read_b128 v[164:167], v168 offset:2048
	ds_read_b128 v[168:171], v168 offset:3072
	s_add_u32 s38, s38, 0x80000
	s_addc_u32 s39, s39, 0
	s_mov_b32 m0, s40
	v_lshl_add_u64 v[214:215], s[38:39], 0, v[130:131]
	ds_read_b128 v[172:175], v139 offset:32768
	ds_read_b128 v[176:179], v139 offset:33792
	ds_read_b128 v[180:183], v139 offset:34816
	ds_read_b128 v[184:187], v139 offset:35840
	ds_read_b128 v[188:191], v139 offset:36864
	ds_read_b128 v[192:195], v139 offset:37888
	ds_read_b128 v[198:201], v139 offset:38912
	ds_read_b128 v[202:205], v139 offset:39936
	global_load_lds_dwordx4 v[214:215], off
	v_lshl_add_u64 v[214:215], s[38:39], 0, v[132:133]
	s_mov_b32 m0, s41
	s_nop 0
	global_load_lds_dwordx4 v[214:215], off
	s_waitcnt vmcnt(8)
	s_waitcnt lgkmcnt(0)
	s_barrier
	s_setprio 1
	s_waitcnt lgkmcnt(0)
	v_mfma_f32_16x16x32_bf16 v[126:129], v[140:143], v[172:175], v[126:129]
	v_mfma_f32_16x16x32_bf16 v[126:129], v[144:147], v[176:179], v[126:129]
	v_mfma_f32_16x16x32_bf16 v[122:125], v[152:155], v[176:179], v[122:125]
	v_mfma_f32_16x16x32_bf16 v[122:125], v[148:151], v[172:175], v[122:125]
	v_mfma_f32_16x16x32_bf16 v[106:109], v[148:151], v[180:183], v[106:109]
	v_mfma_f32_16x16x32_bf16 v[106:109], v[152:155], v[184:187], v[106:109]
	v_mfma_f32_16x16x32_bf16 v[110:113], v[144:147], v[184:187], v[110:113]
	v_mfma_f32_16x16x32_bf16 v[110:113], v[140:143], v[180:183], v[110:113]
	v_mfma_f32_16x16x32_bf16 v[94:97], v[140:143], v[188:191], v[94:97]
	v_mfma_f32_16x16x32_bf16 v[94:97], v[144:147], v[192:195], v[94:97]
	v_mfma_f32_16x16x32_bf16 v[90:93], v[152:155], v[192:195], v[90:93]
	v_mfma_f32_16x16x32_bf16 v[90:93], v[148:151], v[188:191], v[90:93]
	v_mfma_f32_16x16x32_bf16 v[74:77], v[148:151], v[198:201], v[74:77]
	v_mfma_f32_16x16x32_bf16 v[74:77], v[152:155], v[202:205], v[74:77]
	v_mfma_f32_16x16x32_bf16 v[78:81], v[144:147], v[202:205], v[78:81]
	v_mfma_f32_16x16x32_bf16 v[78:81], v[140:143], v[198:201], v[78:81]
	s_setprio 0
	s_setprio 1
	v_mfma_f32_16x16x32_bf16 v[118:121], v[156:159], v[172:175], v[118:121]
	v_mfma_f32_16x16x32_bf16 v[118:121], v[160:163], v[176:179], v[118:121]
	v_mfma_f32_16x16x32_bf16 v[114:117], v[168:171], v[176:179], v[114:117]
	v_mfma_f32_16x16x32_bf16 v[114:117], v[164:167], v[172:175], v[114:117]
	v_mfma_f32_16x16x32_bf16 v[98:101], v[164:167], v[180:183], v[98:101]
	v_mfma_f32_16x16x32_bf16 v[98:101], v[168:171], v[184:187], v[98:101]
	v_mfma_f32_16x16x32_bf16 v[102:105], v[160:163], v[184:187], v[102:105]
	v_mfma_f32_16x16x32_bf16 v[102:105], v[156:159], v[180:183], v[102:105]
	v_mfma_f32_16x16x32_bf16 v[86:89], v[156:159], v[188:191], v[86:89]
	v_mfma_f32_16x16x32_bf16 v[86:89], v[160:163], v[192:195], v[86:89]
	v_mfma_f32_16x16x32_bf16 v[82:85], v[168:171], v[192:195], v[82:85]
	v_mfma_f32_16x16x32_bf16 v[82:85], v[164:167], v[188:191], v[82:85]
	v_mfma_f32_16x16x32_bf16 v[66:69], v[164:167], v[198:201], v[66:69]
	v_mfma_f32_16x16x32_bf16 v[66:69], v[168:171], v[202:205], v[66:69]
	v_mfma_f32_16x16x32_bf16 v[70:73], v[160:163], v[202:205], v[70:73]
	v_mfma_f32_16x16x32_bf16 v[70:73], v[156:159], v[198:201], v[70:73]
	s_setprio 0
	s_barrier
	s_add_i32 s38, s44, s9
	v_lshl_add_u64 v[206:207], v[206:207], 0, s[2:3]
	s_mov_b32 m0, s38
	ds_read_b128 v[172:175], v139 offset:49152
	ds_read_b128 v[176:179], v139 offset:50176
	ds_read_b128 v[180:183], v139 offset:51200
	ds_read_b128 v[184:187], v139 offset:52224
	ds_read_b128 v[188:191], v139 offset:53248
	ds_read_b128 v[192:195], v139 offset:54272
	ds_read_b128 v[198:201], v139 offset:55296
	ds_read_b128 v[202:205], v139 offset:56320
	global_load_lds_dwordx4 v[206:207], off
	s_add_i32 m0, s38, 0x2000
	s_add_u32 s34, s34, 0x80080
	v_lshl_add_u64 v[206:207], v[208:209], 0, s[2:3]
	s_addc_u32 s35, s35, 0
	s_add_i32 s38, s61, s9
	global_load_lds_dwordx4 v[206:207], off
	v_lshl_add_u64 v[206:207], s[34:35], 0, v[196:197]
	s_mov_b32 m0, s38
	s_nop 0
	global_load_lds_dwordx4 v[206:207], off
	v_lshl_add_u64 v[206:207], s[34:35], 0, v[134:135]
	s_add_i32 m0, s38, 0x2000
	s_nop 0
	global_load_lds_dwordx4 v[206:207], off
	v_lshl_add_u64 v[206:207], v[210:211], 0, s[2:3]
	s_mov_b32 m0, s50
	s_nop 0
	global_load_lds_dwordx4 v[206:207], off
	v_lshl_add_u64 v[206:207], v[212:213], 0, s[2:3]
	s_mov_b32 m0, s51
	s_nop 0
	global_load_lds_dwordx4 v[206:207], off
	s_waitcnt vmcnt(8)
	s_waitcnt lgkmcnt(0)
	s_barrier
	s_setprio 1
	s_waitcnt lgkmcnt(0)
	v_mfma_f32_16x16x32_bf16 v[62:65], v[140:143], v[172:175], v[62:65]
	v_mfma_f32_16x16x32_bf16 v[62:65], v[144:147], v[176:179], v[62:65]
	v_mfma_f32_16x16x32_bf16 v[58:61], v[152:155], v[176:179], v[58:61]
	v_mfma_f32_16x16x32_bf16 v[58:61], v[148:151], v[172:175], v[58:61]
	v_mfma_f32_16x16x32_bf16 v[42:45], v[148:151], v[180:183], v[42:45]
	v_mfma_f32_16x16x32_bf16 v[42:45], v[152:155], v[184:187], v[42:45]
	v_mfma_f32_16x16x32_bf16 v[46:49], v[144:147], v[184:187], v[46:49]
	v_mfma_f32_16x16x32_bf16 v[46:49], v[140:143], v[180:183], v[46:49]
	v_mfma_f32_16x16x32_bf16 v[30:33], v[140:143], v[188:191], v[30:33]
	v_mfma_f32_16x16x32_bf16 v[30:33], v[144:147], v[192:195], v[30:33]
	v_mfma_f32_16x16x32_bf16 v[26:29], v[152:155], v[192:195], v[26:29]
	v_mfma_f32_16x16x32_bf16 v[26:29], v[148:151], v[188:191], v[26:29]
	v_mfma_f32_16x16x32_bf16 v[10:13], v[148:151], v[198:201], v[10:13]
	v_mfma_f32_16x16x32_bf16 v[10:13], v[152:155], v[202:205], v[10:13]
	v_mfma_f32_16x16x32_bf16 v[14:17], v[144:147], v[202:205], v[14:17]
	v_mfma_f32_16x16x32_bf16 v[14:17], v[140:143], v[198:201], v[14:17]
	s_setprio 0
	s_setprio 1
	v_mfma_f32_16x16x32_bf16 v[54:57], v[156:159], v[172:175], v[54:57]
	v_mfma_f32_16x16x32_bf16 v[54:57], v[160:163], v[176:179], v[54:57]
	v_mfma_f32_16x16x32_bf16 v[50:53], v[168:171], v[176:179], v[50:53]
	v_mfma_f32_16x16x32_bf16 v[50:53], v[164:167], v[172:175], v[50:53]
	v_mfma_f32_16x16x32_bf16 v[34:37], v[164:167], v[180:183], v[34:37]
	v_mfma_f32_16x16x32_bf16 v[34:37], v[168:171], v[184:187], v[34:37]
	v_mfma_f32_16x16x32_bf16 v[38:41], v[160:163], v[184:187], v[38:41]
	v_mfma_f32_16x16x32_bf16 v[38:41], v[156:159], v[180:183], v[38:41]
	v_mfma_f32_16x16x32_bf16 v[22:25], v[156:159], v[188:191], v[22:25]
	v_mfma_f32_16x16x32_bf16 v[22:25], v[160:163], v[192:195], v[22:25]
	v_mfma_f32_16x16x32_bf16 v[18:21], v[168:171], v[192:195], v[18:21]
	v_mfma_f32_16x16x32_bf16 v[18:21], v[164:167], v[188:191], v[18:21]
	v_mfma_f32_16x16x32_bf16 v[2:5], v[164:167], v[198:201], v[2:5]
	v_mfma_f32_16x16x32_bf16 v[2:5], v[168:171], v[202:205], v[2:5]
	v_mfma_f32_16x16x32_bf16 v[6:9], v[160:163], v[202:205], v[6:9]
	v_mfma_f32_16x16x32_bf16 v[6:9], v[156:159], v[198:201], v[6:9]
	s_setprio 0
	s_barrier
	s_add_i32 s38, s60, 2
	s_cmp_ge_i32 s60, s57
	s_mov_b64 s[34:35], s[36:37]
	s_mov_b32 s60, s38
	s_cbranch_scc0 .LBB0_783

.LBB0_962:
	s_add_u32 s1, s18, 0x100
	s_addc_u32 s7, s19, 0
	s_mov_b32 s22, -2
	s_mov_b64 s[18:19], 0
	s_add_i32 s43, s22, 2
	s_lshr_b32 s44, s43, 2
	s_add_i32 s20, s22, 4
	s_lshl_b64 s[50:51], s[44:45], 9
	s_lshr_b32 s44, s20, 2
	s_and_b32 s47, s18, 0x100
	s_lshl_b64 s[20:21], s[44:45], 9
	s_add_u32 s23, s12, s20
	s_addc_u32 s44, s13, s21
	s_add_u32 s20, s18, 0x100
	s_addc_u32 s21, s19, 0
	s_and_b32 s49, s20, 0x100
	s_add_u32 s49, s23, s49
	s_addc_u32 s23, s44, 0
	s_add_u32 s18, s1, s18
	s_addc_u32 s19, s7, s19
	s_add_i32 s44, 0, 0x10000
	s_add_u32 s50, s12, s50
	s_addc_u32 s51, s13, s51
	s_cmp_eq_u32 s22, 28
	s_cselect_b32 s23, s15, s23
	s_cselect_b32 s22, s14, s49
	v_add_u32_e32 v138, s44, v140
	s_cselect_b32 s19, s17, s19
	s_cselect_b32 s18, s16, s18
	s_add_i32 s49, 0, 0x14000
	ds_read_b128 v[142:145], v138
	ds_read_b128 v[146:149], v138 offset:1024
	ds_read_b128 v[150:153], v138 offset:2048
	ds_read_b128 v[154:157], v138 offset:3072
	v_add_u32_e32 v138, s49, v140
	ds_read_b128 v[158:161], v138
	ds_read_b128 v[162:165], v138 offset:1024
	ds_read_b128 v[166:169], v138 offset:2048
	ds_read_b128 v[170:173], v138 offset:3072
	s_add_u32 s47, s50, s47
	s_addc_u32 s51, s51, 0
	s_add_u32 s50, s47, 0x80080
	s_addc_u32 s51, s51, 0
	v_lshl_add_u64 v[138:139], s[50:51], 0, v[134:135]
	s_add_i32 m0, s33, 0xc000
	ds_read_b128 v[174:177], v141
	ds_read_b128 v[178:181], v141 offset:1024
	ds_read_b128 v[182:185], v141 offset:2048
	ds_read_b128 v[186:189], v141 offset:3072
	ds_read_b128 v[190:193], v141 offset:4096
	ds_read_b128 v[198:201], v141 offset:5120
	ds_read_b128 v[202:205], v141 offset:6144
	ds_read_b128 v[206:209], v141 offset:7168
	global_load_lds_dwordx4 v[138:139], off
	v_lshl_add_u64 v[138:139], s[50:51], 0, v[132:133]
	s_add_i32 m0, s33, 0xe000
	s_nop 0
	global_load_lds_dwordx4 v[138:139], off
	s_waitcnt vmcnt(8)
	s_waitcnt lgkmcnt(0)
	s_barrier
	s_setprio 1
	s_waitcnt lgkmcnt(0)
	v_mfma_f32_16x16x32_bf16 v[126:129], v[142:145], v[174:177], 0
	v_mfma_f32_16x16x32_bf16 v[126:129], v[146:149], v[178:181], v[126:129]
	v_mfma_f32_16x16x32_bf16 v[122:125], v[154:157], v[178:181], 0
	v_mfma_f32_16x16x32_bf16 v[122:125], v[150:153], v[174:177], v[122:125]
	v_mfma_f32_16x16x32_bf16 v[106:109], v[150:153], v[182:185], 0
	v_mfma_f32_16x16x32_bf16 v[106:109], v[154:157], v[186:189], v[106:109]
	v_mfma_f32_16x16x32_bf16 v[110:113], v[146:149], v[186:189], 0
	v_mfma_f32_16x16x32_bf16 v[110:113], v[142:145], v[182:185], v[110:113]
	v_mfma_f32_16x16x32_bf16 v[94:97], v[142:145], v[190:193], 0
	v_mfma_f32_16x16x32_bf16 v[94:97], v[146:149], v[198:201], v[94:97]
	v_mfma_f32_16x16x32_bf16 v[90:93], v[154:157], v[198:201], 0
	v_mfma_f32_16x16x32_bf16 v[90:93], v[150:153], v[190:193], v[90:93]
	v_mfma_f32_16x16x32_bf16 v[74:77], v[150:153], v[202:205], 0
	v_mfma_f32_16x16x32_bf16 v[74:77], v[154:157], v[206:209], v[74:77]
	v_mfma_f32_16x16x32_bf16 v[78:81], v[146:149], v[206:209], 0
	v_mfma_f32_16x16x32_bf16 v[78:81], v[142:145], v[202:205], v[78:81]
	s_setprio 0
	s_setprio 1
	v_mfma_f32_16x16x32_bf16 v[118:121], v[158:161], v[174:177], 0
	v_mfma_f32_16x16x32_bf16 v[118:121], v[162:165], v[178:181], v[118:121]
	v_mfma_f32_16x16x32_bf16 v[114:117], v[170:173], v[178:181], 0
	v_mfma_f32_16x16x32_bf16 v[114:117], v[166:169], v[174:177], v[114:117]
	v_mfma_f32_16x16x32_bf16 v[98:101], v[166:169], v[182:185], 0
	v_mfma_f32_16x16x32_bf16 v[98:101], v[170:173], v[186:189], v[98:101]
	v_mfma_f32_16x16x32_bf16 v[102:105], v[162:165], v[186:189], 0
	v_mfma_f32_16x16x32_bf16 v[102:105], v[158:161], v[182:185], v[102:105]
	v_mfma_f32_16x16x32_bf16 v[86:89], v[158:161], v[190:193], 0
	v_mfma_f32_16x16x32_bf16 v[86:89], v[162:165], v[198:201], v[86:89]
	v_mfma_f32_16x16x32_bf16 v[82:85], v[170:173], v[198:201], 0
	v_mfma_f32_16x16x32_bf16 v[82:85], v[166:169], v[190:193], v[82:85]
	v_mfma_f32_16x16x32_bf16 v[66:69], v[166:169], v[202:205], 0
	v_mfma_f32_16x16x32_bf16 v[66:69], v[170:173], v[206:209], v[66:69]
	v_mfma_f32_16x16x32_bf16 v[70:73], v[162:165], v[206:209], 0
	v_mfma_f32_16x16x32_bf16 v[70:73], v[158:161], v[202:205], v[70:73]
	s_setprio 0
	s_barrier
	s_add_i32 s44, s44, s31
	v_lshl_add_u64 v[138:139], s[18:19], 0, v[196:197]
	s_mov_b32 m0, s44
	ds_read_b128 v[174:177], v141 offset:16384
	ds_read_b128 v[178:181], v141 offset:17408
	ds_read_b128 v[182:185], v141 offset:18432
	ds_read_b128 v[186:189], v141 offset:19456
	ds_read_b128 v[190:193], v141 offset:20480
	ds_read_b128 v[198:201], v141 offset:21504
	ds_read_b128 v[202:205], v141 offset:22528
	ds_read_b128 v[206:209], v141 offset:23552
	global_load_lds_dwordx4 v[138:139], off
	s_add_i32 m0, s44, 0x2000
	s_add_u32 s50, s18, 0x80000
	v_lshl_add_u64 v[194:195], s[18:19], 0, v[130:131]
	s_addc_u32 s51, s19, 0
	s_add_i32 s44, s49, s31
	global_load_lds_dwordx4 v[194:195], off
	v_lshl_add_u64 v[210:211], s[50:51], 0, v[196:197]
	s_mov_b32 m0, s44
	v_lshl_add_u64 v[212:213], s[22:23], 0, v[132:133]
	global_load_lds_dwordx4 v[210:211], off
	v_lshl_add_u64 v[210:211], s[50:51], 0, v[130:131]
	s_add_i32 m0, s44, 0x2000
	s_nop 0
	global_load_lds_dwordx4 v[210:211], off
	v_lshl_add_u64 v[210:211], s[22:23], 0, v[134:135]
	s_mov_b32 m0, s33
	s_nop 0
	global_load_lds_dwordx4 v[210:211], off
	s_mov_b32 m0, s34
	s_nop 0
	global_load_lds_dwordx4 v[212:213], off
	s_waitcnt vmcnt(8)
	s_waitcnt lgkmcnt(0)
	s_barrier
	s_setprio 1
	s_waitcnt lgkmcnt(0)
	v_mfma_f32_16x16x32_bf16 v[62:65], v[142:145], v[174:177], 0
	v_mfma_f32_16x16x32_bf16 v[62:65], v[146:149], v[178:181], v[62:65]
	v_mfma_f32_16x16x32_bf16 v[58:61], v[154:157], v[178:181], 0
	v_mfma_f32_16x16x32_bf16 v[58:61], v[150:153], v[174:177], v[58:61]
	v_mfma_f32_16x16x32_bf16 v[42:45], v[150:153], v[182:185], 0
	v_mfma_f32_16x16x32_bf16 v[42:45], v[154:157], v[186:189], v[42:45]
	v_mfma_f32_16x16x32_bf16 v[46:49], v[146:149], v[186:189], 0
	v_mfma_f32_16x16x32_bf16 v[46:49], v[142:145], v[182:185], v[46:49]
	v_mfma_f32_16x16x32_bf16 v[30:33], v[142:145], v[190:193], 0
	v_mfma_f32_16x16x32_bf16 v[30:33], v[146:149], v[198:201], v[30:33]
	v_mfma_f32_16x16x32_bf16 v[26:29], v[154:157], v[198:201], 0
	v_mfma_f32_16x16x32_bf16 v[26:29], v[150:153], v[190:193], v[26:29]
	v_mfma_f32_16x16x32_bf16 v[10:13], v[150:153], v[202:205], 0
	v_mfma_f32_16x16x32_bf16 v[10:13], v[154:157], v[206:209], v[10:13]
	v_mfma_f32_16x16x32_bf16 v[14:17], v[146:149], v[206:209], 0
	v_mfma_f32_16x16x32_bf16 v[14:17], v[142:145], v[202:205], v[14:17]
	s_setprio 0
	s_setprio 1
	v_mfma_f32_16x16x32_bf16 v[54:57], v[158:161], v[174:177], 0
	v_mfma_f32_16x16x32_bf16 v[54:57], v[162:165], v[178:181], v[54:57]
	v_mfma_f32_16x16x32_bf16 v[50:53], v[170:173], v[178:181], 0
	v_mfma_f32_16x16x32_bf16 v[50:53], v[166:169], v[174:177], v[50:53]
	v_mfma_f32_16x16x32_bf16 v[34:37], v[166:169], v[182:185], 0
	v_mfma_f32_16x16x32_bf16 v[34:37], v[170:173], v[186:189], v[34:37]
	v_mfma_f32_16x16x32_bf16 v[38:41], v[162:165], v[186:189], 0
	v_mfma_f32_16x16x32_bf16 v[38:41], v[158:161], v[182:185], v[38:41]
	v_mfma_f32_16x16x32_bf16 v[22:25], v[158:161], v[190:193], 0
	v_mfma_f32_16x16x32_bf16 v[22:25], v[162:165], v[198:201], v[22:25]
	v_mfma_f32_16x16x32_bf16 v[18:21], v[170:173], v[198:201], 0
	v_mfma_f32_16x16x32_bf16 v[18:21], v[166:169], v[190:193], v[18:21]
	v_mfma_f32_16x16x32_bf16 v[2:5], v[166:169], v[202:205], 0
	v_mfma_f32_16x16x32_bf16 v[2:5], v[170:173], v[206:209], v[2:5]
	v_mfma_f32_16x16x32_bf16 v[6:9], v[162:165], v[206:209], 0
	v_mfma_f32_16x16x32_bf16 v[6:9], v[158:161], v[202:205], v[6:9]
	s_setprio 0
	s_barrier
	s_add_i32 s44, 0, 0x18000
	s_add_i32 s47, 0, 0x1c000
	v_add_u32_e32 v154, s44, v140
	v_add_u32_e32 v170, s47, v140
	ds_read_b128 v[142:145], v154
	ds_read_b128 v[146:149], v154 offset:1024
	ds_read_b128 v[150:153], v154 offset:2048
	ds_read_b128 v[154:157], v154 offset:3072
	ds_read_b128 v[158:161], v170
	ds_read_b128 v[162:165], v170 offset:1024
	ds_read_b128 v[166:169], v170 offset:2048
	ds_read_b128 v[170:173], v170 offset:3072
	s_add_u32 s22, s22, 0x80000
	s_addc_u32 s23, s23, 0
	s_mov_b32 m0, s35
	v_lshl_add_u64 v[214:215], s[22:23], 0, v[134:135]
	ds_read_b128 v[174:177], v141 offset:32768
	ds_read_b128 v[178:181], v141 offset:33792
	ds_read_b128 v[182:185], v141 offset:34816
	ds_read_b128 v[186:189], v141 offset:35840
	ds_read_b128 v[190:193], v141 offset:36864
	ds_read_b128 v[198:201], v141 offset:37888
	ds_read_b128 v[202:205], v141 offset:38912
	ds_read_b128 v[206:209], v141 offset:39936
	global_load_lds_dwordx4 v[214:215], off
	v_lshl_add_u64 v[214:215], s[22:23], 0, v[132:133]
	s_mov_b32 m0, s36
	s_nop 0
	global_load_lds_dwordx4 v[214:215], off
	s_waitcnt vmcnt(8)
	s_waitcnt lgkmcnt(0)
	s_barrier
	s_setprio 1
	s_waitcnt lgkmcnt(0)
	v_mfma_f32_16x16x32_bf16 v[126:129], v[142:145], v[174:177], v[126:129]
	v_mfma_f32_16x16x32_bf16 v[126:129], v[146:149], v[178:181], v[126:129]
	v_mfma_f32_16x16x32_bf16 v[122:125], v[154:157], v[178:181], v[122:125]
	v_mfma_f32_16x16x32_bf16 v[122:125], v[150:153], v[174:177], v[122:125]
	v_mfma_f32_16x16x32_bf16 v[106:109], v[150:153], v[182:185], v[106:109]
	v_mfma_f32_16x16x32_bf16 v[106:109], v[154:157], v[186:189], v[106:109]
	v_mfma_f32_16x16x32_bf16 v[110:113], v[146:149], v[186:189], v[110:113]
	v_mfma_f32_16x16x32_bf16 v[110:113], v[142:145], v[182:185], v[110:113]
	v_mfma_f32_16x16x32_bf16 v[94:97], v[142:145], v[190:193], v[94:97]
	v_mfma_f32_16x16x32_bf16 v[94:97], v[146:149], v[198:201], v[94:97]
	v_mfma_f32_16x16x32_bf16 v[90:93], v[154:157], v[198:201], v[90:93]
	v_mfma_f32_16x16x32_bf16 v[90:93], v[150:153], v[190:193], v[90:93]
	v_mfma_f32_16x16x32_bf16 v[74:77], v[150:153], v[202:205], v[74:77]
	v_mfma_f32_16x16x32_bf16 v[74:77], v[154:157], v[206:209], v[74:77]
	v_mfma_f32_16x16x32_bf16 v[78:81], v[146:149], v[206:209], v[78:81]
	v_mfma_f32_16x16x32_bf16 v[78:81], v[142:145], v[202:205], v[78:81]
	s_setprio 0
	s_setprio 1
	v_mfma_f32_16x16x32_bf16 v[118:121], v[158:161], v[174:177], v[118:121]
	v_mfma_f32_16x16x32_bf16 v[118:121], v[162:165], v[178:181], v[118:121]
	v_mfma_f32_16x16x32_bf16 v[114:117], v[170:173], v[178:181], v[114:117]
	v_mfma_f32_16x16x32_bf16 v[114:117], v[166:169], v[174:177], v[114:117]
	v_mfma_f32_16x16x32_bf16 v[98:101], v[166:169], v[182:185], v[98:101]
	v_mfma_f32_16x16x32_bf16 v[98:101], v[170:173], v[186:189], v[98:101]
	v_mfma_f32_16x16x32_bf16 v[102:105], v[162:165], v[186:189], v[102:105]
	v_mfma_f32_16x16x32_bf16 v[102:105], v[158:161], v[182:185], v[102:105]
	v_mfma_f32_16x16x32_bf16 v[86:89], v[158:161], v[190:193], v[86:89]
	v_mfma_f32_16x16x32_bf16 v[86:89], v[162:165], v[198:201], v[86:89]
	v_mfma_f32_16x16x32_bf16 v[82:85], v[170:173], v[198:201], v[82:85]
	v_mfma_f32_16x16x32_bf16 v[82:85], v[166:169], v[190:193], v[82:85]
	v_mfma_f32_16x16x32_bf16 v[66:69], v[166:169], v[202:205], v[66:69]
	v_mfma_f32_16x16x32_bf16 v[66:69], v[170:173], v[206:209], v[66:69]
	v_mfma_f32_16x16x32_bf16 v[70:73], v[162:165], v[206:209], v[70:73]
	v_mfma_f32_16x16x32_bf16 v[70:73], v[158:161], v[202:205], v[70:73]
	s_setprio 0
	s_barrier
	s_add_i32 s22, s44, s31
	v_lshl_add_u64 v[138:139], v[138:139], 0, s[2:3]
	s_mov_b32 m0, s22
	ds_read_b128 v[174:177], v141 offset:49152
	ds_read_b128 v[178:181], v141 offset:50176
	ds_read_b128 v[182:185], v141 offset:51200
	ds_read_b128 v[186:189], v141 offset:52224
	ds_read_b128 v[190:193], v141 offset:53248
	ds_read_b128 v[198:201], v141 offset:54272
	ds_read_b128 v[202:205], v141 offset:55296
	ds_read_b128 v[206:209], v141 offset:56320
	global_load_lds_dwordx4 v[138:139], off
	s_add_i32 m0, s22, 0x2000
	s_add_u32 s18, s18, 0x80080
	v_lshl_add_u64 v[138:139], v[194:195], 0, s[2:3]
	s_addc_u32 s19, s19, 0
	s_add_i32 s22, s47, s31
	global_load_lds_dwordx4 v[138:139], off
	v_lshl_add_u64 v[138:139], s[18:19], 0, v[196:197]
	s_mov_b32 m0, s22
	s_nop 0
	global_load_lds_dwordx4 v[138:139], off
	v_lshl_add_u64 v[138:139], s[18:19], 0, v[130:131]
	s_add_i32 m0, s22, 0x2000
	s_nop 0
	global_load_lds_dwordx4 v[138:139], off
	v_lshl_add_u64 v[138:139], v[210:211], 0, s[2:3]
	s_mov_b32 m0, s37
	s_nop 0
	global_load_lds_dwordx4 v[138:139], off
	v_lshl_add_u64 v[138:139], v[212:213], 0, s[2:3]
	s_mov_b32 m0, s38
	s_nop 0
	global_load_lds_dwordx4 v[138:139], off
	s_waitcnt vmcnt(8)
	s_waitcnt lgkmcnt(0)
	s_barrier
	s_setprio 1
	s_waitcnt lgkmcnt(0)
	v_mfma_f32_16x16x32_bf16 v[62:65], v[142:145], v[174:177], v[62:65]
	v_mfma_f32_16x16x32_bf16 v[62:65], v[146:149], v[178:181], v[62:65]
	v_mfma_f32_16x16x32_bf16 v[58:61], v[154:157], v[178:181], v[58:61]
	v_mfma_f32_16x16x32_bf16 v[58:61], v[150:153], v[174:177], v[58:61]
	v_mfma_f32_16x16x32_bf16 v[42:45], v[150:153], v[182:185], v[42:45]
	v_mfma_f32_16x16x32_bf16 v[42:45], v[154:157], v[186:189], v[42:45]
	v_mfma_f32_16x16x32_bf16 v[46:49], v[146:149], v[186:189], v[46:49]
	v_mfma_f32_16x16x32_bf16 v[46:49], v[142:145], v[182:185], v[46:49]
	v_mfma_f32_16x16x32_bf16 v[30:33], v[142:145], v[190:193], v[30:33]
	v_mfma_f32_16x16x32_bf16 v[30:33], v[146:149], v[198:201], v[30:33]
	v_mfma_f32_16x16x32_bf16 v[26:29], v[154:157], v[198:201], v[26:29]
	v_mfma_f32_16x16x32_bf16 v[26:29], v[150:153], v[190:193], v[26:29]
	v_mfma_f32_16x16x32_bf16 v[10:13], v[150:153], v[202:205], v[10:13]
	v_mfma_f32_16x16x32_bf16 v[10:13], v[154:157], v[206:209], v[10:13]
	v_mfma_f32_16x16x32_bf16 v[14:17], v[146:149], v[206:209], v[14:17]
	v_mfma_f32_16x16x32_bf16 v[14:17], v[142:145], v[202:205], v[14:17]
	s_setprio 0
	s_setprio 1
	v_mfma_f32_16x16x32_bf16 v[54:57], v[158:161], v[174:177], v[54:57]
	v_mfma_f32_16x16x32_bf16 v[54:57], v[162:165], v[178:181], v[54:57]
	v_mfma_f32_16x16x32_bf16 v[50:53], v[170:173], v[178:181], v[50:53]
	v_mfma_f32_16x16x32_bf16 v[50:53], v[166:169], v[174:177], v[50:53]
	v_mfma_f32_16x16x32_bf16 v[34:37], v[166:169], v[182:185], v[34:37]
	v_mfma_f32_16x16x32_bf16 v[34:37], v[170:173], v[186:189], v[34:37]
	v_mfma_f32_16x16x32_bf16 v[38:41], v[162:165], v[186:189], v[38:41]
	v_mfma_f32_16x16x32_bf16 v[38:41], v[158:161], v[182:185], v[38:41]
	v_mfma_f32_16x16x32_bf16 v[22:25], v[158:161], v[190:193], v[22:25]
	v_mfma_f32_16x16x32_bf16 v[22:25], v[162:165], v[198:201], v[22:25]
	v_mfma_f32_16x16x32_bf16 v[18:21], v[170:173], v[198:201], v[18:21]
	v_mfma_f32_16x16x32_bf16 v[18:21], v[166:169], v[190:193], v[18:21]
	v_mfma_f32_16x16x32_bf16 v[2:5], v[166:169], v[202:205], v[2:5]
	v_mfma_f32_16x16x32_bf16 v[2:5], v[170:173], v[206:209], v[2:5]
	v_mfma_f32_16x16x32_bf16 v[6:9], v[162:165], v[206:209], v[6:9]
	v_mfma_f32_16x16x32_bf16 v[6:9], v[158:161], v[202:205], v[6:9]
	s_setprio 0
	s_barrier
	s_cmp_gt_u32 s43, 29
	s_mov_b64 s[18:19], s[20:21]
	s_mov_b32 s22, s43
	s_cbranch_scc1 .Lpeel_exit_w1
.LBB0_963:
	s_add_i32 s43, s22, 2
	s_lshr_b32 s44, s43, 2
	s_add_i32 s20, s22, 4
	s_lshl_b64 s[50:51], s[44:45], 9
	s_lshr_b32 s44, s20, 2
	s_and_b32 s47, s18, 0x100
	s_lshl_b64 s[20:21], s[44:45], 9
	s_add_u32 s23, s12, s20
	s_addc_u32 s44, s13, s21
	s_add_u32 s20, s18, 0x100
	s_addc_u32 s21, s19, 0
	s_and_b32 s49, s20, 0x100
	s_add_u32 s49, s23, s49
	s_addc_u32 s23, s44, 0
	s_add_u32 s18, s1, s18
	s_addc_u32 s19, s7, s19
	s_add_i32 s44, 0, 0x10000
	s_add_u32 s50, s12, s50
	s_addc_u32 s51, s13, s51
	s_cmp_eq_u32 s22, 28
	s_cselect_b32 s23, s15, s23
	s_cselect_b32 s22, s14, s49
	v_add_u32_e32 v138, s44, v140
	s_cselect_b32 s19, s17, s19
	s_cselect_b32 s18, s16, s18
	s_add_i32 s49, 0, 0x14000
	ds_read_b128 v[142:145], v138
	ds_read_b128 v[146:149], v138 offset:1024
	ds_read_b128 v[150:153], v138 offset:2048
	ds_read_b128 v[154:157], v138 offset:3072
	v_add_u32_e32 v138, s49, v140
	ds_read_b128 v[158:161], v138
	ds_read_b128 v[162:165], v138 offset:1024
	ds_read_b128 v[166:169], v138 offset:2048
	ds_read_b128 v[170:173], v138 offset:3072
	s_add_u32 s47, s50, s47
	s_addc_u32 s51, s51, 0
	s_add_u32 s50, s47, 0x80080
	s_addc_u32 s51, s51, 0
	v_lshl_add_u64 v[138:139], s[50:51], 0, v[134:135]
	s_add_i32 m0, s33, 0xc000
	ds_read_b128 v[174:177], v141
	ds_read_b128 v[178:181], v141 offset:1024
	ds_read_b128 v[182:185], v141 offset:2048
	ds_read_b128 v[186:189], v141 offset:3072
	ds_read_b128 v[190:193], v141 offset:4096
	ds_read_b128 v[198:201], v141 offset:5120
	ds_read_b128 v[202:205], v141 offset:6144
	ds_read_b128 v[206:209], v141 offset:7168
	global_load_lds_dwordx4 v[138:139], off
	v_lshl_add_u64 v[138:139], s[50:51], 0, v[132:133]
	s_add_i32 m0, s33, 0xe000
	s_nop 0
	global_load_lds_dwordx4 v[138:139], off
	s_waitcnt vmcnt(8)
	s_waitcnt lgkmcnt(0)
	s_barrier
	s_setprio 1
	s_waitcnt lgkmcnt(0)
	v_mfma_f32_16x16x32_bf16 v[126:129], v[142:145], v[174:177], v[126:129]
	v_mfma_f32_16x16x32_bf16 v[126:129], v[146:149], v[178:181], v[126:129]
	v_mfma_f32_16x16x32_bf16 v[122:125], v[154:157], v[178:181], v[122:125]
	v_mfma_f32_16x16x32_bf16 v[122:125], v[150:153], v[174:177], v[122:125]
	v_mfma_f32_16x16x32_bf16 v[106:109], v[150:153], v[182:185], v[106:109]
	v_mfma_f32_16x16x32_bf16 v[106:109], v[154:157], v[186:189], v[106:109]
	v_mfma_f32_16x16x32_bf16 v[110:113], v[146:149], v[186:189], v[110:113]
	v_mfma_f32_16x16x32_bf16 v[110:113], v[142:145], v[182:185], v[110:113]
	v_mfma_f32_16x16x32_bf16 v[94:97], v[142:145], v[190:193], v[94:97]
	v_mfma_f32_16x16x32_bf16 v[94:97], v[146:149], v[198:201], v[94:97]
	v_mfma_f32_16x16x32_bf16 v[90:93], v[154:157], v[198:201], v[90:93]
	v_mfma_f32_16x16x32_bf16 v[90:93], v[150:153], v[190:193], v[90:93]
	v_mfma_f32_16x16x32_bf16 v[74:77], v[150:153], v[202:205], v[74:77]
	v_mfma_f32_16x16x32_bf16 v[74:77], v[154:157], v[206:209], v[74:77]
	v_mfma_f32_16x16x32_bf16 v[78:81], v[146:149], v[206:209], v[78:81]
	v_mfma_f32_16x16x32_bf16 v[78:81], v[142:145], v[202:205], v[78:81]
	s_setprio 0
	s_setprio 1
	v_mfma_f32_16x16x32_bf16 v[118:121], v[158:161], v[174:177], v[118:121]
	v_mfma_f32_16x16x32_bf16 v[118:121], v[162:165], v[178:181], v[118:121]
	v_mfma_f32_16x16x32_bf16 v[114:117], v[170:173], v[178:181], v[114:117]
	v_mfma_f32_16x16x32_bf16 v[114:117], v[166:169], v[174:177], v[114:117]
	v_mfma_f32_16x16x32_bf16 v[98:101], v[166:169], v[182:185], v[98:101]
	v_mfma_f32_16x16x32_bf16 v[98:101], v[170:173], v[186:189], v[98:101]
	v_mfma_f32_16x16x32_bf16 v[102:105], v[162:165], v[186:189], v[102:105]
	v_mfma_f32_16x16x32_bf16 v[102:105], v[158:161], v[182:185], v[102:105]
	v_mfma_f32_16x16x32_bf16 v[86:89], v[158:161], v[190:193], v[86:89]
	v_mfma_f32_16x16x32_bf16 v[86:89], v[162:165], v[198:201], v[86:89]
	v_mfma_f32_16x16x32_bf16 v[82:85], v[170:173], v[198:201], v[82:85]
	v_mfma_f32_16x16x32_bf16 v[82:85], v[166:169], v[190:193], v[82:85]
	v_mfma_f32_16x16x32_bf16 v[66:69], v[166:169], v[202:205], v[66:69]
	v_mfma_f32_16x16x32_bf16 v[66:69], v[170:173], v[206:209], v[66:69]
	v_mfma_f32_16x16x32_bf16 v[70:73], v[162:165], v[206:209], v[70:73]
	v_mfma_f32_16x16x32_bf16 v[70:73], v[158:161], v[202:205], v[70:73]
	s_setprio 0
	s_barrier
	s_add_i32 s44, s44, s31
	v_lshl_add_u64 v[138:139], s[18:19], 0, v[196:197]
	s_mov_b32 m0, s44
	ds_read_b128 v[174:177], v141 offset:16384
	ds_read_b128 v[178:181], v141 offset:17408
	ds_read_b128 v[182:185], v141 offset:18432
	ds_read_b128 v[186:189], v141 offset:19456
	ds_read_b128 v[190:193], v141 offset:20480
	ds_read_b128 v[198:201], v141 offset:21504
	ds_read_b128 v[202:205], v141 offset:22528
	ds_read_b128 v[206:209], v141 offset:23552
	global_load_lds_dwordx4 v[138:139], off
	s_add_i32 m0, s44, 0x2000
	s_add_u32 s50, s18, 0x80000
	v_lshl_add_u64 v[194:195], s[18:19], 0, v[130:131]
	s_addc_u32 s51, s19, 0
	s_add_i32 s44, s49, s31
	global_load_lds_dwordx4 v[194:195], off
	v_lshl_add_u64 v[210:211], s[50:51], 0, v[196:197]
	s_mov_b32 m0, s44
	v_lshl_add_u64 v[212:213], s[22:23], 0, v[132:133]
	global_load_lds_dwordx4 v[210:211], off
	v_lshl_add_u64 v[210:211], s[50:51], 0, v[130:131]
	s_add_i32 m0, s44, 0x2000
	s_nop 0
	global_load_lds_dwordx4 v[210:211], off
	v_lshl_add_u64 v[210:211], s[22:23], 0, v[134:135]
	s_mov_b32 m0, s33
	s_nop 0
	global_load_lds_dwordx4 v[210:211], off
	s_mov_b32 m0, s34
	s_nop 0
	global_load_lds_dwordx4 v[212:213], off
	s_waitcnt vmcnt(8)
	s_waitcnt lgkmcnt(0)
	s_barrier
	s_setprio 1
	s_waitcnt lgkmcnt(0)
	v_mfma_f32_16x16x32_bf16 v[62:65], v[142:145], v[174:177], v[62:65]
	v_mfma_f32_16x16x32_bf16 v[62:65], v[146:149], v[178:181], v[62:65]
	v_mfma_f32_16x16x32_bf16 v[58:61], v[154:157], v[178:181], v[58:61]
	v_mfma_f32_16x16x32_bf16 v[58:61], v[150:153], v[174:177], v[58:61]
	v_mfma_f32_16x16x32_bf16 v[42:45], v[150:153], v[182:185], v[42:45]
	v_mfma_f32_16x16x32_bf16 v[42:45], v[154:157], v[186:189], v[42:45]
	v_mfma_f32_16x16x32_bf16 v[46:49], v[146:149], v[186:189], v[46:49]
	v_mfma_f32_16x16x32_bf16 v[46:49], v[142:145], v[182:185], v[46:49]
	v_mfma_f32_16x16x32_bf16 v[30:33], v[142:145], v[190:193], v[30:33]
	v_mfma_f32_16x16x32_bf16 v[30:33], v[146:149], v[198:201], v[30:33]
	v_mfma_f32_16x16x32_bf16 v[26:29], v[154:157], v[198:201], v[26:29]
	v_mfma_f32_16x16x32_bf16 v[26:29], v[150:153], v[190:193], v[26:29]
	v_mfma_f32_16x16x32_bf16 v[10:13], v[150:153], v[202:205], v[10:13]
	v_mfma_f32_16x16x32_bf16 v[10:13], v[154:157], v[206:209], v[10:13]
	v_mfma_f32_16x16x32_bf16 v[14:17], v[146:149], v[206:209], v[14:17]
	v_mfma_f32_16x16x32_bf16 v[14:17], v[142:145], v[202:205], v[14:17]
	s_setprio 0
	s_setprio 1
	v_mfma_f32_16x16x32_bf16 v[54:57], v[158:161], v[174:177], v[54:57]
	v_mfma_f32_16x16x32_bf16 v[54:57], v[162:165], v[178:181], v[54:57]
	v_mfma_f32_16x16x32_bf16 v[50:53], v[170:173], v[178:181], v[50:53]
	v_mfma_f32_16x16x32_bf16 v[50:53], v[166:169], v[174:177], v[50:53]
	v_mfma_f32_16x16x32_bf16 v[34:37], v[166:169], v[182:185], v[34:37]
	v_mfma_f32_16x16x32_bf16 v[34:37], v[170:173], v[186:189], v[34:37]
	v_mfma_f32_16x16x32_bf16 v[38:41], v[162:165], v[186:189], v[38:41]
	v_mfma_f32_16x16x32_bf16 v[38:41], v[158:161], v[182:185], v[38:41]
	v_mfma_f32_16x16x32_bf16 v[22:25], v[158:161], v[190:193], v[22:25]
	v_mfma_f32_16x16x32_bf16 v[22:25], v[162:165], v[198:201], v[22:25]
	v_mfma_f32_16x16x32_bf16 v[18:21], v[170:173], v[198:201], v[18:21]
	v_mfma_f32_16x16x32_bf16 v[18:21], v[166:169], v[190:193], v[18:21]
	v_mfma_f32_16x16x32_bf16 v[2:5], v[166:169], v[202:205], v[2:5]
	v_mfma_f32_16x16x32_bf16 v[2:5], v[170:173], v[206:209], v[2:5]
	v_mfma_f32_16x16x32_bf16 v[6:9], v[162:165], v[206:209], v[6:9]
	v_mfma_f32_16x16x32_bf16 v[6:9], v[158:161], v[202:205], v[6:9]
	s_setprio 0
	s_barrier
	s_add_i32 s44, 0, 0x18000
	s_add_i32 s47, 0, 0x1c000
	v_add_u32_e32 v154, s44, v140
	v_add_u32_e32 v170, s47, v140
	ds_read_b128 v[142:145], v154
	ds_read_b128 v[146:149], v154 offset:1024
	ds_read_b128 v[150:153], v154 offset:2048
	ds_read_b128 v[154:157], v154 offset:3072
	ds_read_b128 v[158:161], v170
	ds_read_b128 v[162:165], v170 offset:1024
	ds_read_b128 v[166:169], v170 offset:2048
	ds_read_b128 v[170:173], v170 offset:3072
	s_add_u32 s22, s22, 0x80000
	s_addc_u32 s23, s23, 0
	s_mov_b32 m0, s35
	v_lshl_add_u64 v[214:215], s[22:23], 0, v[134:135]
	ds_read_b128 v[174:177], v141 offset:32768
	ds_read_b128 v[178:181], v141 offset:33792
	ds_read_b128 v[182:185], v141 offset:34816
	ds_read_b128 v[186:189], v141 offset:35840
	ds_read_b128 v[190:193], v141 offset:36864
	ds_read_b128 v[198:201], v141 offset:37888
	ds_read_b128 v[202:205], v141 offset:38912
	ds_read_b128 v[206:209], v141 offset:39936
	global_load_lds_dwordx4 v[214:215], off
	v_lshl_add_u64 v[214:215], s[22:23], 0, v[132:133]
	s_mov_b32 m0, s36
	s_nop 0
	global_load_lds_dwordx4 v[214:215], off
	s_waitcnt vmcnt(8)
	s_waitcnt lgkmcnt(0)
	s_barrier
	s_setprio 1
	s_waitcnt lgkmcnt(0)
	v_mfma_f32_16x16x32_bf16 v[126:129], v[142:145], v[174:177], v[126:129]
	v_mfma_f32_16x16x32_bf16 v[126:129], v[146:149], v[178:181], v[126:129]
	v_mfma_f32_16x16x32_bf16 v[122:125], v[154:157], v[178:181], v[122:125]
	v_mfma_f32_16x16x32_bf16 v[122:125], v[150:153], v[174:177], v[122:125]
	v_mfma_f32_16x16x32_bf16 v[106:109], v[150:153], v[182:185], v[106:109]
	v_mfma_f32_16x16x32_bf16 v[106:109], v[154:157], v[186:189], v[106:109]
	v_mfma_f32_16x16x32_bf16 v[110:113], v[146:149], v[186:189], v[110:113]
	v_mfma_f32_16x16x32_bf16 v[110:113], v[142:145], v[182:185], v[110:113]
	v_mfma_f32_16x16x32_bf16 v[94:97], v[142:145], v[190:193], v[94:97]
	v_mfma_f32_16x16x32_bf16 v[94:97], v[146:149], v[198:201], v[94:97]
	v_mfma_f32_16x16x32_bf16 v[90:93], v[154:157], v[198:201], v[90:93]
	v_mfma_f32_16x16x32_bf16 v[90:93], v[150:153], v[190:193], v[90:93]
	v_mfma_f32_16x16x32_bf16 v[74:77], v[150:153], v[202:205], v[74:77]
	v_mfma_f32_16x16x32_bf16 v[74:77], v[154:157], v[206:209], v[74:77]
	v_mfma_f32_16x16x32_bf16 v[78:81], v[146:149], v[206:209], v[78:81]
	v_mfma_f32_16x16x32_bf16 v[78:81], v[142:145], v[202:205], v[78:81]
	s_setprio 0
	s_setprio 1
	v_mfma_f32_16x16x32_bf16 v[118:121], v[158:161], v[174:177], v[118:121]
	v_mfma_f32_16x16x32_bf16 v[118:121], v[162:165], v[178:181], v[118:121]
	v_mfma_f32_16x16x32_bf16 v[114:117], v[170:173], v[178:181], v[114:117]
	v_mfma_f32_16x16x32_bf16 v[114:117], v[166:169], v[174:177], v[114:117]
	v_mfma_f32_16x16x32_bf16 v[98:101], v[166:169], v[182:185], v[98:101]
	v_mfma_f32_16x16x32_bf16 v[98:101], v[170:173], v[186:189], v[98:101]
	v_mfma_f32_16x16x32_bf16 v[102:105], v[162:165], v[186:189], v[102:105]
	v_mfma_f32_16x16x32_bf16 v[102:105], v[158:161], v[182:185], v[102:105]
	v_mfma_f32_16x16x32_bf16 v[86:89], v[158:161], v[190:193], v[86:89]
	v_mfma_f32_16x16x32_bf16 v[86:89], v[162:165], v[198:201], v[86:89]
	v_mfma_f32_16x16x32_bf16 v[82:85], v[170:173], v[198:201], v[82:85]
	v_mfma_f32_16x16x32_bf16 v[82:85], v[166:169], v[190:193], v[82:85]
	v_mfma_f32_16x16x32_bf16 v[66:69], v[166:169], v[202:205], v[66:69]
	v_mfma_f32_16x16x32_bf16 v[66:69], v[170:173], v[206:209], v[66:69]
	v_mfma_f32_16x16x32_bf16 v[70:73], v[162:165], v[206:209], v[70:73]
	v_mfma_f32_16x16x32_bf16 v[70:73], v[158:161], v[202:205], v[70:73]
	s_setprio 0
	s_barrier
	s_add_i32 s22, s44, s31
	v_lshl_add_u64 v[138:139], v[138:139], 0, s[2:3]
	s_mov_b32 m0, s22
	ds_read_b128 v[174:177], v141 offset:49152
	ds_read_b128 v[178:181], v141 offset:50176
	ds_read_b128 v[182:185], v141 offset:51200
	ds_read_b128 v[186:189], v141 offset:52224
	ds_read_b128 v[190:193], v141 offset:53248
	ds_read_b128 v[198:201], v141 offset:54272
	ds_read_b128 v[202:205], v141 offset:55296
	ds_read_b128 v[206:209], v141 offset:56320
	global_load_lds_dwordx4 v[138:139], off
	s_add_i32 m0, s22, 0x2000
	s_add_u32 s18, s18, 0x80080
	v_lshl_add_u64 v[138:139], v[194:195], 0, s[2:3]
	s_addc_u32 s19, s19, 0
	s_add_i32 s22, s47, s31
	global_load_lds_dwordx4 v[138:139], off
	v_lshl_add_u64 v[138:139], s[18:19], 0, v[196:197]
	s_mov_b32 m0, s22
	s_nop 0
	global_load_lds_dwordx4 v[138:139], off
	v_lshl_add_u64 v[138:139], s[18:19], 0, v[130:131]
	s_add_i32 m0, s22, 0x2000
	s_nop 0
	global_load_lds_dwordx4 v[138:139], off
	v_lshl_add_u64 v[138:139], v[210:211], 0, s[2:3]
	s_mov_b32 m0, s37
	s_nop 0
	global_load_lds_dwordx4 v[138:139], off
	v_lshl_add_u64 v[138:139], v[212:213], 0, s[2:3]
	s_mov_b32 m0, s38
	s_nop 0
	global_load_lds_dwordx4 v[138:139], off
	s_waitcnt vmcnt(8)
	s_waitcnt lgkmcnt(0)
	s_barrier
	s_setprio 1
	s_waitcnt lgkmcnt(0)
	v_mfma_f32_16x16x32_bf16 v[62:65], v[142:145], v[174:177], v[62:65]
	v_mfma_f32_16x16x32_bf16 v[62:65], v[146:149], v[178:181], v[62:65]
	v_mfma_f32_16x16x32_bf16 v[58:61], v[154:157], v[178:181], v[58:61]
	v_mfma_f32_16x16x32_bf16 v[58:61], v[150:153], v[174:177], v[58:61]
	v_mfma_f32_16x16x32_bf16 v[42:45], v[150:153], v[182:185], v[42:45]
	v_mfma_f32_16x16x32_bf16 v[42:45], v[154:157], v[186:189], v[42:45]
	v_mfma_f32_16x16x32_bf16 v[46:49], v[146:149], v[186:189], v[46:49]
	v_mfma_f32_16x16x32_bf16 v[46:49], v[142:145], v[182:185], v[46:49]
	v_mfma_f32_16x16x32_bf16 v[30:33], v[142:145], v[190:193], v[30:33]
	v_mfma_f32_16x16x32_bf16 v[30:33], v[146:149], v[198:201], v[30:33]
	v_mfma_f32_16x16x32_bf16 v[26:29], v[154:157], v[198:201], v[26:29]
	v_mfma_f32_16x16x32_bf16 v[26:29], v[150:153], v[190:193], v[26:29]
	v_mfma_f32_16x16x32_bf16 v[10:13], v[150:153], v[202:205], v[10:13]
	v_mfma_f32_16x16x32_bf16 v[10:13], v[154:157], v[206:209], v[10:13]
	v_mfma_f32_16x16x32_bf16 v[14:17], v[146:149], v[206:209], v[14:17]
	v_mfma_f32_16x16x32_bf16 v[14:17], v[142:145], v[202:205], v[14:17]
	s_setprio 0
	s_setprio 1
	v_mfma_f32_16x16x32_bf16 v[54:57], v[158:161], v[174:177], v[54:57]
	v_mfma_f32_16x16x32_bf16 v[54:57], v[162:165], v[178:181], v[54:57]
	v_mfma_f32_16x16x32_bf16 v[50:53], v[170:173], v[178:181], v[50:53]
	v_mfma_f32_16x16x32_bf16 v[50:53], v[166:169], v[174:177], v[50:53]
	v_mfma_f32_16x16x32_bf16 v[34:37], v[166:169], v[182:185], v[34:37]
	v_mfma_f32_16x16x32_bf16 v[34:37], v[170:173], v[186:189], v[34:37]
	v_mfma_f32_16x16x32_bf16 v[38:41], v[162:165], v[186:189], v[38:41]
	v_mfma_f32_16x16x32_bf16 v[38:41], v[158:161], v[182:185], v[38:41]
	v_mfma_f32_16x16x32_bf16 v[22:25], v[158:161], v[190:193], v[22:25]
	v_mfma_f32_16x16x32_bf16 v[22:25], v[162:165], v[198:201], v[22:25]
	v_mfma_f32_16x16x32_bf16 v[18:21], v[170:173], v[198:201], v[18:21]
	v_mfma_f32_16x16x32_bf16 v[18:21], v[166:169], v[190:193], v[18:21]
	v_mfma_f32_16x16x32_bf16 v[2:5], v[166:169], v[202:205], v[2:5]
	v_mfma_f32_16x16x32_bf16 v[2:5], v[170:173], v[206:209], v[2:5]
	v_mfma_f32_16x16x32_bf16 v[6:9], v[162:165], v[206:209], v[6:9]
	v_mfma_f32_16x16x32_bf16 v[6:9], v[158:161], v[202:205], v[6:9]
	s_setprio 0
	s_barrier
	s_cmp_gt_u32 s43, 29
	s_mov_b64 s[18:19], s[20:21]
	s_mov_b32 s22, s43
	s_cbranch_scc0 .LBB0_963

.LBB0_1029:
	s_add_u32 s58, s28, 0x100
	s_addc_u32 s59, s29, 0
	s_mov_b32 s60, 2
	s_mov_b64 s[28:29], 0
	s_add_i32 s30, s60, -2
	s_lshr_b32 s44, s30, 2
	s_lshl_b64 s[34:35], s[44:45], 17
	s_lshr_b32 s44, s60, 2
	s_and_b32 s61, s28, 0x100
	s_lshl_b64 s[30:31], s[44:45], 17
	s_add_u32 s44, s26, s30
	s_addc_u32 s62, s27, s31
	s_add_u32 s30, s28, 0x100
	s_addc_u32 s31, s29, 0
	s_and_b32 s63, s30, 0x100
	s_add_u32 s44, s44, s63
	s_addc_u32 s62, s62, 0
	s_add_u32 s28, s58, s28
	s_addc_u32 s29, s59, s29
	s_add_i32 s64, 0, 0x10000
	s_add_u32 s63, s26, s34
	s_addc_u32 s65, s27, s35
	s_cmp_eq_u32 s57, s60
	s_cselect_b32 s35, s23, s62
	s_cselect_b32 s34, s22, s44
	s_cselect_b32 s29, s25, s29
	s_cselect_b32 s28, s24, s28
	s_add_i32 s44, 0, 0x14000
	v_add_u32_e32 v152, s64, v137
	v_add_u32_e32 v168, s44, v137
	ds_read_b128 v[140:143], v152
	ds_read_b128 v[144:147], v152 offset:1024
	ds_read_b128 v[148:151], v152 offset:2048
	ds_read_b128 v[152:155], v152 offset:3072
	ds_read_b128 v[156:159], v168
	ds_read_b128 v[160:163], v168 offset:1024
	ds_read_b128 v[164:167], v168 offset:2048
	ds_read_b128 v[168:171], v168 offset:3072
	s_add_u32 s61, s63, s61
	s_addc_u32 s63, s65, 0
	s_add_u32 s62, s61, 0x10080
	s_addc_u32 s63, s63, 0
	v_lshl_add_u64 v[206:207], s[62:63], 0, v[130:131]
	s_add_i32 m0, s33, 0xc000
	ds_read_b128 v[172:175], v139
	ds_read_b128 v[176:179], v139 offset:1024
	ds_read_b128 v[180:183], v139 offset:2048
	ds_read_b128 v[184:187], v139 offset:3072
	ds_read_b128 v[188:191], v139 offset:4096
	ds_read_b128 v[192:195], v139 offset:5120
	ds_read_b128 v[198:201], v139 offset:6144
	ds_read_b128 v[202:205], v139 offset:7168
	global_load_lds_dwordx4 v[206:207], off
	v_lshl_add_u64 v[206:207], s[62:63], 0, v[132:133]
	s_add_i32 m0, s33, 0xe000
	s_nop 0
	global_load_lds_dwordx4 v[206:207], off
	s_waitcnt vmcnt(8)
	s_waitcnt lgkmcnt(0)
	s_barrier
	s_setprio 1
	s_waitcnt lgkmcnt(0)
	v_mfma_f32_16x16x32_bf16 v[126:129], v[140:143], v[172:175], 0
	v_mfma_f32_16x16x32_bf16 v[126:129], v[144:147], v[176:179], v[126:129]
	v_mfma_f32_16x16x32_bf16 v[122:125], v[152:155], v[176:179], 0
	v_mfma_f32_16x16x32_bf16 v[122:125], v[148:151], v[172:175], v[122:125]
	v_mfma_f32_16x16x32_bf16 v[106:109], v[148:151], v[180:183], 0
	v_mfma_f32_16x16x32_bf16 v[106:109], v[152:155], v[184:187], v[106:109]
	v_mfma_f32_16x16x32_bf16 v[110:113], v[144:147], v[184:187], 0
	v_mfma_f32_16x16x32_bf16 v[110:113], v[140:143], v[180:183], v[110:113]
	v_mfma_f32_16x16x32_bf16 v[94:97], v[140:143], v[188:191], 0
	v_mfma_f32_16x16x32_bf16 v[94:97], v[144:147], v[192:195], v[94:97]
	v_mfma_f32_16x16x32_bf16 v[90:93], v[152:155], v[192:195], 0
	v_mfma_f32_16x16x32_bf16 v[90:93], v[148:151], v[188:191], v[90:93]
	v_mfma_f32_16x16x32_bf16 v[74:77], v[148:151], v[198:201], 0
	v_mfma_f32_16x16x32_bf16 v[74:77], v[152:155], v[202:205], v[74:77]
	v_mfma_f32_16x16x32_bf16 v[78:81], v[144:147], v[202:205], 0
	v_mfma_f32_16x16x32_bf16 v[78:81], v[140:143], v[198:201], v[78:81]
	s_setprio 0
	s_setprio 1
	v_mfma_f32_16x16x32_bf16 v[118:121], v[156:159], v[172:175], 0
	v_mfma_f32_16x16x32_bf16 v[118:121], v[160:163], v[176:179], v[118:121]
	v_mfma_f32_16x16x32_bf16 v[114:117], v[168:171], v[176:179], 0
	v_mfma_f32_16x16x32_bf16 v[114:117], v[164:167], v[172:175], v[114:117]
	v_mfma_f32_16x16x32_bf16 v[98:101], v[164:167], v[180:183], 0
	v_mfma_f32_16x16x32_bf16 v[98:101], v[168:171], v[184:187], v[98:101]
	v_mfma_f32_16x16x32_bf16 v[102:105], v[160:163], v[184:187], 0
	v_mfma_f32_16x16x32_bf16 v[102:105], v[156:159], v[180:183], v[102:105]
	v_mfma_f32_16x16x32_bf16 v[86:89], v[156:159], v[188:191], 0
	v_mfma_f32_16x16x32_bf16 v[86:89], v[160:163], v[192:195], v[86:89]
	v_mfma_f32_16x16x32_bf16 v[82:85], v[168:171], v[192:195], 0
	v_mfma_f32_16x16x32_bf16 v[82:85], v[164:167], v[188:191], v[82:85]
	v_mfma_f32_16x16x32_bf16 v[66:69], v[164:167], v[198:201], 0
	v_mfma_f32_16x16x32_bf16 v[66:69], v[168:171], v[202:205], v[66:69]
	v_mfma_f32_16x16x32_bf16 v[70:73], v[160:163], v[202:205], 0
	v_mfma_f32_16x16x32_bf16 v[70:73], v[156:159], v[198:201], v[70:73]
	s_setprio 0
	s_barrier
	s_add_i32 s61, s64, s9
	v_lshl_add_u64 v[206:207], s[28:29], 0, v[196:197]
	s_mov_b32 m0, s61
	ds_read_b128 v[172:175], v139 offset:16384
	ds_read_b128 v[176:179], v139 offset:17408
	ds_read_b128 v[180:183], v139 offset:18432
	ds_read_b128 v[184:187], v139 offset:19456
	ds_read_b128 v[188:191], v139 offset:20480
	ds_read_b128 v[192:195], v139 offset:21504
	ds_read_b128 v[198:201], v139 offset:22528
	ds_read_b128 v[202:205], v139 offset:23552
	global_load_lds_dwordx4 v[206:207], off
	s_add_i32 m0, s61, 0x2000
	s_add_u32 s62, s28, 0x204000
	v_lshl_add_u64 v[208:209], s[28:29], 0, v[134:135]
	s_addc_u32 s63, s29, 0
	s_add_i32 s44, s44, s9
	global_load_lds_dwordx4 v[208:209], off
	v_lshl_add_u64 v[210:211], s[62:63], 0, v[196:197]
	s_mov_b32 m0, s44
	v_lshl_add_u64 v[212:213], s[34:35], 0, v[132:133]
	global_load_lds_dwordx4 v[210:211], off
	v_lshl_add_u64 v[210:211], s[62:63], 0, v[134:135]
	s_add_i32 m0, s44, 0x2000
	s_nop 0
	global_load_lds_dwordx4 v[210:211], off
	v_lshl_add_u64 v[210:211], s[34:35], 0, v[130:131]
	s_mov_b32 m0, s33
	s_nop 0
	global_load_lds_dwordx4 v[210:211], off
	s_mov_b32 m0, s36
	s_nop 0
	global_load_lds_dwordx4 v[212:213], off
	s_waitcnt vmcnt(8)
	s_waitcnt lgkmcnt(0)
	s_barrier
	s_setprio 1
	s_waitcnt lgkmcnt(0)
	v_mfma_f32_16x16x32_bf16 v[62:65], v[140:143], v[172:175], 0
	v_mfma_f32_16x16x32_bf16 v[62:65], v[144:147], v[176:179], v[62:65]
	v_mfma_f32_16x16x32_bf16 v[58:61], v[152:155], v[176:179], 0
	v_mfma_f32_16x16x32_bf16 v[58:61], v[148:151], v[172:175], v[58:61]
	v_mfma_f32_16x16x32_bf16 v[42:45], v[148:151], v[180:183], 0
	v_mfma_f32_16x16x32_bf16 v[42:45], v[152:155], v[184:187], v[42:45]
	v_mfma_f32_16x16x32_bf16 v[46:49], v[144:147], v[184:187], 0
	v_mfma_f32_16x16x32_bf16 v[46:49], v[140:143], v[180:183], v[46:49]
	v_mfma_f32_16x16x32_bf16 v[30:33], v[140:143], v[188:191], 0
	v_mfma_f32_16x16x32_bf16 v[30:33], v[144:147], v[192:195], v[30:33]
	v_mfma_f32_16x16x32_bf16 v[26:29], v[152:155], v[192:195], 0
	v_mfma_f32_16x16x32_bf16 v[26:29], v[148:151], v[188:191], v[26:29]
	v_mfma_f32_16x16x32_bf16 v[10:13], v[148:151], v[198:201], 0
	v_mfma_f32_16x16x32_bf16 v[10:13], v[152:155], v[202:205], v[10:13]
	v_mfma_f32_16x16x32_bf16 v[14:17], v[144:147], v[202:205], 0
	v_mfma_f32_16x16x32_bf16 v[14:17], v[140:143], v[198:201], v[14:17]
	s_setprio 0
	s_setprio 1
	v_mfma_f32_16x16x32_bf16 v[54:57], v[156:159], v[172:175], 0
	v_mfma_f32_16x16x32_bf16 v[54:57], v[160:163], v[176:179], v[54:57]
	v_mfma_f32_16x16x32_bf16 v[50:53], v[168:171], v[176:179], 0
	v_mfma_f32_16x16x32_bf16 v[50:53], v[164:167], v[172:175], v[50:53]
	v_mfma_f32_16x16x32_bf16 v[34:37], v[164:167], v[180:183], 0
	v_mfma_f32_16x16x32_bf16 v[34:37], v[168:171], v[184:187], v[34:37]
	v_mfma_f32_16x16x32_bf16 v[38:41], v[160:163], v[184:187], 0
	v_mfma_f32_16x16x32_bf16 v[38:41], v[156:159], v[180:183], v[38:41]
	v_mfma_f32_16x16x32_bf16 v[22:25], v[156:159], v[188:191], 0
	v_mfma_f32_16x16x32_bf16 v[22:25], v[160:163], v[192:195], v[22:25]
	v_mfma_f32_16x16x32_bf16 v[18:21], v[168:171], v[192:195], 0
	v_mfma_f32_16x16x32_bf16 v[18:21], v[164:167], v[188:191], v[18:21]
	v_mfma_f32_16x16x32_bf16 v[2:5], v[164:167], v[198:201], 0
	v_mfma_f32_16x16x32_bf16 v[2:5], v[168:171], v[202:205], v[2:5]
	v_mfma_f32_16x16x32_bf16 v[6:9], v[160:163], v[202:205], 0
	v_mfma_f32_16x16x32_bf16 v[6:9], v[156:159], v[198:201], v[6:9]
	s_setprio 0
	s_barrier
	s_add_i32 s44, 0, 0x18000
	s_add_i32 s61, 0, 0x1c000
	v_add_u32_e32 v152, s44, v137
	v_add_u32_e32 v168, s61, v137
	ds_read_b128 v[140:143], v152
	ds_read_b128 v[144:147], v152 offset:1024
	ds_read_b128 v[148:151], v152 offset:2048
	ds_read_b128 v[152:155], v152 offset:3072
	ds_read_b128 v[156:159], v168
	ds_read_b128 v[160:163], v168 offset:1024
	ds_read_b128 v[164:167], v168 offset:2048
	ds_read_b128 v[168:171], v168 offset:3072
	s_add_u32 s34, s34, 0x10000
	s_addc_u32 s35, s35, 0
	s_mov_b32 m0, s37
	v_lshl_add_u64 v[214:215], s[34:35], 0, v[130:131]
	ds_read_b128 v[172:175], v139 offset:32768
	ds_read_b128 v[176:179], v139 offset:33792
	ds_read_b128 v[180:183], v139 offset:34816
	ds_read_b128 v[184:187], v139 offset:35840
	ds_read_b128 v[188:191], v139 offset:36864
	ds_read_b128 v[192:195], v139 offset:37888
	ds_read_b128 v[198:201], v139 offset:38912
	ds_read_b128 v[202:205], v139 offset:39936
	global_load_lds_dwordx4 v[214:215], off
	v_lshl_add_u64 v[214:215], s[34:35], 0, v[132:133]
	s_mov_b32 m0, s38
	s_nop 0
	global_load_lds_dwordx4 v[214:215], off
	s_waitcnt vmcnt(8)
	s_waitcnt lgkmcnt(0)
	s_barrier
	s_setprio 1
	s_waitcnt lgkmcnt(0)
	v_mfma_f32_16x16x32_bf16 v[126:129], v[140:143], v[172:175], v[126:129]
	v_mfma_f32_16x16x32_bf16 v[126:129], v[144:147], v[176:179], v[126:129]
	v_mfma_f32_16x16x32_bf16 v[122:125], v[152:155], v[176:179], v[122:125]
	v_mfma_f32_16x16x32_bf16 v[122:125], v[148:151], v[172:175], v[122:125]
	v_mfma_f32_16x16x32_bf16 v[106:109], v[148:151], v[180:183], v[106:109]
	v_mfma_f32_16x16x32_bf16 v[106:109], v[152:155], v[184:187], v[106:109]
	v_mfma_f32_16x16x32_bf16 v[110:113], v[144:147], v[184:187], v[110:113]
	v_mfma_f32_16x16x32_bf16 v[110:113], v[140:143], v[180:183], v[110:113]
	v_mfma_f32_16x16x32_bf16 v[94:97], v[140:143], v[188:191], v[94:97]
	v_mfma_f32_16x16x32_bf16 v[94:97], v[144:147], v[192:195], v[94:97]
	v_mfma_f32_16x16x32_bf16 v[90:93], v[152:155], v[192:195], v[90:93]
	v_mfma_f32_16x16x32_bf16 v[90:93], v[148:151], v[188:191], v[90:93]
	v_mfma_f32_16x16x32_bf16 v[74:77], v[148:151], v[198:201], v[74:77]
	v_mfma_f32_16x16x32_bf16 v[74:77], v[152:155], v[202:205], v[74:77]
	v_mfma_f32_16x16x32_bf16 v[78:81], v[144:147], v[202:205], v[78:81]
	v_mfma_f32_16x16x32_bf16 v[78:81], v[140:143], v[198:201], v[78:81]
	s_setprio 0
	s_setprio 1
	v_mfma_f32_16x16x32_bf16 v[118:121], v[156:159], v[172:175], v[118:121]
	v_mfma_f32_16x16x32_bf16 v[118:121], v[160:163], v[176:179], v[118:121]
	v_mfma_f32_16x16x32_bf16 v[114:117], v[168:171], v[176:179], v[114:117]
	v_mfma_f32_16x16x32_bf16 v[114:117], v[164:167], v[172:175], v[114:117]
	v_mfma_f32_16x16x32_bf16 v[98:101], v[164:167], v[180:183], v[98:101]
	v_mfma_f32_16x16x32_bf16 v[98:101], v[168:171], v[184:187], v[98:101]
	v_mfma_f32_16x16x32_bf16 v[102:105], v[160:163], v[184:187], v[102:105]
	v_mfma_f32_16x16x32_bf16 v[102:105], v[156:159], v[180:183], v[102:105]
	v_mfma_f32_16x16x32_bf16 v[86:89], v[156:159], v[188:191], v[86:89]
	v_mfma_f32_16x16x32_bf16 v[86:89], v[160:163], v[192:195], v[86:89]
	v_mfma_f32_16x16x32_bf16 v[82:85], v[168:171], v[192:195], v[82:85]
	v_mfma_f32_16x16x32_bf16 v[82:85], v[164:167], v[188:191], v[82:85]
	v_mfma_f32_16x16x32_bf16 v[66:69], v[164:167], v[198:201], v[66:69]
	v_mfma_f32_16x16x32_bf16 v[66:69], v[168:171], v[202:205], v[66:69]
	v_mfma_f32_16x16x32_bf16 v[70:73], v[160:163], v[202:205], v[70:73]
	v_mfma_f32_16x16x32_bf16 v[70:73], v[156:159], v[198:201], v[70:73]
	s_setprio 0
	s_barrier
	s_add_i32 s34, s44, s9
	v_lshl_add_u64 v[206:207], v[206:207], 0, s[2:3]
	s_mov_b32 m0, s34
	ds_read_b128 v[172:175], v139 offset:49152
	ds_read_b128 v[176:179], v139 offset:50176
	ds_read_b128 v[180:183], v139 offset:51200
	ds_read_b128 v[184:187], v139 offset:52224
	ds_read_b128 v[188:191], v139 offset:53248
	ds_read_b128 v[192:195], v139 offset:54272
	ds_read_b128 v[198:201], v139 offset:55296
	ds_read_b128 v[202:205], v139 offset:56320
	global_load_lds_dwordx4 v[206:207], off
	s_add_i32 m0, s34, 0x2000
	s_add_u32 s28, s28, 0x204080
	v_lshl_add_u64 v[206:207], v[208:209], 0, s[2:3]
	s_addc_u32 s29, s29, 0
	s_add_i32 s34, s61, s9
	global_load_lds_dwordx4 v[206:207], off
	v_lshl_add_u64 v[206:207], s[28:29], 0, v[196:197]
	s_mov_b32 m0, s34
	s_nop 0
	global_load_lds_dwordx4 v[206:207], off
	v_lshl_add_u64 v[206:207], s[28:29], 0, v[134:135]
	s_add_i32 m0, s34, 0x2000
	s_nop 0
	global_load_lds_dwordx4 v[206:207], off
	v_lshl_add_u64 v[206:207], v[210:211], 0, s[2:3]
	s_mov_b32 m0, s47
	s_nop 0
	global_load_lds_dwordx4 v[206:207], off
	v_lshl_add_u64 v[206:207], v[212:213], 0, s[2:3]
	s_mov_b32 m0, s49
	s_nop 0
	global_load_lds_dwordx4 v[206:207], off
	s_waitcnt vmcnt(8)
	s_waitcnt lgkmcnt(0)
	s_barrier
	s_setprio 1
	s_waitcnt lgkmcnt(0)
	v_mfma_f32_16x16x32_bf16 v[62:65], v[140:143], v[172:175], v[62:65]
	v_mfma_f32_16x16x32_bf16 v[62:65], v[144:147], v[176:179], v[62:65]
	v_mfma_f32_16x16x32_bf16 v[58:61], v[152:155], v[176:179], v[58:61]
	v_mfma_f32_16x16x32_bf16 v[58:61], v[148:151], v[172:175], v[58:61]
	v_mfma_f32_16x16x32_bf16 v[42:45], v[148:151], v[180:183], v[42:45]
	v_mfma_f32_16x16x32_bf16 v[42:45], v[152:155], v[184:187], v[42:45]
	v_mfma_f32_16x16x32_bf16 v[46:49], v[144:147], v[184:187], v[46:49]
	v_mfma_f32_16x16x32_bf16 v[46:49], v[140:143], v[180:183], v[46:49]
	v_mfma_f32_16x16x32_bf16 v[30:33], v[140:143], v[188:191], v[30:33]
	v_mfma_f32_16x16x32_bf16 v[30:33], v[144:147], v[192:195], v[30:33]
	v_mfma_f32_16x16x32_bf16 v[26:29], v[152:155], v[192:195], v[26:29]
	v_mfma_f32_16x16x32_bf16 v[26:29], v[148:151], v[188:191], v[26:29]
	v_mfma_f32_16x16x32_bf16 v[10:13], v[148:151], v[198:201], v[10:13]
	v_mfma_f32_16x16x32_bf16 v[10:13], v[152:155], v[202:205], v[10:13]
	v_mfma_f32_16x16x32_bf16 v[14:17], v[144:147], v[202:205], v[14:17]
	v_mfma_f32_16x16x32_bf16 v[14:17], v[140:143], v[198:201], v[14:17]
	s_setprio 0
	s_setprio 1
	v_mfma_f32_16x16x32_bf16 v[54:57], v[156:159], v[172:175], v[54:57]
	v_mfma_f32_16x16x32_bf16 v[54:57], v[160:163], v[176:179], v[54:57]
	v_mfma_f32_16x16x32_bf16 v[50:53], v[168:171], v[176:179], v[50:53]
	v_mfma_f32_16x16x32_bf16 v[50:53], v[164:167], v[172:175], v[50:53]
	v_mfma_f32_16x16x32_bf16 v[34:37], v[164:167], v[180:183], v[34:37]
	v_mfma_f32_16x16x32_bf16 v[34:37], v[168:171], v[184:187], v[34:37]
	v_mfma_f32_16x16x32_bf16 v[38:41], v[160:163], v[184:187], v[38:41]
	v_mfma_f32_16x16x32_bf16 v[38:41], v[156:159], v[180:183], v[38:41]
	v_mfma_f32_16x16x32_bf16 v[22:25], v[156:159], v[188:191], v[22:25]
	v_mfma_f32_16x16x32_bf16 v[22:25], v[160:163], v[192:195], v[22:25]
	v_mfma_f32_16x16x32_bf16 v[18:21], v[168:171], v[192:195], v[18:21]
	v_mfma_f32_16x16x32_bf16 v[18:21], v[164:167], v[188:191], v[18:21]
	v_mfma_f32_16x16x32_bf16 v[2:5], v[164:167], v[198:201], v[2:5]
	v_mfma_f32_16x16x32_bf16 v[2:5], v[168:171], v[202:205], v[2:5]
	v_mfma_f32_16x16x32_bf16 v[6:9], v[160:163], v[202:205], v[6:9]
	v_mfma_f32_16x16x32_bf16 v[6:9], v[156:159], v[198:201], v[6:9]
	s_setprio 0
	s_barrier
	s_add_i32 s34, s60, 2
	s_cmp_ge_i32 s60, s57
	s_mov_b64 s[28:29], s[30:31]
	s_mov_b32 s60, s34
	s_cbranch_scc1 .Lpeel_exit_w2
.LBB0_1030:
	s_add_i32 s30, s60, -2
	s_lshr_b32 s44, s30, 2
	s_lshl_b64 s[34:35], s[44:45], 17
	s_lshr_b32 s44, s60, 2
	s_and_b32 s61, s28, 0x100
	s_lshl_b64 s[30:31], s[44:45], 17
	s_add_u32 s44, s26, s30
	s_addc_u32 s62, s27, s31
	s_add_u32 s30, s28, 0x100
	s_addc_u32 s31, s29, 0
	s_and_b32 s63, s30, 0x100
	s_add_u32 s44, s44, s63
	s_addc_u32 s62, s62, 0
	s_add_u32 s28, s58, s28
	s_addc_u32 s29, s59, s29
	s_add_i32 s64, 0, 0x10000
	s_add_u32 s63, s26, s34
	s_addc_u32 s65, s27, s35
	s_cmp_eq_u32 s57, s60
	s_cselect_b32 s35, s23, s62
	s_cselect_b32 s34, s22, s44
	s_cselect_b32 s29, s25, s29
	s_cselect_b32 s28, s24, s28
	s_add_i32 s44, 0, 0x14000
	v_add_u32_e32 v152, s64, v137
	v_add_u32_e32 v168, s44, v137
	ds_read_b128 v[140:143], v152
	ds_read_b128 v[144:147], v152 offset:1024
	ds_read_b128 v[148:151], v152 offset:2048
	ds_read_b128 v[152:155], v152 offset:3072
	ds_read_b128 v[156:159], v168
	ds_read_b128 v[160:163], v168 offset:1024
	ds_read_b128 v[164:167], v168 offset:2048
	ds_read_b128 v[168:171], v168 offset:3072
	s_add_u32 s61, s63, s61
	s_addc_u32 s63, s65, 0
	s_add_u32 s62, s61, 0x10080
	s_addc_u32 s63, s63, 0
	v_lshl_add_u64 v[206:207], s[62:63], 0, v[130:131]
	s_add_i32 m0, s33, 0xc000
	ds_read_b128 v[172:175], v139
	ds_read_b128 v[176:179], v139 offset:1024
	ds_read_b128 v[180:183], v139 offset:2048
	ds_read_b128 v[184:187], v139 offset:3072
	ds_read_b128 v[188:191], v139 offset:4096
	ds_read_b128 v[192:195], v139 offset:5120
	ds_read_b128 v[198:201], v139 offset:6144
	ds_read_b128 v[202:205], v139 offset:7168
	global_load_lds_dwordx4 v[206:207], off
	v_lshl_add_u64 v[206:207], s[62:63], 0, v[132:133]
	s_add_i32 m0, s33, 0xe000
	s_nop 0
	global_load_lds_dwordx4 v[206:207], off
	s_waitcnt vmcnt(8)
	s_waitcnt lgkmcnt(0)
	s_barrier
	s_setprio 1
	s_waitcnt lgkmcnt(0)
	v_mfma_f32_16x16x32_bf16 v[126:129], v[140:143], v[172:175], v[126:129]
	v_mfma_f32_16x16x32_bf16 v[126:129], v[144:147], v[176:179], v[126:129]
	v_mfma_f32_16x16x32_bf16 v[122:125], v[152:155], v[176:179], v[122:125]
	v_mfma_f32_16x16x32_bf16 v[122:125], v[148:151], v[172:175], v[122:125]
	v_mfma_f32_16x16x32_bf16 v[106:109], v[148:151], v[180:183], v[106:109]
	v_mfma_f32_16x16x32_bf16 v[106:109], v[152:155], v[184:187], v[106:109]
	v_mfma_f32_16x16x32_bf16 v[110:113], v[144:147], v[184:187], v[110:113]
	v_mfma_f32_16x16x32_bf16 v[110:113], v[140:143], v[180:183], v[110:113]
	v_mfma_f32_16x16x32_bf16 v[94:97], v[140:143], v[188:191], v[94:97]
	v_mfma_f32_16x16x32_bf16 v[94:97], v[144:147], v[192:195], v[94:97]
	v_mfma_f32_16x16x32_bf16 v[90:93], v[152:155], v[192:195], v[90:93]
	v_mfma_f32_16x16x32_bf16 v[90:93], v[148:151], v[188:191], v[90:93]
	v_mfma_f32_16x16x32_bf16 v[74:77], v[148:151], v[198:201], v[74:77]
	v_mfma_f32_16x16x32_bf16 v[74:77], v[152:155], v[202:205], v[74:77]
	v_mfma_f32_16x16x32_bf16 v[78:81], v[144:147], v[202:205], v[78:81]
	v_mfma_f32_16x16x32_bf16 v[78:81], v[140:143], v[198:201], v[78:81]
	s_setprio 0
	s_setprio 1
	v_mfma_f32_16x16x32_bf16 v[118:121], v[156:159], v[172:175], v[118:121]
	v_mfma_f32_16x16x32_bf16 v[118:121], v[160:163], v[176:179], v[118:121]
	v_mfma_f32_16x16x32_bf16 v[114:117], v[168:171], v[176:179], v[114:117]
	v_mfma_f32_16x16x32_bf16 v[114:117], v[164:167], v[172:175], v[114:117]
	v_mfma_f32_16x16x32_bf16 v[98:101], v[164:167], v[180:183], v[98:101]
	v_mfma_f32_16x16x32_bf16 v[98:101], v[168:171], v[184:187], v[98:101]
	v_mfma_f32_16x16x32_bf16 v[102:105], v[160:163], v[184:187], v[102:105]
	v_mfma_f32_16x16x32_bf16 v[102:105], v[156:159], v[180:183], v[102:105]
	v_mfma_f32_16x16x32_bf16 v[86:89], v[156:159], v[188:191], v[86:89]
	v_mfma_f32_16x16x32_bf16 v[86:89], v[160:163], v[192:195], v[86:89]
	v_mfma_f32_16x16x32_bf16 v[82:85], v[168:171], v[192:195], v[82:85]
	v_mfma_f32_16x16x32_bf16 v[82:85], v[164:167], v[188:191], v[82:85]
	v_mfma_f32_16x16x32_bf16 v[66:69], v[164:167], v[198:201], v[66:69]
	v_mfma_f32_16x16x32_bf16 v[66:69], v[168:171], v[202:205], v[66:69]
	v_mfma_f32_16x16x32_bf16 v[70:73], v[160:163], v[202:205], v[70:73]
	v_mfma_f32_16x16x32_bf16 v[70:73], v[156:159], v[198:201], v[70:73]
	s_setprio 0
	s_barrier
	s_add_i32 s61, s64, s9
	v_lshl_add_u64 v[206:207], s[28:29], 0, v[196:197]
	s_mov_b32 m0, s61
	ds_read_b128 v[172:175], v139 offset:16384
	ds_read_b128 v[176:179], v139 offset:17408
	ds_read_b128 v[180:183], v139 offset:18432
	ds_read_b128 v[184:187], v139 offset:19456
	ds_read_b128 v[188:191], v139 offset:20480
	ds_read_b128 v[192:195], v139 offset:21504
	ds_read_b128 v[198:201], v139 offset:22528
	ds_read_b128 v[202:205], v139 offset:23552
	global_load_lds_dwordx4 v[206:207], off
	s_add_i32 m0, s61, 0x2000
	s_add_u32 s62, s28, 0x204000
	v_lshl_add_u64 v[208:209], s[28:29], 0, v[134:135]
	s_addc_u32 s63, s29, 0
	s_add_i32 s44, s44, s9
	global_load_lds_dwordx4 v[208:209], off
	v_lshl_add_u64 v[210:211], s[62:63], 0, v[196:197]
	s_mov_b32 m0, s44
	v_lshl_add_u64 v[212:213], s[34:35], 0, v[132:133]
	global_load_lds_dwordx4 v[210:211], off
	v_lshl_add_u64 v[210:211], s[62:63], 0, v[134:135]
	s_add_i32 m0, s44, 0x2000
	s_nop 0
	global_load_lds_dwordx4 v[210:211], off
	v_lshl_add_u64 v[210:211], s[34:35], 0, v[130:131]
	s_mov_b32 m0, s33
	s_nop 0
	global_load_lds_dwordx4 v[210:211], off
	s_mov_b32 m0, s36
	s_nop 0
	global_load_lds_dwordx4 v[212:213], off
	s_waitcnt vmcnt(8)
	s_waitcnt lgkmcnt(0)
	s_barrier
	s_setprio 1
	s_waitcnt lgkmcnt(0)
	v_mfma_f32_16x16x32_bf16 v[62:65], v[140:143], v[172:175], v[62:65]
	v_mfma_f32_16x16x32_bf16 v[62:65], v[144:147], v[176:179], v[62:65]
	v_mfma_f32_16x16x32_bf16 v[58:61], v[152:155], v[176:179], v[58:61]
	v_mfma_f32_16x16x32_bf16 v[58:61], v[148:151], v[172:175], v[58:61]
	v_mfma_f32_16x16x32_bf16 v[42:45], v[148:151], v[180:183], v[42:45]
	v_mfma_f32_16x16x32_bf16 v[42:45], v[152:155], v[184:187], v[42:45]
	v_mfma_f32_16x16x32_bf16 v[46:49], v[144:147], v[184:187], v[46:49]
	v_mfma_f32_16x16x32_bf16 v[46:49], v[140:143], v[180:183], v[46:49]
	v_mfma_f32_16x16x32_bf16 v[30:33], v[140:143], v[188:191], v[30:33]
	v_mfma_f32_16x16x32_bf16 v[30:33], v[144:147], v[192:195], v[30:33]
	v_mfma_f32_16x16x32_bf16 v[26:29], v[152:155], v[192:195], v[26:29]
	v_mfma_f32_16x16x32_bf16 v[26:29], v[148:151], v[188:191], v[26:29]
	v_mfma_f32_16x16x32_bf16 v[10:13], v[148:151], v[198:201], v[10:13]
	v_mfma_f32_16x16x32_bf16 v[10:13], v[152:155], v[202:205], v[10:13]
	v_mfma_f32_16x16x32_bf16 v[14:17], v[144:147], v[202:205], v[14:17]
	v_mfma_f32_16x16x32_bf16 v[14:17], v[140:143], v[198:201], v[14:17]
	s_setprio 0
	s_setprio 1
	v_mfma_f32_16x16x32_bf16 v[54:57], v[156:159], v[172:175], v[54:57]
	v_mfma_f32_16x16x32_bf16 v[54:57], v[160:163], v[176:179], v[54:57]
	v_mfma_f32_16x16x32_bf16 v[50:53], v[168:171], v[176:179], v[50:53]
	v_mfma_f32_16x16x32_bf16 v[50:53], v[164:167], v[172:175], v[50:53]
	v_mfma_f32_16x16x32_bf16 v[34:37], v[164:167], v[180:183], v[34:37]
	v_mfma_f32_16x16x32_bf16 v[34:37], v[168:171], v[184:187], v[34:37]
	v_mfma_f32_16x16x32_bf16 v[38:41], v[160:163], v[184:187], v[38:41]
	v_mfma_f32_16x16x32_bf16 v[38:41], v[156:159], v[180:183], v[38:41]
	v_mfma_f32_16x16x32_bf16 v[22:25], v[156:159], v[188:191], v[22:25]
	v_mfma_f32_16x16x32_bf16 v[22:25], v[160:163], v[192:195], v[22:25]
	v_mfma_f32_16x16x32_bf16 v[18:21], v[168:171], v[192:195], v[18:21]
	v_mfma_f32_16x16x32_bf16 v[18:21], v[164:167], v[188:191], v[18:21]
	v_mfma_f32_16x16x32_bf16 v[2:5], v[164:167], v[198:201], v[2:5]
	v_mfma_f32_16x16x32_bf16 v[2:5], v[168:171], v[202:205], v[2:5]
	v_mfma_f32_16x16x32_bf16 v[6:9], v[160:163], v[202:205], v[6:9]
	v_mfma_f32_16x16x32_bf16 v[6:9], v[156:159], v[198:201], v[6:9]
	s_setprio 0
	s_barrier
	s_add_i32 s44, 0, 0x18000
	s_add_i32 s61, 0, 0x1c000
	v_add_u32_e32 v152, s44, v137
	v_add_u32_e32 v168, s61, v137
	ds_read_b128 v[140:143], v152
	ds_read_b128 v[144:147], v152 offset:1024
	ds_read_b128 v[148:151], v152 offset:2048
	ds_read_b128 v[152:155], v152 offset:3072
	ds_read_b128 v[156:159], v168
	ds_read_b128 v[160:163], v168 offset:1024
	ds_read_b128 v[164:167], v168 offset:2048
	ds_read_b128 v[168:171], v168 offset:3072
	s_add_u32 s34, s34, 0x10000
	s_addc_u32 s35, s35, 0
	s_mov_b32 m0, s37
	v_lshl_add_u64 v[214:215], s[34:35], 0, v[130:131]
	ds_read_b128 v[172:175], v139 offset:32768
	ds_read_b128 v[176:179], v139 offset:33792
	ds_read_b128 v[180:183], v139 offset:34816
	ds_read_b128 v[184:187], v139 offset:35840
	ds_read_b128 v[188:191], v139 offset:36864
	ds_read_b128 v[192:195], v139 offset:37888
	ds_read_b128 v[198:201], v139 offset:38912
	ds_read_b128 v[202:205], v139 offset:39936
	global_load_lds_dwordx4 v[214:215], off
	v_lshl_add_u64 v[214:215], s[34:35], 0, v[132:133]
	s_mov_b32 m0, s38
	s_nop 0
	global_load_lds_dwordx4 v[214:215], off
	s_waitcnt vmcnt(8)
	s_waitcnt lgkmcnt(0)
	s_barrier
	s_setprio 1
	s_waitcnt lgkmcnt(0)
	v_mfma_f32_16x16x32_bf16 v[126:129], v[140:143], v[172:175], v[126:129]
	v_mfma_f32_16x16x32_bf16 v[126:129], v[144:147], v[176:179], v[126:129]
	v_mfma_f32_16x16x32_bf16 v[122:125], v[152:155], v[176:179], v[122:125]
	v_mfma_f32_16x16x32_bf16 v[122:125], v[148:151], v[172:175], v[122:125]
	v_mfma_f32_16x16x32_bf16 v[106:109], v[148:151], v[180:183], v[106:109]
	v_mfma_f32_16x16x32_bf16 v[106:109], v[152:155], v[184:187], v[106:109]
	v_mfma_f32_16x16x32_bf16 v[110:113], v[144:147], v[184:187], v[110:113]
	v_mfma_f32_16x16x32_bf16 v[110:113], v[140:143], v[180:183], v[110:113]
	v_mfma_f32_16x16x32_bf16 v[94:97], v[140:143], v[188:191], v[94:97]
	v_mfma_f32_16x16x32_bf16 v[94:97], v[144:147], v[192:195], v[94:97]
	v_mfma_f32_16x16x32_bf16 v[90:93], v[152:155], v[192:195], v[90:93]
	v_mfma_f32_16x16x32_bf16 v[90:93], v[148:151], v[188:191], v[90:93]
	v_mfma_f32_16x16x32_bf16 v[74:77], v[148:151], v[198:201], v[74:77]
	v_mfma_f32_16x16x32_bf16 v[74:77], v[152:155], v[202:205], v[74:77]
	v_mfma_f32_16x16x32_bf16 v[78:81], v[144:147], v[202:205], v[78:81]
	v_mfma_f32_16x16x32_bf16 v[78:81], v[140:143], v[198:201], v[78:81]
	s_setprio 0
	s_setprio 1
	v_mfma_f32_16x16x32_bf16 v[118:121], v[156:159], v[172:175], v[118:121]
	v_mfma_f32_16x16x32_bf16 v[118:121], v[160:163], v[176:179], v[118:121]
	v_mfma_f32_16x16x32_bf16 v[114:117], v[168:171], v[176:179], v[114:117]
	v_mfma_f32_16x16x32_bf16 v[114:117], v[164:167], v[172:175], v[114:117]
	v_mfma_f32_16x16x32_bf16 v[98:101], v[164:167], v[180:183], v[98:101]
	v_mfma_f32_16x16x32_bf16 v[98:101], v[168:171], v[184:187], v[98:101]
	v_mfma_f32_16x16x32_bf16 v[102:105], v[160:163], v[184:187], v[102:105]
	v_mfma_f32_16x16x32_bf16 v[102:105], v[156:159], v[180:183], v[102:105]
	v_mfma_f32_16x16x32_bf16 v[86:89], v[156:159], v[188:191], v[86:89]
	v_mfma_f32_16x16x32_bf16 v[86:89], v[160:163], v[192:195], v[86:89]
	v_mfma_f32_16x16x32_bf16 v[82:85], v[168:171], v[192:195], v[82:85]
	v_mfma_f32_16x16x32_bf16 v[82:85], v[164:167], v[188:191], v[82:85]
	v_mfma_f32_16x16x32_bf16 v[66:69], v[164:167], v[198:201], v[66:69]
	v_mfma_f32_16x16x32_bf16 v[66:69], v[168:171], v[202:205], v[66:69]
	v_mfma_f32_16x16x32_bf16 v[70:73], v[160:163], v[202:205], v[70:73]
	v_mfma_f32_16x16x32_bf16 v[70:73], v[156:159], v[198:201], v[70:73]
	s_setprio 0
	s_barrier
	s_add_i32 s34, s44, s9
	v_lshl_add_u64 v[206:207], v[206:207], 0, s[2:3]
	s_mov_b32 m0, s34
	ds_read_b128 v[172:175], v139 offset:49152
	ds_read_b128 v[176:179], v139 offset:50176
	ds_read_b128 v[180:183], v139 offset:51200
	ds_read_b128 v[184:187], v139 offset:52224
	ds_read_b128 v[188:191], v139 offset:53248
	ds_read_b128 v[192:195], v139 offset:54272
	ds_read_b128 v[198:201], v139 offset:55296
	ds_read_b128 v[202:205], v139 offset:56320
	global_load_lds_dwordx4 v[206:207], off
	s_add_i32 m0, s34, 0x2000
	s_add_u32 s28, s28, 0x204080
	v_lshl_add_u64 v[206:207], v[208:209], 0, s[2:3]
	s_addc_u32 s29, s29, 0
	s_add_i32 s34, s61, s9
	global_load_lds_dwordx4 v[206:207], off
	v_lshl_add_u64 v[206:207], s[28:29], 0, v[196:197]
	s_mov_b32 m0, s34
	s_nop 0
	global_load_lds_dwordx4 v[206:207], off
	v_lshl_add_u64 v[206:207], s[28:29], 0, v[134:135]
	s_add_i32 m0, s34, 0x2000
	s_nop 0
	global_load_lds_dwordx4 v[206:207], off
	v_lshl_add_u64 v[206:207], v[210:211], 0, s[2:3]
	s_mov_b32 m0, s47
	s_nop 0
	global_load_lds_dwordx4 v[206:207], off
	v_lshl_add_u64 v[206:207], v[212:213], 0, s[2:3]
	s_mov_b32 m0, s49
	s_nop 0
	global_load_lds_dwordx4 v[206:207], off
	s_waitcnt vmcnt(8)
	s_waitcnt lgkmcnt(0)
	s_barrier
	s_setprio 1
	s_waitcnt lgkmcnt(0)
	v_mfma_f32_16x16x32_bf16 v[62:65], v[140:143], v[172:175], v[62:65]
	v_mfma_f32_16x16x32_bf16 v[62:65], v[144:147], v[176:179], v[62:65]
	v_mfma_f32_16x16x32_bf16 v[58:61], v[152:155], v[176:179], v[58:61]
	v_mfma_f32_16x16x32_bf16 v[58:61], v[148:151], v[172:175], v[58:61]
	v_mfma_f32_16x16x32_bf16 v[42:45], v[148:151], v[180:183], v[42:45]
	v_mfma_f32_16x16x32_bf16 v[42:45], v[152:155], v[184:187], v[42:45]
	v_mfma_f32_16x16x32_bf16 v[46:49], v[144:147], v[184:187], v[46:49]
	v_mfma_f32_16x16x32_bf16 v[46:49], v[140:143], v[180:183], v[46:49]
	v_mfma_f32_16x16x32_bf16 v[30:33], v[140:143], v[188:191], v[30:33]
	v_mfma_f32_16x16x32_bf16 v[30:33], v[144:147], v[192:195], v[30:33]
	v_mfma_f32_16x16x32_bf16 v[26:29], v[152:155], v[192:195], v[26:29]
	v_mfma_f32_16x16x32_bf16 v[26:29], v[148:151], v[188:191], v[26:29]
	v_mfma_f32_16x16x32_bf16 v[10:13], v[148:151], v[198:201], v[10:13]
	v_mfma_f32_16x16x32_bf16 v[10:13], v[152:155], v[202:205], v[10:13]
	v_mfma_f32_16x16x32_bf16 v[14:17], v[144:147], v[202:205], v[14:17]
	v_mfma_f32_16x16x32_bf16 v[14:17], v[140:143], v[198:201], v[14:17]
	s_setprio 0
	s_setprio 1
	v_mfma_f32_16x16x32_bf16 v[54:57], v[156:159], v[172:175], v[54:57]
	v_mfma_f32_16x16x32_bf16 v[54:57], v[160:163], v[176:179], v[54:57]
	v_mfma_f32_16x16x32_bf16 v[50:53], v[168:171], v[176:179], v[50:53]
	v_mfma_f32_16x16x32_bf16 v[50:53], v[164:167], v[172:175], v[50:53]
	v_mfma_f32_16x16x32_bf16 v[34:37], v[164:167], v[180:183], v[34:37]
	v_mfma_f32_16x16x32_bf16 v[34:37], v[168:171], v[184:187], v[34:37]
	v_mfma_f32_16x16x32_bf16 v[38:41], v[160:163], v[184:187], v[38:41]
	v_mfma_f32_16x16x32_bf16 v[38:41], v[156:159], v[180:183], v[38:41]
	v_mfma_f32_16x16x32_bf16 v[22:25], v[156:159], v[188:191], v[22:25]
	v_mfma_f32_16x16x32_bf16 v[22:25], v[160:163], v[192:195], v[22:25]
	v_mfma_f32_16x16x32_bf16 v[18:21], v[168:171], v[192:195], v[18:21]
	v_mfma_f32_16x16x32_bf16 v[18:21], v[164:167], v[188:191], v[18:21]
	v_mfma_f32_16x16x32_bf16 v[2:5], v[164:167], v[198:201], v[2:5]
	v_mfma_f32_16x16x32_bf16 v[2:5], v[168:171], v[202:205], v[2:5]
	v_mfma_f32_16x16x32_bf16 v[6:9], v[160:163], v[202:205], v[6:9]
	v_mfma_f32_16x16x32_bf16 v[6:9], v[156:159], v[198:201], v[6:9]
	s_setprio 0
	s_barrier
	s_add_i32 s34, s60, 2
	s_cmp_ge_i32 s60, s57
	s_mov_b64 s[28:29], s[30:31]
	s_mov_b32 s60, s34
	s_cbranch_scc0 .LBB0_1030
